# v30 plus scalar per-tile test in indexer scoring (s_cmp on 2p instead of v_cmp + s_and_saveexec + execz and exec restore)
# speedup vs baseline: 1.0057x; 1.0016x over previous
.Lidxd_p:
	v_mad_i64_i32 v[4:5], s[74:75], v2, s80, v[42:43]
	v_lshl_add_u64 v[4:5], v[4:5], 0, v[0:1]
	v_mov_b32_e32 v87, v1
	v_lshl_add_u64 v[4:5], v[4:5], 0, v[86:87]
	s_mov_b64 s[74:75], 0x1200
	v_lshl_add_u64 v[34:35], v[4:5], 0, s[74:75]
	v_add_co_u32_e32 v4, vcc, 0x1000, v4
	global_load_dwordx4 v[10:13], v[34:35], off offset:64
	s_nop 0
	v_addc_co_u32_e32 v5, vcc, 0, v5, vcc
	global_load_dwordx4 v[14:17], v[4:5], off offset:512
	v_ashrrev_i32_e32 v3, 31, v2
	v_lshlrev_b64 v[2:3], 8, v[2:3]
	v_lshl_add_u64 v[44:45], v[82:83], 0, v[2:3]
	global_load_dwordx4 v[18:21], v[44:45], off
	global_load_dwordx4 v[22:25], v[44:45], off offset:16
	global_load_dwordx4 v[26:29], v[44:45], off offset:32
	global_load_dwordx4 v[30:33], v[44:45], off offset:48
	global_load_dwordx4 v[6:9], v[34:35], off offset:32
	global_load_dwordx4 v[2:5], v[34:35], off offset:96
	s_movk_i32 s2, 0xf800
	v_and_b32_e32 v177, 0x7fe, v88
	v_or_b32_e32 v184, v88, v94
	v_mad_i64_i32 v[184:185], vcc, v184, s80, v[42:43]
	v_add_co_u32_e32 v184, vcc, 0x3300, v184
	s_nop 1
	v_addc_co_u32_e32 v185, vcc, 0, v185, vcc
	global_load_dwordx4 v[66:69], v[184:185], off
	global_load_dwordx4 v[180:183], v[184:185], off offset:16
	s_waitcnt vmcnt(7)
	v_lshlrev_b32_e32 v34, 16, v10
	v_and_b32_e32 v10, 0xffff0000, v10
	v_lshlrev_b32_e32 v36, 16, v11
	v_and_b32_e32 v38, 0xffff0000, v11
	v_lshlrev_b32_e32 v40, 16, v12
	v_and_b32_e32 v12, 0xffff0000, v12
	v_lshlrev_b32_e32 v46, 16, v13
	v_and_b32_e32 v48, 0xffff0000, v13
	s_waitcnt vmcnt(6)
	v_lshlrev_b32_e32 v35, 16, v14
	v_and_b32_e32 v11, 0xffff0000, v14
	v_lshlrev_b32_e32 v37, 16, v15
	v_and_b32_e32 v39, 0xffff0000, v15
	v_lshlrev_b32_e32 v41, 16, v16
	v_and_b32_e32 v13, 0xffff0000, v16
	v_lshlrev_b32_e32 v47, 16, v17
	v_and_b32_e32 v49, 0xffff0000, v17
	s_waitcnt vmcnt(5)
	v_pk_mul_f32 v[14:15], v[18:19], v[34:35] op_sel:[0,1] op_sel_hi:[1,0]
	v_pk_mul_f32 v[16:17], v[18:19], v[34:35]
	v_pk_mul_f32 v[18:19], v[20:21], v[10:11] op_sel:[0,1] op_sel_hi:[1,0]
	v_pk_mul_f32 v[10:11], v[20:21], v[10:11]
	s_waitcnt vmcnt(4)
	v_pk_mul_f32 v[20:21], v[22:23], v[36:37] op_sel:[0,1] op_sel_hi:[1,0]
	v_pk_mul_f32 v[22:23], v[22:23], v[36:37]
	v_pk_mul_f32 v[34:35], v[24:25], v[38:39] op_sel:[0,1] op_sel_hi:[1,0]
	v_pk_mul_f32 v[24:25], v[24:25], v[38:39]
	s_waitcnt vmcnt(3)
	v_pk_mul_f32 v[36:37], v[26:27], v[40:41] op_sel:[0,1] op_sel_hi:[1,0]
	v_pk_mul_f32 v[26:27], v[26:27], v[40:41]
	v_pk_mul_f32 v[38:39], v[28:29], v[12:13] op_sel:[0,1] op_sel_hi:[1,0]
	v_pk_mul_f32 v[12:13], v[28:29], v[12:13]
	s_waitcnt vmcnt(2)
	v_pk_mul_f32 v[28:29], v[30:31], v[46:47] op_sel:[0,1] op_sel_hi:[1,0]
	v_pk_mul_f32 v[30:31], v[30:31], v[46:47]
	v_pk_mul_f32 v[40:41], v[32:33], v[48:49] op_sel:[0,1] op_sel_hi:[1,0]
	v_pk_mul_f32 v[32:33], v[32:33], v[48:49]
	v_sub_f32_e32 v14, v14, v15
	v_add_f32_e32 v15, v17, v16
	v_sub_f32_e32 v16, v18, v19
	v_add_f32_e32 v10, v10, v11
	v_sub_f32_e32 v11, v20, v21
	v_add_f32_e32 v17, v22, v23
	v_sub_f32_e32 v18, v34, v35
	v_add_f32_e32 v19, v24, v25
	v_sub_f32_e32 v20, v36, v37
	v_add_f32_e32 v21, v26, v27
	v_sub_f32_e32 v22, v38, v39
	v_add_f32_e32 v12, v12, v13
	v_sub_f32_e32 v13, v28, v29
	v_add_f32_e32 v23, v30, v31
	v_sub_f32_e32 v24, v40, v41
	v_add_f32_e32 v25, v32, v33
	v_cvt_pk_bf16_f32 v38, v14, v16
	v_cvt_pk_bf16_f32 v39, v11, v18
	v_cvt_pk_bf16_f32 v40, v20, v22
	v_cvt_pk_bf16_f32 v41, v13, v24
	v_cvt_pk_bf16_f32 v34, v15, v10
	v_cvt_pk_bf16_f32 v35, v17, v19
	v_cvt_pk_bf16_f32 v36, v21, v12
	v_cvt_pk_bf16_f32 v37, v23, v25
	global_load_dwordx4 v[10:13], v[44:45], off offset:128
	global_load_dwordx4 v[14:17], v[44:45], off offset:144
	global_load_dwordx4 v[18:21], v[44:45], off offset:160
	global_load_dwordx4 v[22:25], v[44:45], off offset:176
	v_or_b32_e32 v26, v88, v94
	v_and_or_b32 v28, v88, s2, v93
	v_mad_i64_i32 v[26:27], s[74:75], v26, s80, v[42:43]
	s_movk_i32 s2, 0x3000
	v_mad_i64_i32 v[28:29], s[74:75], v28, s80, v[42:43]
	v_add_co_u32_e32 v32, vcc, s2, v26
	v_lshl_add_u64 v[30:31], v[28:29], 0, v[86:87]
	s_nop 0
	v_addc_co_u32_e32 v33, vcc, 0, v27, vcc
	s_waitcnt vmcnt(5)
	v_lshlrev_b32_e32 v27, 16, v6
	v_and_b32_e32 v29, 0xffff0000, v6
	v_lshlrev_b32_e32 v43, 16, v7
	v_and_b32_e32 v7, 0xffff0000, v7
	v_lshlrev_b32_e32 v45, 16, v8
	v_and_b32_e32 v47, 0xffff0000, v8
	v_lshlrev_b32_e32 v49, 16, v9
	v_and_b32_e32 v9, 0xffff0000, v9
	s_waitcnt vmcnt(4)
	v_lshlrev_b32_e32 v26, 16, v2
	v_and_b32_e32 v28, 0xffff0000, v2
	v_lshlrev_b32_e32 v42, 16, v3
	v_and_b32_e32 v6, 0xffff0000, v3
	v_lshlrev_b32_e32 v44, 16, v4
	v_and_b32_e32 v46, 0xffff0000, v4
	v_and_b32_e32 v8, 0xffff0000, v5
	s_mov_b64 s[74:75], 0x3200
	v_lshlrev_b32_e32 v48, 16, v5
	v_lshl_add_u64 v[90:91], v[30:31], 0, s[74:75]
	v_add_co_u32_e32 v30, vcc, 0x3000, v30
	v_cmp_lt_u32_e64 s[74:75], 31, v177
	s_nop 0
	v_addc_co_u32_e32 v31, vcc, 0, v31, vcc
	s_waitcnt vmcnt(3)
	v_pk_mul_f32 v[2:3], v[10:11], v[26:27] op_sel:[0,1] op_sel_hi:[1,0]
	v_pk_mul_f32 v[4:5], v[10:11], v[26:27]
	v_pk_mul_f32 v[10:11], v[12:13], v[28:29] op_sel:[0,1] op_sel_hi:[1,0]
	v_pk_mul_f32 v[12:13], v[12:13], v[28:29]
	s_waitcnt vmcnt(2)
	v_pk_mul_f32 v[26:27], v[14:15], v[42:43] op_sel:[0,1] op_sel_hi:[1,0]
	v_pk_mul_f32 v[14:15], v[14:15], v[42:43]
	v_pk_mul_f32 v[28:29], v[16:17], v[6:7] op_sel:[0,1] op_sel_hi:[1,0]
	v_pk_mul_f32 v[6:7], v[16:17], v[6:7]
	s_waitcnt vmcnt(1)
	v_pk_mul_f32 v[16:17], v[18:19], v[44:45] op_sel:[0,1] op_sel_hi:[1,0]
	v_pk_mul_f32 v[18:19], v[18:19], v[44:45]
	v_pk_mul_f32 v[42:43], v[20:21], v[46:47] op_sel:[0,1] op_sel_hi:[1,0]
	v_pk_mul_f32 v[20:21], v[20:21], v[46:47]
	s_waitcnt vmcnt(0)
	v_pk_mul_f32 v[46:47], v[24:25], v[8:9] op_sel:[0,1] op_sel_hi:[1,0]
	v_pk_mul_f32 v[44:45], v[22:23], v[48:49] op_sel:[0,1] op_sel_hi:[1,0]
	v_pk_mul_f32 v[22:23], v[22:23], v[48:49]
	v_pk_mul_f32 v[8:9], v[24:25], v[8:9]
	v_sub_f32_e32 v2, v2, v3
	v_add_f32_e32 v3, v4, v5
	v_sub_f32_e32 v4, v10, v11
	v_add_f32_e32 v5, v12, v13
	v_add_f32_e32 v13, v18, v19
	v_sub_f32_e32 v18, v46, v47
	v_sub_f32_e32 v10, v26, v27
	v_add_f32_e32 v11, v14, v15
	v_sub_f32_e32 v12, v28, v29
	v_add_f32_e32 v6, v6, v7
	v_sub_f32_e32 v7, v16, v17
	v_sub_f32_e32 v14, v42, v43
	v_add_f32_e32 v15, v20, v21
	v_sub_f32_e32 v16, v44, v45
	v_add_f32_e32 v17, v22, v23
	v_add_f32_e32 v8, v8, v9
	v_cvt_pk_bf16_f32 v46, v2, v4
	v_cvt_pk_bf16_f32 v47, v10, v12
	v_cvt_pk_bf16_f32 v48, v7, v14
	v_cvt_pk_bf16_f32 v49, v16, v18
	v_cvt_pk_bf16_f32 v42, v3, v5
	v_cvt_pk_bf16_f32 v43, v11, v6
	v_cvt_pk_bf16_f32 v44, v13, v15
	v_cvt_pk_bf16_f32 v45, v17, v8
	s_waitcnt vmcnt(0)
	s_barrier
	v_add_u32_e32 v78, 0x10000, v74
	ds_read_b128 v[6:9], v78
	ds_read_b128 v[58:61], v78 offset:4096
	v_add_u32_e32 v78, 0x10000, v75
	ds_read_b128 v[26:29], v78
	ds_read_b128 v[54:57], v78 offset:4096
	v_add_u32_e32 v78, 0x10000, v76
	ds_read_b128 v[18:21], v78
	ds_read_b128 v[50:53], v78 offset:4096
	v_add_u32_e32 v78, 0x10000, v77
	ds_read_b128 v[22:25], v78
	ds_read_b128 v[62:65], v78 offset:4096
	v_mov_b64_e32 v[2:3], v[66:67]
	v_mov_b64_e32 v[4:5], v[68:69]
	v_mov_b64_e32 v[10:11], v[180:181]
	v_mov_b64_e32 v[12:13], v[182:183]
	v_lshlrev_b32_e32 v174, 16, v2
	v_lshlrev_b32_e32 v166, 16, v10
	v_and_b32_e32 v173, 0xffff0000, v2
	v_and_b32_e32 v165, 0xffff0000, v10
	v_lshlrev_b32_e32 v172, 16, v3
	v_lshlrev_b32_e32 v164, 16, v11
	v_and_b32_e32 v171, 0xffff0000, v3
	v_and_b32_e32 v163, 0xffff0000, v11
	v_lshlrev_b32_e32 v170, 16, v4
	v_lshlrev_b32_e32 v162, 16, v12
	v_and_b32_e32 v169, 0xffff0000, v4
	v_and_b32_e32 v161, 0xffff0000, v12
	v_lshlrev_b32_e32 v168, 16, v5
	v_lshlrev_b32_e32 v160, 16, v13
	v_and_b32_e32 v167, 0xffff0000, v5
	v_and_b32_e32 v89, 0xffff0000, v13
	s_waitcnt lgkmcnt(0)
	v_mfma_f32_32x32x16_bf16 v[2:17], v[38:41], v[6:9], 0
	v_or_b32_e32 v87, v177, v94
	v_mov_b32_e32 v175, 0
	v_mfma_f32_32x32x16_bf16 v[2:17], v[46:49], v[26:29], v[2:17]
	v_mfma_f32_32x32x16_bf16 v[2:17], v[34:37], v[18:21], v[2:17]
	v_mfma_f32_32x32x16_bf16 v[2:17], v[42:45], v[22:25], v[2:17]
	v_readfirstlane_b32 s2, v177
	s_cmp_gt_u32 s2, 0x1f
	s_cbranch_scc0 .Lidxp_e1
	s_waitcnt lgkmcnt(0)
	v_mfma_f32_32x32x16_bf16 v[18:33], v[38:41], v[58:61], 0
	v_mfma_f32_32x32x16_bf16 v[18:33], v[46:49], v[54:57], v[18:33]
	v_mfma_f32_32x32x16_bf16 v[18:33], v[34:37], v[50:53], v[18:33]
	v_mfma_f32_32x32x16_bf16 v[18:33], v[42:45], v[62:65], v[18:33]
	ds_read_b128 v[58:61], v74 offset:0
	ds_read_b128 v[54:57], v75 offset:0
	ds_read_b128 v[50:53], v76 offset:0
	ds_read_b128 v[62:65], v77 offset:0
	s_nop 3
	v_max_f32_e32 v2, 0, v2
	v_fma_f32 v2, v174, v2, 0
	v_max_f32_e32 v3, 0, v3
	v_fmac_f32_e32 v2, v173, v3
	v_max_f32_e32 v3, 0, v4
	v_fmac_f32_e32 v2, v172, v3
	v_max_f32_e32 v3, 0, v5
	v_fmac_f32_e32 v2, v171, v3
	v_max_f32_e32 v3, 0, v6
	v_fmac_f32_e32 v2, v170, v3
	v_max_f32_e32 v3, 0, v7
	v_fmac_f32_e32 v2, v169, v3
	v_max_f32_e32 v3, 0, v8
	v_fmac_f32_e32 v2, v168, v3
	v_max_f32_e32 v3, 0, v9
	v_fmac_f32_e32 v2, v167, v3
	v_max_f32_e32 v3, 0, v10
	v_fmac_f32_e32 v2, v166, v3
	v_max_f32_e32 v3, 0, v11
	v_fmac_f32_e32 v2, v165, v3
	v_max_f32_e32 v3, 0, v12
	v_fmac_f32_e32 v2, v164, v3
	v_max_f32_e32 v3, 0, v13
	v_fmac_f32_e32 v2, v163, v3
	v_max_f32_e32 v3, 0, v14
	v_fmac_f32_e32 v2, v162, v3
	v_max_f32_e32 v3, 0, v15
	v_fmac_f32_e32 v2, v161, v3
	v_max_f32_e32 v3, 0, v16
	v_fmac_f32_e32 v2, v160, v3
	v_max_f32_e32 v3, 0, v17
	v_fmac_f32_e32 v2, v89, v3
	v_not_b32_e32 v3, v2
	v_or_b32_e32 v4, 0x80000000, v2
	v_cmp_gt_i32_e32 vcc, 0, v2
	s_nop 1
	v_cndmask_b32_e32 v2, v4, v3, vcc
	v_cmp_le_u32_e32 vcc, v93, v87
	s_nop 1
	v_cndmask_b32_e32 v81, 0, v2, vcc
.LBB0_405:
	s_xor_b64 s[80:81], s[82:83], -1
	v_mov_b32_e32 v176, 0
	s_cmp_gt_u32 s2, 0x3f
	s_cbranch_scc0 .Lidxp_e2
	s_waitcnt lgkmcnt(0)
	v_mfma_f32_32x32x16_bf16 v[2:17], v[38:41], v[58:61], 0
	v_max_f32_e32 v18, 0, v18
	v_max_f32_e32 v19, 0, v19
	v_fma_f32 v18, v174, v18, 0
	v_max_f32_e32 v20, 0, v20
	v_fmac_f32_e32 v18, v173, v19
	v_max_f32_e32 v21, 0, v21
	v_fmac_f32_e32 v18, v172, v20
	v_max_f32_e32 v22, 0, v22
	v_fmac_f32_e32 v18, v171, v21
	v_max_f32_e32 v23, 0, v23
	v_mfma_f32_32x32x16_bf16 v[2:17], v[46:49], v[54:57], v[2:17]
	v_fmac_f32_e32 v18, v170, v22
	v_max_f32_e32 v24, 0, v24
	v_fmac_f32_e32 v18, v169, v23
	v_max_f32_e32 v25, 0, v25
	v_fmac_f32_e32 v18, v168, v24
	v_max_f32_e32 v26, 0, v26
	v_fmac_f32_e32 v18, v167, v25
	v_max_f32_e32 v27, 0, v27
	v_fmac_f32_e32 v18, v166, v26
	v_max_f32_e32 v28, 0, v28
	v_mfma_f32_32x32x16_bf16 v[2:17], v[34:37], v[50:53], v[2:17]
	v_fmac_f32_e32 v18, v165, v27
	v_max_f32_e32 v29, 0, v29
	v_fmac_f32_e32 v18, v164, v28
	v_max_f32_e32 v30, 0, v30
	v_fmac_f32_e32 v18, v163, v29
	v_fmac_f32_e32 v18, v162, v30
	v_max_f32_e32 v19, 0, v31
	v_fmac_f32_e32 v18, v161, v19
	v_max_f32_e32 v19, 0, v32
	v_fmac_f32_e32 v18, v160, v19
	v_mfma_f32_32x32x16_bf16 v[2:17], v[42:45], v[62:65], v[2:17]
	ds_read_b128 v[58:61], v74 offset:4096
	ds_read_b128 v[54:57], v75 offset:4096
	ds_read_b128 v[50:53], v76 offset:4096
	ds_read_b128 v[62:65], v77 offset:4096
	v_max_f32_e32 v19, 0, v33
	v_fmac_f32_e32 v18, v89, v19
	v_not_b32_e32 v19, v18
	v_or_b32_e32 v20, 0x80000000, v18
	v_cmp_gt_i32_e32 vcc, 0, v18
	s_nop 1
	v_cndmask_b32_e32 v18, v20, v19, vcc
	v_cmp_le_u32_e32 vcc, v96, v87
	s_nop 1
	v_cndmask_b32_e32 v175, 0, v18, vcc
.LBB0_409:
	v_mov_b32_e32 v179, 0
	s_cmp_gt_u32 s2, 0x5f
	s_cbranch_scc0 .Lidxp_e3
	s_waitcnt lgkmcnt(0)
	v_mfma_f32_32x32x16_bf16 v[18:33], v[38:41], v[58:61], 0
	v_max_f32_e32 v2, 0, v2
	v_max_f32_e32 v3, 0, v3
	v_fma_f32 v2, v174, v2, 0
	v_max_f32_e32 v4, 0, v4
	v_fmac_f32_e32 v2, v173, v3
	v_max_f32_e32 v5, 0, v5
	v_fmac_f32_e32 v2, v172, v4
	v_max_f32_e32 v6, 0, v6
	v_fmac_f32_e32 v2, v171, v5
	v_max_f32_e32 v7, 0, v7
	v_mfma_f32_32x32x16_bf16 v[18:33], v[46:49], v[54:57], v[18:33]
	v_fmac_f32_e32 v2, v170, v6
	v_max_f32_e32 v8, 0, v8
	v_fmac_f32_e32 v2, v169, v7
	v_max_f32_e32 v9, 0, v9
	v_fmac_f32_e32 v2, v168, v8
	v_max_f32_e32 v10, 0, v10
	v_fmac_f32_e32 v2, v167, v9
	v_max_f32_e32 v11, 0, v11
	v_fmac_f32_e32 v2, v166, v10
	v_max_f32_e32 v12, 0, v12
	v_mfma_f32_32x32x16_bf16 v[18:33], v[34:37], v[50:53], v[18:33]
	v_fmac_f32_e32 v2, v165, v11
	v_max_f32_e32 v13, 0, v13
	v_fmac_f32_e32 v2, v164, v12
	v_max_f32_e32 v14, 0, v14
	v_fmac_f32_e32 v2, v163, v13
	v_fmac_f32_e32 v2, v162, v14
	v_max_f32_e32 v3, 0, v15
	v_fmac_f32_e32 v2, v161, v3
	v_max_f32_e32 v3, 0, v16
	v_fmac_f32_e32 v2, v160, v3
	v_mfma_f32_32x32x16_bf16 v[18:33], v[42:45], v[62:65], v[18:33]
	ds_read_b128 v[58:61], v74 offset:8192
	ds_read_b128 v[54:57], v75 offset:8192
	ds_read_b128 v[50:53], v76 offset:8192
	ds_read_b128 v[62:65], v77 offset:8192
	v_max_f32_e32 v3, 0, v17
	v_fmac_f32_e32 v2, v89, v3
	v_not_b32_e32 v3, v2
	v_or_b32_e32 v4, 0x80000000, v2
	v_cmp_gt_i32_e32 vcc, 0, v2
	s_nop 1
	v_cndmask_b32_e32 v2, v4, v3, vcc
	v_cmp_le_u32_e32 vcc, v97, v87
	s_nop 1
	v_cndmask_b32_e32 v176, 0, v2, vcc
.LBB0_413:
	v_mov_b32_e32 v180, 0
	s_cmp_gt_u32 s2, 0x7f
	s_cbranch_scc0 .Lidxp_e4
	s_waitcnt lgkmcnt(0)
	v_mfma_f32_32x32x16_bf16 v[2:17], v[38:41], v[58:61], 0
	v_max_f32_e32 v18, 0, v18
	v_max_f32_e32 v19, 0, v19
	v_fma_f32 v18, v174, v18, 0
	v_max_f32_e32 v20, 0, v20
	v_fmac_f32_e32 v18, v173, v19
	v_max_f32_e32 v21, 0, v21
	v_fmac_f32_e32 v18, v172, v20
	v_max_f32_e32 v22, 0, v22
	v_fmac_f32_e32 v18, v171, v21
	v_max_f32_e32 v23, 0, v23
	v_mfma_f32_32x32x16_bf16 v[2:17], v[46:49], v[54:57], v[2:17]
	v_fmac_f32_e32 v18, v170, v22
	v_max_f32_e32 v24, 0, v24
	v_fmac_f32_e32 v18, v169, v23
	v_max_f32_e32 v25, 0, v25
	v_fmac_f32_e32 v18, v168, v24
	v_max_f32_e32 v26, 0, v26
	v_fmac_f32_e32 v18, v167, v25
	v_max_f32_e32 v27, 0, v27
	v_fmac_f32_e32 v18, v166, v26
	v_max_f32_e32 v28, 0, v28
	v_mfma_f32_32x32x16_bf16 v[2:17], v[34:37], v[50:53], v[2:17]
	v_fmac_f32_e32 v18, v165, v27
	v_max_f32_e32 v29, 0, v29
	v_fmac_f32_e32 v18, v164, v28
	v_max_f32_e32 v30, 0, v30
	v_fmac_f32_e32 v18, v163, v29
	v_fmac_f32_e32 v18, v162, v30
	v_max_f32_e32 v19, 0, v31
	v_fmac_f32_e32 v18, v161, v19
	v_max_f32_e32 v19, 0, v32
	v_fmac_f32_e32 v18, v160, v19
	v_mfma_f32_32x32x16_bf16 v[2:17], v[42:45], v[62:65], v[2:17]
	ds_read_b128 v[58:61], v74 offset:12288
	ds_read_b128 v[54:57], v75 offset:12288
	ds_read_b128 v[50:53], v76 offset:12288
	ds_read_b128 v[62:65], v77 offset:12288
	v_max_f32_e32 v19, 0, v33
	v_fmac_f32_e32 v18, v89, v19
	v_not_b32_e32 v19, v18
	v_or_b32_e32 v20, 0x80000000, v18
	v_cmp_gt_i32_e32 vcc, 0, v18
	s_nop 1
	v_cndmask_b32_e32 v18, v20, v19, vcc
	v_cmp_le_u32_e32 vcc, v98, v87
	s_nop 1
	v_cndmask_b32_e32 v179, 0, v18, vcc
.LBB0_417:
	v_mov_b32_e32 v181, 0
	s_cmp_gt_u32 s2, 0x9f
	s_cbranch_scc0 .Lidxp_e5
	s_waitcnt lgkmcnt(0)
	v_mfma_f32_32x32x16_bf16 v[18:33], v[38:41], v[58:61], 0
	v_max_f32_e32 v2, 0, v2
	v_max_f32_e32 v3, 0, v3
	v_fma_f32 v2, v174, v2, 0
	v_max_f32_e32 v4, 0, v4
	v_fmac_f32_e32 v2, v173, v3
	v_max_f32_e32 v5, 0, v5
	v_fmac_f32_e32 v2, v172, v4
	v_max_f32_e32 v6, 0, v6
	v_fmac_f32_e32 v2, v171, v5
	v_max_f32_e32 v7, 0, v7
	v_mfma_f32_32x32x16_bf16 v[18:33], v[46:49], v[54:57], v[18:33]
	v_fmac_f32_e32 v2, v170, v6
	v_max_f32_e32 v8, 0, v8
	v_fmac_f32_e32 v2, v169, v7
	v_max_f32_e32 v9, 0, v9
	v_fmac_f32_e32 v2, v168, v8
	v_max_f32_e32 v10, 0, v10
	v_fmac_f32_e32 v2, v167, v9
	v_max_f32_e32 v11, 0, v11
	v_fmac_f32_e32 v2, v166, v10
	v_max_f32_e32 v12, 0, v12
	v_mfma_f32_32x32x16_bf16 v[18:33], v[34:37], v[50:53], v[18:33]
	v_fmac_f32_e32 v2, v165, v11
	v_max_f32_e32 v13, 0, v13
	v_fmac_f32_e32 v2, v164, v12
	v_max_f32_e32 v14, 0, v14
	v_fmac_f32_e32 v2, v163, v13
	v_fmac_f32_e32 v2, v162, v14
	v_max_f32_e32 v3, 0, v15
	v_fmac_f32_e32 v2, v161, v3
	v_max_f32_e32 v3, 0, v16
	v_fmac_f32_e32 v2, v160, v3
	v_mfma_f32_32x32x16_bf16 v[18:33], v[42:45], v[62:65], v[18:33]
	ds_read_b128 v[58:61], v74 offset:16384
	ds_read_b128 v[54:57], v75 offset:16384
	ds_read_b128 v[50:53], v76 offset:16384
	ds_read_b128 v[62:65], v77 offset:16384
	v_max_f32_e32 v3, 0, v17
	v_fmac_f32_e32 v2, v89, v3
	v_not_b32_e32 v3, v2
	v_or_b32_e32 v4, 0x80000000, v2
	v_cmp_gt_i32_e32 vcc, 0, v2
	s_nop 1
	v_cndmask_b32_e32 v2, v4, v3, vcc
	v_cmp_le_u32_e32 vcc, v99, v87
	s_nop 1
	v_cndmask_b32_e32 v180, 0, v2, vcc
.LBB0_421:
	v_mov_b32_e32 v182, 0
	s_cmp_gt_u32 s2, 0xbf
	s_cbranch_scc0 .Lidxp_e6
	s_waitcnt lgkmcnt(0)
	v_mfma_f32_32x32x16_bf16 v[2:17], v[38:41], v[58:61], 0
	v_max_f32_e32 v18, 0, v18
	v_max_f32_e32 v19, 0, v19
	v_fma_f32 v18, v174, v18, 0
	v_max_f32_e32 v20, 0, v20
	v_fmac_f32_e32 v18, v173, v19
	v_max_f32_e32 v21, 0, v21
	v_fmac_f32_e32 v18, v172, v20
	v_max_f32_e32 v22, 0, v22
	v_fmac_f32_e32 v18, v171, v21
	v_max_f32_e32 v23, 0, v23
	v_mfma_f32_32x32x16_bf16 v[2:17], v[46:49], v[54:57], v[2:17]
	v_fmac_f32_e32 v18, v170, v22
	v_max_f32_e32 v24, 0, v24
	v_fmac_f32_e32 v18, v169, v23
	v_max_f32_e32 v25, 0, v25
	v_fmac_f32_e32 v18, v168, v24
	v_max_f32_e32 v26, 0, v26
	v_fmac_f32_e32 v18, v167, v25
	v_max_f32_e32 v27, 0, v27
	v_fmac_f32_e32 v18, v166, v26
	v_max_f32_e32 v28, 0, v28
	v_mfma_f32_32x32x16_bf16 v[2:17], v[34:37], v[50:53], v[2:17]
	v_fmac_f32_e32 v18, v165, v27
	v_max_f32_e32 v29, 0, v29
	v_fmac_f32_e32 v18, v164, v28
	v_max_f32_e32 v30, 0, v30
	v_fmac_f32_e32 v18, v163, v29
	v_fmac_f32_e32 v18, v162, v30
	v_max_f32_e32 v19, 0, v31
	v_fmac_f32_e32 v18, v161, v19
	v_max_f32_e32 v19, 0, v32
	v_fmac_f32_e32 v18, v160, v19
	v_mfma_f32_32x32x16_bf16 v[2:17], v[42:45], v[62:65], v[2:17]
	ds_read_b128 v[58:61], v74 offset:20480
	ds_read_b128 v[54:57], v75 offset:20480
	ds_read_b128 v[50:53], v76 offset:20480
	ds_read_b128 v[62:65], v77 offset:20480
	v_max_f32_e32 v19, 0, v33
	v_fmac_f32_e32 v18, v89, v19
	v_not_b32_e32 v19, v18
	v_or_b32_e32 v20, 0x80000000, v18
	v_cmp_gt_i32_e32 vcc, 0, v18
	s_nop 1
	v_cndmask_b32_e32 v18, v20, v19, vcc
	v_cmp_le_u32_e32 vcc, v100, v87
	s_nop 1
	v_cndmask_b32_e32 v181, 0, v18, vcc
.LBB0_425:
	v_mov_b32_e32 v183, 0
	s_cmp_gt_u32 s2, 0xdf
	s_cbranch_scc0 .Lidxp_e7
	s_waitcnt lgkmcnt(0)
	v_mfma_f32_32x32x16_bf16 v[18:33], v[38:41], v[58:61], 0
	v_max_f32_e32 v2, 0, v2
	v_max_f32_e32 v3, 0, v3
	v_fma_f32 v2, v174, v2, 0
	v_max_f32_e32 v4, 0, v4
	v_fmac_f32_e32 v2, v173, v3
	v_max_f32_e32 v5, 0, v5
	v_fmac_f32_e32 v2, v172, v4
	v_max_f32_e32 v6, 0, v6
	v_fmac_f32_e32 v2, v171, v5
	v_max_f32_e32 v7, 0, v7
	v_mfma_f32_32x32x16_bf16 v[18:33], v[46:49], v[54:57], v[18:33]
	v_fmac_f32_e32 v2, v170, v6
	v_max_f32_e32 v8, 0, v8
	v_fmac_f32_e32 v2, v169, v7
	v_max_f32_e32 v9, 0, v9
	v_fmac_f32_e32 v2, v168, v8
	v_max_f32_e32 v10, 0, v10
	v_fmac_f32_e32 v2, v167, v9
	v_max_f32_e32 v11, 0, v11
	v_fmac_f32_e32 v2, v166, v10
	v_max_f32_e32 v12, 0, v12
	v_mfma_f32_32x32x16_bf16 v[18:33], v[34:37], v[50:53], v[18:33]
	v_fmac_f32_e32 v2, v165, v11
	v_max_f32_e32 v13, 0, v13
	v_fmac_f32_e32 v2, v164, v12
	v_max_f32_e32 v14, 0, v14
	v_fmac_f32_e32 v2, v163, v13
	v_fmac_f32_e32 v2, v162, v14
	v_max_f32_e32 v3, 0, v15
	v_fmac_f32_e32 v2, v161, v3
	v_max_f32_e32 v3, 0, v16
	v_fmac_f32_e32 v2, v160, v3
	v_mfma_f32_32x32x16_bf16 v[18:33], v[42:45], v[62:65], v[18:33]
	ds_read_b128 v[58:61], v74 offset:24576
	ds_read_b128 v[54:57], v75 offset:24576
	ds_read_b128 v[50:53], v76 offset:24576
	ds_read_b128 v[62:65], v77 offset:24576
	v_max_f32_e32 v3, 0, v17
	v_fmac_f32_e32 v2, v89, v3
	v_not_b32_e32 v3, v2
	v_or_b32_e32 v4, 0x80000000, v2
	v_cmp_gt_i32_e32 vcc, 0, v2
	s_nop 1
	v_cndmask_b32_e32 v2, v4, v3, vcc
	v_cmp_le_u32_e32 vcc, v101, v87
	s_nop 1
	v_cndmask_b32_e32 v182, 0, v2, vcc
.LBB0_429:
	v_cmp_gt_u32_e64 s[74:75], s33, v177
	v_mov_b32_e32 v184, 0
	s_cmp_gt_u32 s2, 0xff
	s_cbranch_scc0 .Lidxp_e8
	s_waitcnt lgkmcnt(0)
	v_mfma_f32_32x32x16_bf16 v[2:17], v[38:41], v[58:61], 0
	v_max_f32_e32 v18, 0, v18
	v_max_f32_e32 v19, 0, v19
	v_fma_f32 v18, v174, v18, 0
	v_max_f32_e32 v20, 0, v20
	v_fmac_f32_e32 v18, v173, v19
	v_max_f32_e32 v21, 0, v21
	v_fmac_f32_e32 v18, v172, v20
	v_max_f32_e32 v22, 0, v22
	v_fmac_f32_e32 v18, v171, v21
	v_max_f32_e32 v23, 0, v23
	v_mfma_f32_32x32x16_bf16 v[2:17], v[46:49], v[54:57], v[2:17]
	v_fmac_f32_e32 v18, v170, v22
	v_max_f32_e32 v24, 0, v24
	v_fmac_f32_e32 v18, v169, v23
	v_max_f32_e32 v25, 0, v25
	v_fmac_f32_e32 v18, v168, v24
	v_max_f32_e32 v26, 0, v26
	v_fmac_f32_e32 v18, v167, v25
	v_max_f32_e32 v27, 0, v27
	v_fmac_f32_e32 v18, v166, v26
	v_max_f32_e32 v28, 0, v28
	v_mfma_f32_32x32x16_bf16 v[2:17], v[34:37], v[50:53], v[2:17]
	v_fmac_f32_e32 v18, v165, v27
	v_max_f32_e32 v29, 0, v29
	v_fmac_f32_e32 v18, v164, v28
	v_max_f32_e32 v30, 0, v30
	v_fmac_f32_e32 v18, v163, v29
	v_fmac_f32_e32 v18, v162, v30
	v_max_f32_e32 v19, 0, v31
	v_fmac_f32_e32 v18, v161, v19
	v_max_f32_e32 v19, 0, v32
	v_fmac_f32_e32 v18, v160, v19
	v_mfma_f32_32x32x16_bf16 v[2:17], v[42:45], v[62:65], v[2:17]
	ds_read_b128 v[58:61], v74 offset:28672
	ds_read_b128 v[54:57], v75 offset:28672
	ds_read_b128 v[50:53], v76 offset:28672
	ds_read_b128 v[62:65], v77 offset:28672
	v_max_f32_e32 v19, 0, v33
	v_fmac_f32_e32 v18, v89, v19
	v_not_b32_e32 v19, v18
	v_or_b32_e32 v20, 0x80000000, v18
	v_cmp_gt_i32_e32 vcc, 0, v18
	s_nop 1
	v_cndmask_b32_e32 v18, v20, v19, vcc
	v_cmp_le_u32_e32 vcc, v102, v87
	s_nop 1
	v_cndmask_b32_e32 v183, 0, v18, vcc
.LBB0_433:
	v_mov_b32_e32 v185, 0
	s_cmp_gt_u32 s2, 0x11f
	s_cbranch_scc0 .Lidxp_e9
	s_waitcnt lgkmcnt(0)
	s_waitcnt vmcnt(0)
	s_barrier
	v_cmp_le_u32_e32 vcc, v79, v80
	s_and_b64 vcc, exec, vcc
	s_cbranch_vccz .Lidxd_s1
	s_nop 0
	global_load_lds_dwordx4 v72, s[100:101]
	s_add_u32 m0, m0, 0x400
	s_add_u32 s100, s100, 0x1a000
	s_addc_u32 s101, s101, 0
	s_nop 0
	global_load_lds_dwordx4 v73, s[100:101]
	s_add_u32 m0, m0, 0x400
	s_add_u32 s100, s100, 0x1a000
	s_addc_u32 s101, s101, 0
	s_nop 0
	global_load_lds_dwordx4 v72, s[100:101]
	s_add_u32 m0, m0, 0x400
	s_add_u32 s100, s100, 0x1a000
	s_addc_u32 s101, s101, 0
	s_nop 0
	global_load_lds_dwordx4 v73, s[100:101]
	s_add_u32 m0, m0, 0x400
	s_add_u32 s100, s100, 0x1a000
	s_addc_u32 s101, s101, 0
	s_add_u32 m0, m0, 0x7000
	s_add_u32 s100, s100, 0x2d8000
	s_addc_u32 s101, s101, 0
	v_add_u32_e32 v79, 8, v79

.LBB0_437:
	v_mov_b32_e32 v186, 0
	s_cmp_gt_u32 s2, 0x13f
	s_cbranch_scc0 .Lidxp_e10
	s_waitcnt lgkmcnt(0)
	v_mfma_f32_32x32x16_bf16 v[2:17], v[38:41], v[58:61], 0
	v_max_f32_e32 v18, 0, v18
	v_max_f32_e32 v19, 0, v19
	v_fma_f32 v18, v174, v18, 0
	v_max_f32_e32 v20, 0, v20
	v_fmac_f32_e32 v18, v173, v19
	v_max_f32_e32 v21, 0, v21
	v_fmac_f32_e32 v18, v172, v20
	v_max_f32_e32 v22, 0, v22
	v_fmac_f32_e32 v18, v171, v21
	v_max_f32_e32 v23, 0, v23
	v_mfma_f32_32x32x16_bf16 v[2:17], v[46:49], v[54:57], v[2:17]
	v_fmac_f32_e32 v18, v170, v22
	v_max_f32_e32 v24, 0, v24
	v_fmac_f32_e32 v18, v169, v23
	v_max_f32_e32 v25, 0, v25
	v_fmac_f32_e32 v18, v168, v24
	v_max_f32_e32 v26, 0, v26
	v_fmac_f32_e32 v18, v167, v25
	v_max_f32_e32 v27, 0, v27
	v_fmac_f32_e32 v18, v166, v26
	v_max_f32_e32 v28, 0, v28
	v_mfma_f32_32x32x16_bf16 v[2:17], v[34:37], v[50:53], v[2:17]
	v_fmac_f32_e32 v18, v165, v27
	v_max_f32_e32 v29, 0, v29
	v_fmac_f32_e32 v18, v164, v28
	v_max_f32_e32 v30, 0, v30
	v_fmac_f32_e32 v18, v163, v29
	v_fmac_f32_e32 v18, v162, v30
	v_max_f32_e32 v19, 0, v31
	v_fmac_f32_e32 v18, v161, v19
	v_max_f32_e32 v19, 0, v32
	v_fmac_f32_e32 v18, v160, v19
	v_mfma_f32_32x32x16_bf16 v[2:17], v[42:45], v[62:65], v[2:17]
	ds_read_b128 v[58:61], v74 offset:36864
	ds_read_b128 v[54:57], v75 offset:36864
	ds_read_b128 v[50:53], v76 offset:36864
	ds_read_b128 v[62:65], v77 offset:36864
	v_max_f32_e32 v19, 0, v33
	v_fmac_f32_e32 v18, v89, v19
	v_not_b32_e32 v19, v18
	v_or_b32_e32 v20, 0x80000000, v18
	v_cmp_gt_i32_e32 vcc, 0, v18
	s_nop 1
	v_cndmask_b32_e32 v18, v20, v19, vcc
	v_cmp_le_u32_e32 vcc, v104, v87
	s_nop 1
	v_cndmask_b32_e32 v185, 0, v18, vcc
.LBB0_441:
	v_mov_b32_e32 v187, 0
	s_cmp_gt_u32 s2, 0x15f
	s_cbranch_scc0 .Lidxp_e11
	s_waitcnt lgkmcnt(0)
	v_mfma_f32_32x32x16_bf16 v[18:33], v[38:41], v[58:61], 0
	v_max_f32_e32 v2, 0, v2
	v_max_f32_e32 v3, 0, v3
	v_fma_f32 v2, v174, v2, 0
	v_max_f32_e32 v4, 0, v4
	v_fmac_f32_e32 v2, v173, v3
	v_max_f32_e32 v5, 0, v5
	v_fmac_f32_e32 v2, v172, v4
	v_max_f32_e32 v6, 0, v6
	v_fmac_f32_e32 v2, v171, v5
	v_max_f32_e32 v7, 0, v7
	v_mfma_f32_32x32x16_bf16 v[18:33], v[46:49], v[54:57], v[18:33]
	v_fmac_f32_e32 v2, v170, v6
	v_max_f32_e32 v8, 0, v8
	v_fmac_f32_e32 v2, v169, v7
	v_max_f32_e32 v9, 0, v9
	v_fmac_f32_e32 v2, v168, v8
	v_max_f32_e32 v10, 0, v10
	v_fmac_f32_e32 v2, v167, v9
	v_max_f32_e32 v11, 0, v11
	v_fmac_f32_e32 v2, v166, v10
	v_max_f32_e32 v12, 0, v12
	v_mfma_f32_32x32x16_bf16 v[18:33], v[34:37], v[50:53], v[18:33]
	v_fmac_f32_e32 v2, v165, v11
	v_max_f32_e32 v13, 0, v13
	v_fmac_f32_e32 v2, v164, v12
	v_max_f32_e32 v14, 0, v14
	v_fmac_f32_e32 v2, v163, v13
	v_fmac_f32_e32 v2, v162, v14
	v_max_f32_e32 v3, 0, v15
	v_fmac_f32_e32 v2, v161, v3
	v_max_f32_e32 v3, 0, v16
	v_fmac_f32_e32 v2, v160, v3
	v_mfma_f32_32x32x16_bf16 v[18:33], v[42:45], v[62:65], v[18:33]
	ds_read_b128 v[58:61], v74 offset:40960
	ds_read_b128 v[54:57], v75 offset:40960
	ds_read_b128 v[50:53], v76 offset:40960
	ds_read_b128 v[62:65], v77 offset:40960
	v_max_f32_e32 v3, 0, v17
	v_fmac_f32_e32 v2, v89, v3
	v_not_b32_e32 v3, v2
	v_or_b32_e32 v4, 0x80000000, v2
	v_cmp_gt_i32_e32 vcc, 0, v2
	s_nop 1
	v_cndmask_b32_e32 v2, v4, v3, vcc
	v_cmp_le_u32_e32 vcc, v105, v87
	s_nop 1
	v_cndmask_b32_e32 v186, 0, v2, vcc
.LBB0_445:
	v_mov_b32_e32 v188, 0
	s_cmp_gt_u32 s2, 0x17f
	s_cbranch_scc0 .Lidxp_e12
	s_waitcnt lgkmcnt(0)
	v_mfma_f32_32x32x16_bf16 v[2:17], v[38:41], v[58:61], 0
	v_max_f32_e32 v18, 0, v18
	v_max_f32_e32 v19, 0, v19
	v_fma_f32 v18, v174, v18, 0
	v_max_f32_e32 v20, 0, v20
	v_fmac_f32_e32 v18, v173, v19
	v_max_f32_e32 v21, 0, v21
	v_fmac_f32_e32 v18, v172, v20
	v_max_f32_e32 v22, 0, v22
	v_fmac_f32_e32 v18, v171, v21
	v_max_f32_e32 v23, 0, v23
	v_mfma_f32_32x32x16_bf16 v[2:17], v[46:49], v[54:57], v[2:17]
	v_fmac_f32_e32 v18, v170, v22
	v_max_f32_e32 v24, 0, v24
	v_fmac_f32_e32 v18, v169, v23
	v_max_f32_e32 v25, 0, v25
	v_fmac_f32_e32 v18, v168, v24
	v_max_f32_e32 v26, 0, v26
	v_fmac_f32_e32 v18, v167, v25
	v_max_f32_e32 v27, 0, v27
	v_fmac_f32_e32 v18, v166, v26
	v_max_f32_e32 v28, 0, v28
	v_mfma_f32_32x32x16_bf16 v[2:17], v[34:37], v[50:53], v[2:17]
	v_fmac_f32_e32 v18, v165, v27
	v_max_f32_e32 v29, 0, v29
	v_fmac_f32_e32 v18, v164, v28
	v_max_f32_e32 v30, 0, v30
	v_fmac_f32_e32 v18, v163, v29
	v_fmac_f32_e32 v18, v162, v30
	v_max_f32_e32 v19, 0, v31
	v_fmac_f32_e32 v18, v161, v19
	v_max_f32_e32 v19, 0, v32
	v_fmac_f32_e32 v18, v160, v19
	v_mfma_f32_32x32x16_bf16 v[2:17], v[42:45], v[62:65], v[2:17]
	ds_read_b128 v[58:61], v74 offset:45056
	ds_read_b128 v[54:57], v75 offset:45056
	ds_read_b128 v[50:53], v76 offset:45056
	ds_read_b128 v[62:65], v77 offset:45056
	v_max_f32_e32 v19, 0, v33
	v_fmac_f32_e32 v18, v89, v19
	v_not_b32_e32 v19, v18
	v_or_b32_e32 v20, 0x80000000, v18
	v_cmp_gt_i32_e32 vcc, 0, v18
	s_nop 1
	v_cndmask_b32_e32 v18, v20, v19, vcc
	v_cmp_le_u32_e32 vcc, v106, v87
	s_nop 1
	v_cndmask_b32_e32 v187, 0, v18, vcc
.LBB0_449:
	v_mov_b32_e32 v189, 0
	s_cmp_gt_u32 s2, 0x19f
	s_cbranch_scc0 .Lidxp_e13
	s_waitcnt lgkmcnt(0)
	v_mfma_f32_32x32x16_bf16 v[18:33], v[38:41], v[58:61], 0
	v_max_f32_e32 v2, 0, v2
	v_max_f32_e32 v3, 0, v3
	v_fma_f32 v2, v174, v2, 0
	v_max_f32_e32 v4, 0, v4
	v_fmac_f32_e32 v2, v173, v3
	v_max_f32_e32 v5, 0, v5
	v_fmac_f32_e32 v2, v172, v4
	v_max_f32_e32 v6, 0, v6
	v_fmac_f32_e32 v2, v171, v5
	v_max_f32_e32 v7, 0, v7
	v_mfma_f32_32x32x16_bf16 v[18:33], v[46:49], v[54:57], v[18:33]
	v_fmac_f32_e32 v2, v170, v6
	v_max_f32_e32 v8, 0, v8
	v_fmac_f32_e32 v2, v169, v7
	v_max_f32_e32 v9, 0, v9
	v_fmac_f32_e32 v2, v168, v8
	v_max_f32_e32 v10, 0, v10
	v_fmac_f32_e32 v2, v167, v9
	v_max_f32_e32 v11, 0, v11
	v_fmac_f32_e32 v2, v166, v10
	v_max_f32_e32 v12, 0, v12
	v_mfma_f32_32x32x16_bf16 v[18:33], v[34:37], v[50:53], v[18:33]
	v_fmac_f32_e32 v2, v165, v11
	v_max_f32_e32 v13, 0, v13
	v_fmac_f32_e32 v2, v164, v12
	v_max_f32_e32 v14, 0, v14
	v_fmac_f32_e32 v2, v163, v13
	v_fmac_f32_e32 v2, v162, v14
	v_max_f32_e32 v3, 0, v15
	v_fmac_f32_e32 v2, v161, v3
	v_max_f32_e32 v3, 0, v16
	v_fmac_f32_e32 v2, v160, v3
	v_mfma_f32_32x32x16_bf16 v[18:33], v[42:45], v[62:65], v[18:33]
	ds_read_b128 v[58:61], v74 offset:49152
	ds_read_b128 v[54:57], v75 offset:49152
	ds_read_b128 v[50:53], v76 offset:49152
	ds_read_b128 v[62:65], v77 offset:49152
	v_max_f32_e32 v3, 0, v17
	v_fmac_f32_e32 v2, v89, v3
	v_not_b32_e32 v3, v2
	v_or_b32_e32 v4, 0x80000000, v2
	v_cmp_gt_i32_e32 vcc, 0, v2
	s_nop 1
	v_cndmask_b32_e32 v2, v4, v3, vcc
	v_cmp_le_u32_e32 vcc, v107, v87
	s_nop 1
	v_cndmask_b32_e32 v188, 0, v2, vcc
.LBB0_453:
	v_mov_b32_e32 v190, 0
	s_cmp_gt_u32 s2, 0x1bf
	s_cbranch_scc0 .Lidxp_e14
	s_waitcnt lgkmcnt(0)
	v_mfma_f32_32x32x16_bf16 v[2:17], v[38:41], v[58:61], 0
	v_max_f32_e32 v18, 0, v18
	v_max_f32_e32 v19, 0, v19
	v_fma_f32 v18, v174, v18, 0
	v_max_f32_e32 v20, 0, v20
	v_fmac_f32_e32 v18, v173, v19
	v_max_f32_e32 v21, 0, v21
	v_fmac_f32_e32 v18, v172, v20
	v_max_f32_e32 v22, 0, v22
	v_fmac_f32_e32 v18, v171, v21
	v_max_f32_e32 v23, 0, v23
	v_mfma_f32_32x32x16_bf16 v[2:17], v[46:49], v[54:57], v[2:17]
	v_fmac_f32_e32 v18, v170, v22
	v_max_f32_e32 v24, 0, v24
	v_fmac_f32_e32 v18, v169, v23
	v_max_f32_e32 v25, 0, v25
	v_fmac_f32_e32 v18, v168, v24
	v_max_f32_e32 v26, 0, v26
	v_fmac_f32_e32 v18, v167, v25
	v_max_f32_e32 v27, 0, v27
	v_fmac_f32_e32 v18, v166, v26
	v_max_f32_e32 v28, 0, v28
	v_mfma_f32_32x32x16_bf16 v[2:17], v[34:37], v[50:53], v[2:17]
	v_fmac_f32_e32 v18, v165, v27
	v_max_f32_e32 v29, 0, v29
	v_fmac_f32_e32 v18, v164, v28
	v_max_f32_e32 v30, 0, v30
	v_fmac_f32_e32 v18, v163, v29
	v_fmac_f32_e32 v18, v162, v30
	v_max_f32_e32 v19, 0, v31
	v_fmac_f32_e32 v18, v161, v19
	v_max_f32_e32 v19, 0, v32
	v_fmac_f32_e32 v18, v160, v19
	v_mfma_f32_32x32x16_bf16 v[2:17], v[42:45], v[62:65], v[2:17]
	ds_read_b128 v[58:61], v74 offset:53248
	ds_read_b128 v[54:57], v75 offset:53248
	ds_read_b128 v[50:53], v76 offset:53248
	ds_read_b128 v[62:65], v77 offset:53248
	v_max_f32_e32 v19, 0, v33
	v_fmac_f32_e32 v18, v89, v19
	v_not_b32_e32 v19, v18
	v_or_b32_e32 v20, 0x80000000, v18
	v_cmp_gt_i32_e32 vcc, 0, v18
	s_nop 1
	v_cndmask_b32_e32 v18, v20, v19, vcc
	v_cmp_le_u32_e32 vcc, v108, v87
	s_nop 1
	v_cndmask_b32_e32 v189, 0, v18, vcc
.LBB0_457:
	v_mov_b32_e32 v191, 0
	s_cmp_gt_u32 s2, 0x1df
	s_cbranch_scc0 .Lidxp_e15
	s_waitcnt lgkmcnt(0)
	v_mfma_f32_32x32x16_bf16 v[18:33], v[38:41], v[58:61], 0
	v_max_f32_e32 v2, 0, v2
	v_max_f32_e32 v3, 0, v3
	v_fma_f32 v2, v174, v2, 0
	v_max_f32_e32 v4, 0, v4
	v_fmac_f32_e32 v2, v173, v3
	v_max_f32_e32 v5, 0, v5
	v_fmac_f32_e32 v2, v172, v4
	v_max_f32_e32 v6, 0, v6
	v_fmac_f32_e32 v2, v171, v5
	v_max_f32_e32 v7, 0, v7
	v_mfma_f32_32x32x16_bf16 v[18:33], v[46:49], v[54:57], v[18:33]
	v_fmac_f32_e32 v2, v170, v6
	v_max_f32_e32 v8, 0, v8
	v_fmac_f32_e32 v2, v169, v7
	v_max_f32_e32 v9, 0, v9
	v_fmac_f32_e32 v2, v168, v8
	v_max_f32_e32 v10, 0, v10
	v_fmac_f32_e32 v2, v167, v9
	v_max_f32_e32 v11, 0, v11
	v_fmac_f32_e32 v2, v166, v10
	v_max_f32_e32 v12, 0, v12
	v_mfma_f32_32x32x16_bf16 v[18:33], v[34:37], v[50:53], v[18:33]
	v_fmac_f32_e32 v2, v165, v11
	v_max_f32_e32 v13, 0, v13
	v_fmac_f32_e32 v2, v164, v12
	v_max_f32_e32 v14, 0, v14
	v_fmac_f32_e32 v2, v163, v13
	v_fmac_f32_e32 v2, v162, v14
	v_max_f32_e32 v3, 0, v15
	v_fmac_f32_e32 v2, v161, v3
	v_max_f32_e32 v3, 0, v16
	v_fmac_f32_e32 v2, v160, v3
	v_mfma_f32_32x32x16_bf16 v[18:33], v[42:45], v[62:65], v[18:33]
	ds_read_b128 v[58:61], v74 offset:57344
	ds_read_b128 v[54:57], v75 offset:57344
	ds_read_b128 v[50:53], v76 offset:57344
	ds_read_b128 v[62:65], v77 offset:57344
	v_max_f32_e32 v3, 0, v17
	v_fmac_f32_e32 v2, v89, v3
	v_not_b32_e32 v3, v2
	v_or_b32_e32 v4, 0x80000000, v2
	v_cmp_gt_i32_e32 vcc, 0, v2
	s_nop 1
	v_cndmask_b32_e32 v2, v4, v3, vcc
	v_cmp_le_u32_e32 vcc, v109, v87
	s_nop 1
	v_cndmask_b32_e32 v190, 0, v2, vcc
.LBB0_461:
	v_mov_b32_e32 v192, 0
	s_cmp_gt_u32 s2, 0x1ff
	s_cbranch_scc0 .Lidxp_e16
	s_waitcnt lgkmcnt(0)
	v_mfma_f32_32x32x16_bf16 v[2:17], v[38:41], v[58:61], 0
	v_max_f32_e32 v18, 0, v18
	v_max_f32_e32 v19, 0, v19
	v_fma_f32 v18, v174, v18, 0
	v_max_f32_e32 v20, 0, v20
	v_fmac_f32_e32 v18, v173, v19
	v_max_f32_e32 v21, 0, v21
	v_fmac_f32_e32 v18, v172, v20
	v_max_f32_e32 v22, 0, v22
	v_fmac_f32_e32 v18, v171, v21
	v_max_f32_e32 v23, 0, v23
	v_mfma_f32_32x32x16_bf16 v[2:17], v[46:49], v[54:57], v[2:17]
	v_fmac_f32_e32 v18, v170, v22
	v_max_f32_e32 v24, 0, v24
	v_fmac_f32_e32 v18, v169, v23
	v_max_f32_e32 v25, 0, v25
	v_fmac_f32_e32 v18, v168, v24
	v_max_f32_e32 v26, 0, v26
	v_fmac_f32_e32 v18, v167, v25
	v_max_f32_e32 v27, 0, v27
	v_fmac_f32_e32 v18, v166, v26
	v_max_f32_e32 v28, 0, v28
	v_mfma_f32_32x32x16_bf16 v[2:17], v[34:37], v[50:53], v[2:17]
	v_fmac_f32_e32 v18, v165, v27
	v_max_f32_e32 v29, 0, v29
	v_fmac_f32_e32 v18, v164, v28
	v_max_f32_e32 v30, 0, v30
	v_fmac_f32_e32 v18, v163, v29
	v_fmac_f32_e32 v18, v162, v30
	v_max_f32_e32 v19, 0, v31
	v_fmac_f32_e32 v18, v161, v19
	v_max_f32_e32 v19, 0, v32
	v_fmac_f32_e32 v18, v160, v19
	v_mfma_f32_32x32x16_bf16 v[2:17], v[42:45], v[62:65], v[2:17]
	ds_read_b128 v[58:61], v74 offset:61440
	ds_read_b128 v[54:57], v75 offset:61440
	ds_read_b128 v[50:53], v76 offset:61440
	ds_read_b128 v[62:65], v77 offset:61440
	v_max_f32_e32 v19, 0, v33
	v_fmac_f32_e32 v18, v89, v19
	v_not_b32_e32 v19, v18
	v_or_b32_e32 v20, 0x80000000, v18
	v_cmp_gt_i32_e32 vcc, 0, v18
	s_nop 1
	v_cndmask_b32_e32 v18, v20, v19, vcc
	v_cmp_le_u32_e32 vcc, v110, v87
	s_nop 1
	v_cndmask_b32_e32 v191, 0, v18, vcc
.LBB0_465:
	v_mov_b32_e32 v193, 0
	s_cmp_gt_u32 s2, 0x21f
	s_cbranch_scc0 .Lidxp_e17
	s_waitcnt lgkmcnt(0)
	s_waitcnt vmcnt(0)
	s_barrier
	v_cmp_le_u32_e32 vcc, v79, v80
	s_and_b64 vcc, exec, vcc
	s_cbranch_vccz .Lidxd_s2
	s_nop 0
	global_load_lds_dwordx4 v72, s[100:101]
	s_add_u32 m0, m0, 0x400
	s_add_u32 s100, s100, 0x1a000
	s_addc_u32 s101, s101, 0
	s_nop 0
	global_load_lds_dwordx4 v73, s[100:101]
	s_add_u32 m0, m0, 0x400
	s_add_u32 s100, s100, 0x1a000
	s_addc_u32 s101, s101, 0
	s_nop 0
	global_load_lds_dwordx4 v72, s[100:101]
	s_add_u32 m0, m0, 0x400
	s_add_u32 s100, s100, 0x1a000
	s_addc_u32 s101, s101, 0
	s_nop 0
	global_load_lds_dwordx4 v73, s[100:101]
	s_add_u32 m0, m0, 0x400
	s_add_u32 s100, s100, 0x1a000
	s_addc_u32 s101, s101, 0
	s_sub_u32 m0, m0, 0x9000
	s_add_u32 s100, s100, 0x2d8000
	s_addc_u32 s101, s101, 0
	v_add_u32_e32 v79, 8, v79

.LBB0_469:
	v_mov_b32_e32 v194, 0
	s_cmp_gt_u32 s2, 0x23f
	s_cbranch_scc0 .Lidxp_e18
	s_waitcnt lgkmcnt(0)
	v_mfma_f32_32x32x16_bf16 v[2:17], v[38:41], v[58:61], 0
	v_max_f32_e32 v18, 0, v18
	v_max_f32_e32 v19, 0, v19
	v_fma_f32 v18, v174, v18, 0
	v_max_f32_e32 v20, 0, v20
	v_fmac_f32_e32 v18, v173, v19
	v_max_f32_e32 v21, 0, v21
	v_fmac_f32_e32 v18, v172, v20
	v_max_f32_e32 v22, 0, v22
	v_fmac_f32_e32 v18, v171, v21
	v_max_f32_e32 v23, 0, v23
	v_mfma_f32_32x32x16_bf16 v[2:17], v[46:49], v[54:57], v[2:17]
	v_fmac_f32_e32 v18, v170, v22
	v_max_f32_e32 v24, 0, v24
	v_fmac_f32_e32 v18, v169, v23
	v_max_f32_e32 v25, 0, v25
	v_fmac_f32_e32 v18, v168, v24
	v_max_f32_e32 v26, 0, v26
	v_fmac_f32_e32 v18, v167, v25
	v_max_f32_e32 v27, 0, v27
	v_fmac_f32_e32 v18, v166, v26
	v_max_f32_e32 v28, 0, v28
	v_mfma_f32_32x32x16_bf16 v[2:17], v[34:37], v[50:53], v[2:17]
	v_fmac_f32_e32 v18, v165, v27
	v_max_f32_e32 v29, 0, v29
	v_fmac_f32_e32 v18, v164, v28
	v_max_f32_e32 v30, 0, v30
	v_fmac_f32_e32 v18, v163, v29
	v_fmac_f32_e32 v18, v162, v30
	v_max_f32_e32 v19, 0, v31
	v_fmac_f32_e32 v18, v161, v19
	v_max_f32_e32 v19, 0, v32
	v_fmac_f32_e32 v18, v160, v19
	v_mfma_f32_32x32x16_bf16 v[2:17], v[42:45], v[62:65], v[2:17]
	ds_read_b128 v[58:61], v74 offset:4096
	ds_read_b128 v[54:57], v75 offset:4096
	ds_read_b128 v[50:53], v76 offset:4096
	ds_read_b128 v[62:65], v77 offset:4096
	v_max_f32_e32 v19, 0, v33
	v_fmac_f32_e32 v18, v89, v19
	v_not_b32_e32 v19, v18
	v_or_b32_e32 v20, 0x80000000, v18
	v_cmp_gt_i32_e32 vcc, 0, v18
	s_nop 1
	v_cndmask_b32_e32 v18, v20, v19, vcc
	v_cmp_le_u32_e32 vcc, v112, v87
	s_nop 1
	v_cndmask_b32_e32 v193, 0, v18, vcc
.LBB0_473:
	v_mov_b32_e32 v195, 0
	s_cmp_gt_u32 s2, 0x25f
	s_cbranch_scc0 .Lidxp_e19
	s_waitcnt lgkmcnt(0)
	v_mfma_f32_32x32x16_bf16 v[18:33], v[38:41], v[58:61], 0
	v_max_f32_e32 v2, 0, v2
	v_max_f32_e32 v3, 0, v3
	v_fma_f32 v2, v174, v2, 0
	v_max_f32_e32 v4, 0, v4
	v_fmac_f32_e32 v2, v173, v3
	v_max_f32_e32 v5, 0, v5
	v_fmac_f32_e32 v2, v172, v4
	v_max_f32_e32 v6, 0, v6
	v_fmac_f32_e32 v2, v171, v5
	v_max_f32_e32 v7, 0, v7
	v_mfma_f32_32x32x16_bf16 v[18:33], v[46:49], v[54:57], v[18:33]
	v_fmac_f32_e32 v2, v170, v6
	v_max_f32_e32 v8, 0, v8
	v_fmac_f32_e32 v2, v169, v7
	v_max_f32_e32 v9, 0, v9
	v_fmac_f32_e32 v2, v168, v8
	v_max_f32_e32 v10, 0, v10
	v_fmac_f32_e32 v2, v167, v9
	v_max_f32_e32 v11, 0, v11
	v_fmac_f32_e32 v2, v166, v10
	v_max_f32_e32 v12, 0, v12
	v_mfma_f32_32x32x16_bf16 v[18:33], v[34:37], v[50:53], v[18:33]
	v_fmac_f32_e32 v2, v165, v11
	v_max_f32_e32 v13, 0, v13
	v_fmac_f32_e32 v2, v164, v12
	v_max_f32_e32 v14, 0, v14
	v_fmac_f32_e32 v2, v163, v13
	v_fmac_f32_e32 v2, v162, v14
	v_max_f32_e32 v3, 0, v15
	v_fmac_f32_e32 v2, v161, v3
	v_max_f32_e32 v3, 0, v16
	v_fmac_f32_e32 v2, v160, v3
	v_mfma_f32_32x32x16_bf16 v[18:33], v[42:45], v[62:65], v[18:33]
	ds_read_b128 v[58:61], v74 offset:8192
	ds_read_b128 v[54:57], v75 offset:8192
	ds_read_b128 v[50:53], v76 offset:8192
	ds_read_b128 v[62:65], v77 offset:8192
	v_max_f32_e32 v3, 0, v17
	v_fmac_f32_e32 v2, v89, v3
	v_not_b32_e32 v3, v2
	v_or_b32_e32 v4, 0x80000000, v2
	v_cmp_gt_i32_e32 vcc, 0, v2
	s_nop 1
	v_cndmask_b32_e32 v2, v4, v3, vcc
	v_cmp_le_u32_e32 vcc, v113, v87
	s_nop 1
	v_cndmask_b32_e32 v194, 0, v2, vcc
.LBB0_477:
	v_mov_b32_e32 v196, 0
	s_cmp_gt_u32 s2, 0x27f
	s_cbranch_scc0 .Lidxp_e20
	s_waitcnt lgkmcnt(0)
	v_mfma_f32_32x32x16_bf16 v[2:17], v[38:41], v[58:61], 0
	v_max_f32_e32 v18, 0, v18
	v_max_f32_e32 v19, 0, v19
	v_fma_f32 v18, v174, v18, 0
	v_max_f32_e32 v20, 0, v20
	v_fmac_f32_e32 v18, v173, v19
	v_max_f32_e32 v21, 0, v21
	v_fmac_f32_e32 v18, v172, v20
	v_max_f32_e32 v22, 0, v22
	v_fmac_f32_e32 v18, v171, v21
	v_max_f32_e32 v23, 0, v23
	v_mfma_f32_32x32x16_bf16 v[2:17], v[46:49], v[54:57], v[2:17]
	v_fmac_f32_e32 v18, v170, v22
	v_max_f32_e32 v24, 0, v24
	v_fmac_f32_e32 v18, v169, v23
	v_max_f32_e32 v25, 0, v25
	v_fmac_f32_e32 v18, v168, v24
	v_max_f32_e32 v26, 0, v26
	v_fmac_f32_e32 v18, v167, v25
	v_max_f32_e32 v27, 0, v27
	v_fmac_f32_e32 v18, v166, v26
	v_max_f32_e32 v28, 0, v28
	v_mfma_f32_32x32x16_bf16 v[2:17], v[34:37], v[50:53], v[2:17]
	v_fmac_f32_e32 v18, v165, v27
	v_max_f32_e32 v29, 0, v29
	v_fmac_f32_e32 v18, v164, v28
	v_max_f32_e32 v30, 0, v30
	v_fmac_f32_e32 v18, v163, v29
	v_fmac_f32_e32 v18, v162, v30
	v_max_f32_e32 v19, 0, v31
	v_fmac_f32_e32 v18, v161, v19
	v_max_f32_e32 v19, 0, v32
	v_fmac_f32_e32 v18, v160, v19
	v_mfma_f32_32x32x16_bf16 v[2:17], v[42:45], v[62:65], v[2:17]
	ds_read_b128 v[58:61], v74 offset:12288
	ds_read_b128 v[54:57], v75 offset:12288
	ds_read_b128 v[50:53], v76 offset:12288
	ds_read_b128 v[62:65], v77 offset:12288
	v_max_f32_e32 v19, 0, v33
	v_fmac_f32_e32 v18, v89, v19
	v_not_b32_e32 v19, v18
	v_or_b32_e32 v20, 0x80000000, v18
	v_cmp_gt_i32_e32 vcc, 0, v18
	s_nop 1
	v_cndmask_b32_e32 v18, v20, v19, vcc
	v_cmp_le_u32_e32 vcc, v114, v87
	s_nop 1
	v_cndmask_b32_e32 v195, 0, v18, vcc
.LBB0_481:
	v_mov_b32_e32 v197, 0
	s_cmp_gt_u32 s2, 0x29f
	s_cbranch_scc0 .Lidxp_e21
	s_waitcnt lgkmcnt(0)
	v_mfma_f32_32x32x16_bf16 v[18:33], v[38:41], v[58:61], 0
	v_max_f32_e32 v2, 0, v2
	v_max_f32_e32 v3, 0, v3
	v_fma_f32 v2, v174, v2, 0
	v_max_f32_e32 v4, 0, v4
	v_fmac_f32_e32 v2, v173, v3
	v_max_f32_e32 v5, 0, v5
	v_fmac_f32_e32 v2, v172, v4
	v_max_f32_e32 v6, 0, v6
	v_fmac_f32_e32 v2, v171, v5
	v_max_f32_e32 v7, 0, v7
	v_mfma_f32_32x32x16_bf16 v[18:33], v[46:49], v[54:57], v[18:33]
	v_fmac_f32_e32 v2, v170, v6
	v_max_f32_e32 v8, 0, v8
	v_fmac_f32_e32 v2, v169, v7
	v_max_f32_e32 v9, 0, v9
	v_fmac_f32_e32 v2, v168, v8
	v_max_f32_e32 v10, 0, v10
	v_fmac_f32_e32 v2, v167, v9
	v_max_f32_e32 v11, 0, v11
	v_fmac_f32_e32 v2, v166, v10
	v_max_f32_e32 v12, 0, v12
	v_mfma_f32_32x32x16_bf16 v[18:33], v[34:37], v[50:53], v[18:33]
	v_fmac_f32_e32 v2, v165, v11
	v_max_f32_e32 v13, 0, v13
	v_fmac_f32_e32 v2, v164, v12
	v_max_f32_e32 v14, 0, v14
	v_fmac_f32_e32 v2, v163, v13
	v_fmac_f32_e32 v2, v162, v14
	v_max_f32_e32 v3, 0, v15
	v_fmac_f32_e32 v2, v161, v3
	v_max_f32_e32 v3, 0, v16
	v_fmac_f32_e32 v2, v160, v3
	v_mfma_f32_32x32x16_bf16 v[18:33], v[42:45], v[62:65], v[18:33]
	ds_read_b128 v[58:61], v74 offset:16384
	ds_read_b128 v[54:57], v75 offset:16384
	ds_read_b128 v[50:53], v76 offset:16384
	ds_read_b128 v[62:65], v77 offset:16384
	v_max_f32_e32 v3, 0, v17
	v_fmac_f32_e32 v2, v89, v3
	v_not_b32_e32 v3, v2
	v_or_b32_e32 v4, 0x80000000, v2
	v_cmp_gt_i32_e32 vcc, 0, v2
	s_nop 1
	v_cndmask_b32_e32 v2, v4, v3, vcc
	v_cmp_le_u32_e32 vcc, v115, v87
	s_nop 1
	v_cndmask_b32_e32 v196, 0, v2, vcc
.LBB0_485:
	v_mov_b32_e32 v216, 0
	s_cmp_gt_u32 s2, 0x2bf
	s_cbranch_scc0 .Lidxp_e22
	s_waitcnt lgkmcnt(0)
	v_mfma_f32_32x32x16_bf16 v[2:17], v[38:41], v[58:61], 0
	v_max_f32_e32 v18, 0, v18
	v_max_f32_e32 v19, 0, v19
	v_fma_f32 v18, v174, v18, 0
	v_max_f32_e32 v20, 0, v20
	v_fmac_f32_e32 v18, v173, v19
	v_max_f32_e32 v21, 0, v21
	v_fmac_f32_e32 v18, v172, v20
	v_max_f32_e32 v22, 0, v22
	v_fmac_f32_e32 v18, v171, v21
	v_max_f32_e32 v23, 0, v23
	v_mfma_f32_32x32x16_bf16 v[2:17], v[46:49], v[54:57], v[2:17]
	v_fmac_f32_e32 v18, v170, v22
	v_max_f32_e32 v24, 0, v24
	v_fmac_f32_e32 v18, v169, v23
	v_max_f32_e32 v25, 0, v25
	v_fmac_f32_e32 v18, v168, v24
	v_max_f32_e32 v26, 0, v26
	v_fmac_f32_e32 v18, v167, v25
	v_max_f32_e32 v27, 0, v27
	v_fmac_f32_e32 v18, v166, v26
	v_max_f32_e32 v28, 0, v28
	v_mfma_f32_32x32x16_bf16 v[2:17], v[34:37], v[50:53], v[2:17]
	v_fmac_f32_e32 v18, v165, v27
	v_max_f32_e32 v29, 0, v29
	v_fmac_f32_e32 v18, v164, v28
	v_max_f32_e32 v30, 0, v30
	v_fmac_f32_e32 v18, v163, v29
	v_fmac_f32_e32 v18, v162, v30
	v_max_f32_e32 v19, 0, v31
	v_fmac_f32_e32 v18, v161, v19
	v_max_f32_e32 v19, 0, v32
	v_fmac_f32_e32 v18, v160, v19
	v_mfma_f32_32x32x16_bf16 v[2:17], v[42:45], v[62:65], v[2:17]
	ds_read_b128 v[58:61], v74 offset:20480
	ds_read_b128 v[54:57], v75 offset:20480
	ds_read_b128 v[50:53], v76 offset:20480
	ds_read_b128 v[62:65], v77 offset:20480
	v_max_f32_e32 v19, 0, v33
	v_fmac_f32_e32 v18, v89, v19
	v_not_b32_e32 v19, v18
	v_or_b32_e32 v20, 0x80000000, v18
	v_cmp_gt_i32_e32 vcc, 0, v18
	s_nop 1
	v_cndmask_b32_e32 v18, v20, v19, vcc
	v_cmp_le_u32_e32 vcc, v116, v87
	s_nop 1
	v_cndmask_b32_e32 v197, 0, v18, vcc
.LBB0_489:
	v_mov_b32_e32 v217, 0
	s_cmp_gt_u32 s2, 0x2df
	s_cbranch_scc0 .Lidxp_e23
	s_waitcnt lgkmcnt(0)
	v_mfma_f32_32x32x16_bf16 v[18:33], v[38:41], v[58:61], 0
	v_max_f32_e32 v2, 0, v2
	v_max_f32_e32 v3, 0, v3
	v_fma_f32 v2, v174, v2, 0
	v_max_f32_e32 v4, 0, v4
	v_fmac_f32_e32 v2, v173, v3
	v_max_f32_e32 v5, 0, v5
	v_fmac_f32_e32 v2, v172, v4
	v_max_f32_e32 v6, 0, v6
	v_fmac_f32_e32 v2, v171, v5
	v_max_f32_e32 v7, 0, v7
	v_mfma_f32_32x32x16_bf16 v[18:33], v[46:49], v[54:57], v[18:33]
	v_fmac_f32_e32 v2, v170, v6
	v_max_f32_e32 v8, 0, v8
	v_fmac_f32_e32 v2, v169, v7
	v_max_f32_e32 v9, 0, v9
	v_fmac_f32_e32 v2, v168, v8
	v_max_f32_e32 v10, 0, v10
	v_fmac_f32_e32 v2, v167, v9
	v_max_f32_e32 v11, 0, v11
	v_fmac_f32_e32 v2, v166, v10
	v_max_f32_e32 v12, 0, v12
	v_mfma_f32_32x32x16_bf16 v[18:33], v[34:37], v[50:53], v[18:33]
	v_fmac_f32_e32 v2, v165, v11
	v_max_f32_e32 v13, 0, v13
	v_fmac_f32_e32 v2, v164, v12
	v_max_f32_e32 v14, 0, v14
	v_fmac_f32_e32 v2, v163, v13
	v_fmac_f32_e32 v2, v162, v14
	v_max_f32_e32 v3, 0, v15
	v_fmac_f32_e32 v2, v161, v3
	v_max_f32_e32 v3, 0, v16
	v_fmac_f32_e32 v2, v160, v3
	v_mfma_f32_32x32x16_bf16 v[18:33], v[42:45], v[62:65], v[18:33]
	ds_read_b128 v[58:61], v74 offset:24576
	ds_read_b128 v[54:57], v75 offset:24576
	ds_read_b128 v[50:53], v76 offset:24576
	ds_read_b128 v[62:65], v77 offset:24576
	v_max_f32_e32 v3, 0, v17
	v_fmac_f32_e32 v2, v89, v3
	v_not_b32_e32 v3, v2
	v_or_b32_e32 v4, 0x80000000, v2
	v_cmp_gt_i32_e32 vcc, 0, v2
	s_nop 1
	v_cndmask_b32_e32 v2, v4, v3, vcc
	v_cmp_le_u32_e32 vcc, v117, v87
	s_nop 1
	v_cndmask_b32_e32 v216, 0, v2, vcc
.LBB0_493:
	v_mov_b32_e32 v218, 0
	s_cmp_gt_u32 s2, 0x2ff
	s_cbranch_scc0 .Lidxp_e24
	s_waitcnt lgkmcnt(0)
	v_mfma_f32_32x32x16_bf16 v[2:17], v[38:41], v[58:61], 0
	v_max_f32_e32 v18, 0, v18
	v_max_f32_e32 v19, 0, v19
	v_fma_f32 v18, v174, v18, 0
	v_max_f32_e32 v20, 0, v20
	v_fmac_f32_e32 v18, v173, v19
	v_max_f32_e32 v21, 0, v21
	v_fmac_f32_e32 v18, v172, v20
	v_max_f32_e32 v22, 0, v22
	v_fmac_f32_e32 v18, v171, v21
	v_max_f32_e32 v23, 0, v23
	v_mfma_f32_32x32x16_bf16 v[2:17], v[46:49], v[54:57], v[2:17]
	v_fmac_f32_e32 v18, v170, v22
	v_max_f32_e32 v24, 0, v24
	v_fmac_f32_e32 v18, v169, v23
	v_max_f32_e32 v25, 0, v25
	v_fmac_f32_e32 v18, v168, v24
	v_max_f32_e32 v26, 0, v26
	v_fmac_f32_e32 v18, v167, v25
	v_max_f32_e32 v27, 0, v27
	v_fmac_f32_e32 v18, v166, v26
	v_max_f32_e32 v28, 0, v28
	v_mfma_f32_32x32x16_bf16 v[2:17], v[34:37], v[50:53], v[2:17]
	v_fmac_f32_e32 v18, v165, v27
	v_max_f32_e32 v29, 0, v29
	v_fmac_f32_e32 v18, v164, v28
	v_max_f32_e32 v30, 0, v30
	v_fmac_f32_e32 v18, v163, v29
	v_fmac_f32_e32 v18, v162, v30
	v_max_f32_e32 v19, 0, v31
	v_fmac_f32_e32 v18, v161, v19
	v_max_f32_e32 v19, 0, v32
	v_fmac_f32_e32 v18, v160, v19
	v_mfma_f32_32x32x16_bf16 v[2:17], v[42:45], v[62:65], v[2:17]
	ds_read_b128 v[58:61], v74 offset:28672
	ds_read_b128 v[54:57], v75 offset:28672
	ds_read_b128 v[50:53], v76 offset:28672
	ds_read_b128 v[62:65], v77 offset:28672
	v_max_f32_e32 v19, 0, v33
	v_fmac_f32_e32 v18, v89, v19
	v_not_b32_e32 v19, v18
	v_or_b32_e32 v20, 0x80000000, v18
	v_cmp_gt_i32_e32 vcc, 0, v18
	s_nop 1
	v_cndmask_b32_e32 v18, v20, v19, vcc
	v_cmp_le_u32_e32 vcc, v118, v87
	s_nop 1
	v_cndmask_b32_e32 v217, 0, v18, vcc
.LBB0_497:
	v_mov_b32_e32 v219, 0
	s_cmp_gt_u32 s2, 0x31f
	s_cbranch_scc0 .Lidxp_e25
	s_waitcnt lgkmcnt(0)
	s_waitcnt vmcnt(0)
	s_barrier
	v_cmp_le_u32_e32 vcc, v79, v80
	s_and_b64 vcc, exec, vcc
	s_cbranch_vccz .Lidxd_s3
	s_nop 0
	global_load_lds_dwordx4 v72, s[100:101]
	s_add_u32 m0, m0, 0x400
	s_add_u32 s100, s100, 0x1a000
	s_addc_u32 s101, s101, 0
	s_nop 0
	global_load_lds_dwordx4 v73, s[100:101]
	s_add_u32 m0, m0, 0x400
	s_add_u32 s100, s100, 0x1a000
	s_addc_u32 s101, s101, 0
	s_nop 0
	global_load_lds_dwordx4 v72, s[100:101]
	s_add_u32 m0, m0, 0x400
	s_add_u32 s100, s100, 0x1a000
	s_addc_u32 s101, s101, 0
	s_nop 0
	global_load_lds_dwordx4 v73, s[100:101]
	s_add_u32 m0, m0, 0x400
	s_add_u32 s100, s100, 0x1a000
	s_addc_u32 s101, s101, 0
	s_add_u32 m0, m0, 0x7000
	s_add_u32 s100, s100, 0x2d8000
	s_addc_u32 s101, s101, 0
	v_add_u32_e32 v79, 8, v79

.LBB0_501:
	v_mov_b32_e32 v220, 0
	s_cmp_gt_u32 s2, 0x33f
	s_cbranch_scc0 .Lidxp_e26
	s_waitcnt lgkmcnt(0)
	v_mfma_f32_32x32x16_bf16 v[2:17], v[38:41], v[58:61], 0
	v_max_f32_e32 v18, 0, v18
	v_max_f32_e32 v19, 0, v19
	v_fma_f32 v18, v174, v18, 0
	v_max_f32_e32 v20, 0, v20
	v_fmac_f32_e32 v18, v173, v19
	v_max_f32_e32 v21, 0, v21
	v_fmac_f32_e32 v18, v172, v20
	v_max_f32_e32 v22, 0, v22
	v_fmac_f32_e32 v18, v171, v21
	v_max_f32_e32 v23, 0, v23
	v_mfma_f32_32x32x16_bf16 v[2:17], v[46:49], v[54:57], v[2:17]
	v_fmac_f32_e32 v18, v170, v22
	v_max_f32_e32 v24, 0, v24
	v_fmac_f32_e32 v18, v169, v23
	v_max_f32_e32 v25, 0, v25
	v_fmac_f32_e32 v18, v168, v24
	v_max_f32_e32 v26, 0, v26
	v_fmac_f32_e32 v18, v167, v25
	v_max_f32_e32 v27, 0, v27
	v_fmac_f32_e32 v18, v166, v26
	v_max_f32_e32 v28, 0, v28
	v_mfma_f32_32x32x16_bf16 v[2:17], v[34:37], v[50:53], v[2:17]
	v_fmac_f32_e32 v18, v165, v27
	v_max_f32_e32 v29, 0, v29
	v_fmac_f32_e32 v18, v164, v28
	v_max_f32_e32 v30, 0, v30
	v_fmac_f32_e32 v18, v163, v29
	v_fmac_f32_e32 v18, v162, v30
	v_max_f32_e32 v19, 0, v31
	v_fmac_f32_e32 v18, v161, v19
	v_max_f32_e32 v19, 0, v32
	v_fmac_f32_e32 v18, v160, v19
	v_mfma_f32_32x32x16_bf16 v[2:17], v[42:45], v[62:65], v[2:17]
	ds_read_b128 v[58:61], v74 offset:36864
	ds_read_b128 v[54:57], v75 offset:36864
	ds_read_b128 v[50:53], v76 offset:36864
	ds_read_b128 v[62:65], v77 offset:36864
	v_max_f32_e32 v19, 0, v33
	v_fmac_f32_e32 v18, v89, v19
	v_not_b32_e32 v19, v18
	v_or_b32_e32 v20, 0x80000000, v18
	v_cmp_gt_i32_e32 vcc, 0, v18
	s_nop 1
	v_cndmask_b32_e32 v18, v20, v19, vcc
	v_cmp_le_u32_e32 vcc, v120, v87
	s_nop 1
	v_cndmask_b32_e32 v219, 0, v18, vcc
.LBB0_505:
	v_mov_b32_e32 v221, 0
	s_cmp_gt_u32 s2, 0x35f
	s_cbranch_scc0 .Lidxp_e27
	s_waitcnt lgkmcnt(0)
	v_mfma_f32_32x32x16_bf16 v[18:33], v[38:41], v[58:61], 0
	v_max_f32_e32 v2, 0, v2
	v_max_f32_e32 v3, 0, v3
	v_fma_f32 v2, v174, v2, 0
	v_max_f32_e32 v4, 0, v4
	v_fmac_f32_e32 v2, v173, v3
	v_max_f32_e32 v5, 0, v5
	v_fmac_f32_e32 v2, v172, v4
	v_max_f32_e32 v6, 0, v6
	v_fmac_f32_e32 v2, v171, v5
	v_max_f32_e32 v7, 0, v7
	v_mfma_f32_32x32x16_bf16 v[18:33], v[46:49], v[54:57], v[18:33]
	v_fmac_f32_e32 v2, v170, v6
	v_max_f32_e32 v8, 0, v8
	v_fmac_f32_e32 v2, v169, v7
	v_max_f32_e32 v9, 0, v9
	v_fmac_f32_e32 v2, v168, v8
	v_max_f32_e32 v10, 0, v10
	v_fmac_f32_e32 v2, v167, v9
	v_max_f32_e32 v11, 0, v11
	v_fmac_f32_e32 v2, v166, v10
	v_max_f32_e32 v12, 0, v12
	v_mfma_f32_32x32x16_bf16 v[18:33], v[34:37], v[50:53], v[18:33]
	v_fmac_f32_e32 v2, v165, v11
	v_max_f32_e32 v13, 0, v13
	v_fmac_f32_e32 v2, v164, v12
	v_max_f32_e32 v14, 0, v14
	v_fmac_f32_e32 v2, v163, v13
	v_fmac_f32_e32 v2, v162, v14
	v_max_f32_e32 v3, 0, v15
	v_fmac_f32_e32 v2, v161, v3
	v_max_f32_e32 v3, 0, v16
	v_fmac_f32_e32 v2, v160, v3
	v_mfma_f32_32x32x16_bf16 v[18:33], v[42:45], v[62:65], v[18:33]
	ds_read_b128 v[58:61], v74 offset:40960
	ds_read_b128 v[54:57], v75 offset:40960
	ds_read_b128 v[50:53], v76 offset:40960
	ds_read_b128 v[62:65], v77 offset:40960
	v_max_f32_e32 v3, 0, v17
	v_fmac_f32_e32 v2, v89, v3
	v_not_b32_e32 v3, v2
	v_or_b32_e32 v4, 0x80000000, v2
	v_cmp_gt_i32_e32 vcc, 0, v2
	s_nop 1
	v_cndmask_b32_e32 v2, v4, v3, vcc
	v_cmp_le_u32_e32 vcc, v121, v87
	s_nop 1
	v_cndmask_b32_e32 v220, 0, v2, vcc
.LBB0_509:
	v_mov_b32_e32 v222, 0
	s_cmp_gt_u32 s2, 0x37f
	s_cbranch_scc0 .Lidxp_e28
	s_waitcnt lgkmcnt(0)
	v_mfma_f32_32x32x16_bf16 v[2:17], v[38:41], v[58:61], 0
	v_max_f32_e32 v18, 0, v18
	v_max_f32_e32 v19, 0, v19
	v_fma_f32 v18, v174, v18, 0
	v_max_f32_e32 v20, 0, v20
	v_fmac_f32_e32 v18, v173, v19
	v_max_f32_e32 v21, 0, v21
	v_fmac_f32_e32 v18, v172, v20
	v_max_f32_e32 v22, 0, v22
	v_fmac_f32_e32 v18, v171, v21
	v_max_f32_e32 v23, 0, v23
	v_mfma_f32_32x32x16_bf16 v[2:17], v[46:49], v[54:57], v[2:17]
	v_fmac_f32_e32 v18, v170, v22
	v_max_f32_e32 v24, 0, v24
	v_fmac_f32_e32 v18, v169, v23
	v_max_f32_e32 v25, 0, v25
	v_fmac_f32_e32 v18, v168, v24
	v_max_f32_e32 v26, 0, v26
	v_fmac_f32_e32 v18, v167, v25
	v_max_f32_e32 v27, 0, v27
	v_fmac_f32_e32 v18, v166, v26
	v_max_f32_e32 v28, 0, v28
	v_mfma_f32_32x32x16_bf16 v[2:17], v[34:37], v[50:53], v[2:17]
	v_fmac_f32_e32 v18, v165, v27
	v_max_f32_e32 v29, 0, v29
	v_fmac_f32_e32 v18, v164, v28
	v_max_f32_e32 v30, 0, v30
	v_fmac_f32_e32 v18, v163, v29
	v_fmac_f32_e32 v18, v162, v30
	v_max_f32_e32 v19, 0, v31
	v_fmac_f32_e32 v18, v161, v19
	v_max_f32_e32 v19, 0, v32
	v_fmac_f32_e32 v18, v160, v19
	v_mfma_f32_32x32x16_bf16 v[2:17], v[42:45], v[62:65], v[2:17]
	ds_read_b128 v[58:61], v74 offset:45056
	ds_read_b128 v[54:57], v75 offset:45056
	ds_read_b128 v[50:53], v76 offset:45056
	ds_read_b128 v[62:65], v77 offset:45056
	v_max_f32_e32 v19, 0, v33
	v_fmac_f32_e32 v18, v89, v19
	v_not_b32_e32 v19, v18
	v_or_b32_e32 v20, 0x80000000, v18
	v_cmp_gt_i32_e32 vcc, 0, v18
	s_nop 1
	v_cndmask_b32_e32 v18, v20, v19, vcc
	v_cmp_le_u32_e32 vcc, v122, v87
	s_nop 1
	v_cndmask_b32_e32 v221, 0, v18, vcc
.LBB0_513:
	v_mov_b32_e32 v223, 0
	s_cmp_gt_u32 s2, 0x39f
	s_cbranch_scc0 .Lidxp_e29
	s_waitcnt lgkmcnt(0)
	v_mfma_f32_32x32x16_bf16 v[18:33], v[38:41], v[58:61], 0
	v_max_f32_e32 v2, 0, v2
	v_max_f32_e32 v3, 0, v3
	v_fma_f32 v2, v174, v2, 0
	v_max_f32_e32 v4, 0, v4
	v_fmac_f32_e32 v2, v173, v3
	v_max_f32_e32 v5, 0, v5
	v_fmac_f32_e32 v2, v172, v4
	v_max_f32_e32 v6, 0, v6
	v_fmac_f32_e32 v2, v171, v5
	v_max_f32_e32 v7, 0, v7
	v_mfma_f32_32x32x16_bf16 v[18:33], v[46:49], v[54:57], v[18:33]
	v_fmac_f32_e32 v2, v170, v6
	v_max_f32_e32 v8, 0, v8
	v_fmac_f32_e32 v2, v169, v7
	v_max_f32_e32 v9, 0, v9
	v_fmac_f32_e32 v2, v168, v8
	v_max_f32_e32 v10, 0, v10
	v_fmac_f32_e32 v2, v167, v9
	v_max_f32_e32 v11, 0, v11
	v_fmac_f32_e32 v2, v166, v10
	v_max_f32_e32 v12, 0, v12
	v_mfma_f32_32x32x16_bf16 v[18:33], v[34:37], v[50:53], v[18:33]
	v_fmac_f32_e32 v2, v165, v11
	v_max_f32_e32 v13, 0, v13
	v_fmac_f32_e32 v2, v164, v12
	v_max_f32_e32 v14, 0, v14
	v_fmac_f32_e32 v2, v163, v13
	v_fmac_f32_e32 v2, v162, v14
	v_max_f32_e32 v3, 0, v15
	v_fmac_f32_e32 v2, v161, v3
	v_max_f32_e32 v3, 0, v16
	v_fmac_f32_e32 v2, v160, v3
	v_mfma_f32_32x32x16_bf16 v[18:33], v[42:45], v[62:65], v[18:33]
	ds_read_b128 v[58:61], v74 offset:49152
	ds_read_b128 v[54:57], v75 offset:49152
	ds_read_b128 v[50:53], v76 offset:49152
	ds_read_b128 v[62:65], v77 offset:49152
	v_max_f32_e32 v3, 0, v17
	v_fmac_f32_e32 v2, v89, v3
	v_not_b32_e32 v3, v2
	v_or_b32_e32 v4, 0x80000000, v2
	v_cmp_gt_i32_e32 vcc, 0, v2
	s_nop 1
	v_cndmask_b32_e32 v2, v4, v3, vcc
	v_cmp_le_u32_e32 vcc, v123, v87
	s_nop 1
	v_cndmask_b32_e32 v222, 0, v2, vcc
.LBB0_517:
	v_mov_b32_e32 v224, 0
	s_cmp_gt_u32 s2, 0x3bf
	s_cbranch_scc0 .Lidxp_e30
	s_waitcnt lgkmcnt(0)
	v_mfma_f32_32x32x16_bf16 v[2:17], v[38:41], v[58:61], 0
	v_max_f32_e32 v18, 0, v18
	v_max_f32_e32 v19, 0, v19
	v_fma_f32 v18, v174, v18, 0
	v_max_f32_e32 v20, 0, v20
	v_fmac_f32_e32 v18, v173, v19
	v_max_f32_e32 v21, 0, v21
	v_fmac_f32_e32 v18, v172, v20
	v_max_f32_e32 v22, 0, v22
	v_fmac_f32_e32 v18, v171, v21
	v_max_f32_e32 v23, 0, v23
	v_mfma_f32_32x32x16_bf16 v[2:17], v[46:49], v[54:57], v[2:17]
	v_fmac_f32_e32 v18, v170, v22
	v_max_f32_e32 v24, 0, v24
	v_fmac_f32_e32 v18, v169, v23
	v_max_f32_e32 v25, 0, v25
	v_fmac_f32_e32 v18, v168, v24
	v_max_f32_e32 v26, 0, v26
	v_fmac_f32_e32 v18, v167, v25
	v_max_f32_e32 v27, 0, v27
	v_fmac_f32_e32 v18, v166, v26
	v_max_f32_e32 v28, 0, v28
	v_mfma_f32_32x32x16_bf16 v[2:17], v[34:37], v[50:53], v[2:17]
	v_fmac_f32_e32 v18, v165, v27
	v_max_f32_e32 v29, 0, v29
	v_fmac_f32_e32 v18, v164, v28
	v_max_f32_e32 v30, 0, v30
	v_fmac_f32_e32 v18, v163, v29
	v_fmac_f32_e32 v18, v162, v30
	v_max_f32_e32 v19, 0, v31
	v_fmac_f32_e32 v18, v161, v19
	v_max_f32_e32 v19, 0, v32
	v_fmac_f32_e32 v18, v160, v19
	v_mfma_f32_32x32x16_bf16 v[2:17], v[42:45], v[62:65], v[2:17]
	ds_read_b128 v[58:61], v74 offset:53248
	ds_read_b128 v[54:57], v75 offset:53248
	ds_read_b128 v[50:53], v76 offset:53248
	ds_read_b128 v[62:65], v77 offset:53248
	v_max_f32_e32 v19, 0, v33
	v_fmac_f32_e32 v18, v89, v19
	v_not_b32_e32 v19, v18
	v_or_b32_e32 v20, 0x80000000, v18
	v_cmp_gt_i32_e32 vcc, 0, v18
	s_nop 1
	v_cndmask_b32_e32 v18, v20, v19, vcc
	v_cmp_le_u32_e32 vcc, v124, v87
	s_nop 1
	v_cndmask_b32_e32 v223, 0, v18, vcc
.LBB0_521:
	v_mov_b32_e32 v225, 0
	s_cmp_gt_u32 s2, 0x3df
	s_cbranch_scc0 .Lidxp_e31
	s_waitcnt lgkmcnt(0)
	v_mfma_f32_32x32x16_bf16 v[18:33], v[38:41], v[58:61], 0
	v_max_f32_e32 v2, 0, v2
	v_max_f32_e32 v3, 0, v3
	v_fma_f32 v2, v174, v2, 0
	v_max_f32_e32 v4, 0, v4
	v_fmac_f32_e32 v2, v173, v3
	v_max_f32_e32 v5, 0, v5
	v_fmac_f32_e32 v2, v172, v4
	v_max_f32_e32 v6, 0, v6
	v_fmac_f32_e32 v2, v171, v5
	v_max_f32_e32 v7, 0, v7
	v_mfma_f32_32x32x16_bf16 v[18:33], v[46:49], v[54:57], v[18:33]
	v_fmac_f32_e32 v2, v170, v6
	v_max_f32_e32 v8, 0, v8
	v_fmac_f32_e32 v2, v169, v7
	v_max_f32_e32 v9, 0, v9
	v_fmac_f32_e32 v2, v168, v8
	v_max_f32_e32 v10, 0, v10
	v_fmac_f32_e32 v2, v167, v9
	v_max_f32_e32 v11, 0, v11
	v_fmac_f32_e32 v2, v166, v10
	v_max_f32_e32 v12, 0, v12
	v_mfma_f32_32x32x16_bf16 v[18:33], v[34:37], v[50:53], v[18:33]
	v_fmac_f32_e32 v2, v165, v11
	v_max_f32_e32 v13, 0, v13
	v_fmac_f32_e32 v2, v164, v12
	v_max_f32_e32 v14, 0, v14
	v_fmac_f32_e32 v2, v163, v13
	v_fmac_f32_e32 v2, v162, v14
	v_max_f32_e32 v3, 0, v15
	v_fmac_f32_e32 v2, v161, v3
	v_max_f32_e32 v3, 0, v16
	v_fmac_f32_e32 v2, v160, v3
	v_mfma_f32_32x32x16_bf16 v[18:33], v[42:45], v[62:65], v[18:33]
	ds_read_b128 v[58:61], v74 offset:57344
	ds_read_b128 v[54:57], v75 offset:57344
	ds_read_b128 v[50:53], v76 offset:57344
	ds_read_b128 v[62:65], v77 offset:57344
	v_max_f32_e32 v3, 0, v17
	v_fmac_f32_e32 v2, v89, v3
	v_not_b32_e32 v3, v2
	v_or_b32_e32 v4, 0x80000000, v2
	v_cmp_gt_i32_e32 vcc, 0, v2
	s_nop 1
	v_cndmask_b32_e32 v2, v4, v3, vcc
	v_cmp_le_u32_e32 vcc, v125, v87
	s_nop 1
	v_cndmask_b32_e32 v224, 0, v2, vcc
.LBB0_525:
	v_mov_b32_e32 v226, 0
	s_cmp_gt_u32 s2, 0x3ff
	s_cbranch_scc0 .Lidxp_e32
	s_waitcnt lgkmcnt(0)
	v_mfma_f32_32x32x16_bf16 v[2:17], v[38:41], v[58:61], 0
	v_max_f32_e32 v18, 0, v18
	v_max_f32_e32 v19, 0, v19
	v_fma_f32 v18, v174, v18, 0
	v_max_f32_e32 v20, 0, v20
	v_fmac_f32_e32 v18, v173, v19
	v_max_f32_e32 v21, 0, v21
	v_fmac_f32_e32 v18, v172, v20
	v_max_f32_e32 v22, 0, v22
	v_fmac_f32_e32 v18, v171, v21
	v_max_f32_e32 v23, 0, v23
	v_mfma_f32_32x32x16_bf16 v[2:17], v[46:49], v[54:57], v[2:17]
	v_fmac_f32_e32 v18, v170, v22
	v_max_f32_e32 v24, 0, v24
	v_fmac_f32_e32 v18, v169, v23
	v_max_f32_e32 v25, 0, v25
	v_fmac_f32_e32 v18, v168, v24
	v_max_f32_e32 v26, 0, v26
	v_fmac_f32_e32 v18, v167, v25
	v_max_f32_e32 v27, 0, v27
	v_fmac_f32_e32 v18, v166, v26
	v_max_f32_e32 v28, 0, v28
	v_mfma_f32_32x32x16_bf16 v[2:17], v[34:37], v[50:53], v[2:17]
	v_fmac_f32_e32 v18, v165, v27
	v_max_f32_e32 v29, 0, v29
	v_fmac_f32_e32 v18, v164, v28
	v_max_f32_e32 v30, 0, v30
	v_fmac_f32_e32 v18, v163, v29
	v_fmac_f32_e32 v18, v162, v30
	v_max_f32_e32 v19, 0, v31
	v_fmac_f32_e32 v18, v161, v19
	v_max_f32_e32 v19, 0, v32
	v_fmac_f32_e32 v18, v160, v19
	v_mfma_f32_32x32x16_bf16 v[2:17], v[42:45], v[62:65], v[2:17]
	ds_read_b128 v[58:61], v74 offset:61440
	ds_read_b128 v[54:57], v75 offset:61440
	ds_read_b128 v[50:53], v76 offset:61440
	ds_read_b128 v[62:65], v77 offset:61440
	v_max_f32_e32 v19, 0, v33
	v_fmac_f32_e32 v18, v89, v19
	v_not_b32_e32 v19, v18
	v_or_b32_e32 v20, 0x80000000, v18
	v_cmp_gt_i32_e32 vcc, 0, v18
	s_nop 1
	v_cndmask_b32_e32 v18, v20, v19, vcc
	v_cmp_le_u32_e32 vcc, v126, v87
	s_nop 1
	v_cndmask_b32_e32 v225, 0, v18, vcc
.LBB0_529:
	v_mov_b32_e32 v227, 0
	s_cmp_gt_u32 s2, 0x41f
	s_cbranch_scc0 .Lidxp_e33
	s_waitcnt lgkmcnt(0)
	s_waitcnt vmcnt(0)
	s_barrier
	v_cmp_le_u32_e32 vcc, v79, v80
	s_and_b64 vcc, exec, vcc
	s_cbranch_vccz .Lidxd_s4
	s_nop 0
	global_load_lds_dwordx4 v72, s[100:101]
	s_add_u32 m0, m0, 0x400
	s_add_u32 s100, s100, 0x1a000
	s_addc_u32 s101, s101, 0
	s_nop 0
	global_load_lds_dwordx4 v73, s[100:101]
	s_add_u32 m0, m0, 0x400
	s_add_u32 s100, s100, 0x1a000
	s_addc_u32 s101, s101, 0
	s_nop 0
	global_load_lds_dwordx4 v72, s[100:101]
	s_add_u32 m0, m0, 0x400
	s_add_u32 s100, s100, 0x1a000
	s_addc_u32 s101, s101, 0
	s_nop 0
	global_load_lds_dwordx4 v73, s[100:101]
	s_add_u32 m0, m0, 0x400
	s_add_u32 s100, s100, 0x1a000
	s_addc_u32 s101, s101, 0
	s_sub_u32 m0, m0, 0x9000
	s_add_u32 s100, s100, 0x2d8000
	s_addc_u32 s101, s101, 0
	v_add_u32_e32 v79, 8, v79

.LBB0_533:
	v_mov_b32_e32 v228, 0
	s_cmp_gt_u32 s2, 0x43f
	s_cbranch_scc0 .Lidxp_e34
	s_waitcnt lgkmcnt(0)
	v_mfma_f32_32x32x16_bf16 v[2:17], v[38:41], v[58:61], 0
	v_max_f32_e32 v18, 0, v18
	v_max_f32_e32 v19, 0, v19
	v_fma_f32 v18, v174, v18, 0
	v_max_f32_e32 v20, 0, v20
	v_fmac_f32_e32 v18, v173, v19
	v_max_f32_e32 v21, 0, v21
	v_fmac_f32_e32 v18, v172, v20
	v_max_f32_e32 v22, 0, v22
	v_fmac_f32_e32 v18, v171, v21
	v_max_f32_e32 v23, 0, v23
	v_mfma_f32_32x32x16_bf16 v[2:17], v[46:49], v[54:57], v[2:17]
	v_fmac_f32_e32 v18, v170, v22
	v_max_f32_e32 v24, 0, v24
	v_fmac_f32_e32 v18, v169, v23
	v_max_f32_e32 v25, 0, v25
	v_fmac_f32_e32 v18, v168, v24
	v_max_f32_e32 v26, 0, v26
	v_fmac_f32_e32 v18, v167, v25
	v_max_f32_e32 v27, 0, v27
	v_fmac_f32_e32 v18, v166, v26
	v_max_f32_e32 v28, 0, v28
	v_mfma_f32_32x32x16_bf16 v[2:17], v[34:37], v[50:53], v[2:17]
	v_fmac_f32_e32 v18, v165, v27
	v_max_f32_e32 v29, 0, v29
	v_fmac_f32_e32 v18, v164, v28
	v_max_f32_e32 v30, 0, v30
	v_fmac_f32_e32 v18, v163, v29
	v_fmac_f32_e32 v18, v162, v30
	v_max_f32_e32 v19, 0, v31
	v_fmac_f32_e32 v18, v161, v19
	v_max_f32_e32 v19, 0, v32
	v_fmac_f32_e32 v18, v160, v19
	v_mfma_f32_32x32x16_bf16 v[2:17], v[42:45], v[62:65], v[2:17]
	ds_read_b128 v[58:61], v74 offset:4096
	ds_read_b128 v[54:57], v75 offset:4096
	ds_read_b128 v[50:53], v76 offset:4096
	ds_read_b128 v[62:65], v77 offset:4096
	v_max_f32_e32 v19, 0, v33
	v_fmac_f32_e32 v18, v89, v19
	v_not_b32_e32 v19, v18
	v_or_b32_e32 v20, 0x80000000, v18
	v_cmp_gt_i32_e32 vcc, 0, v18
	s_nop 1
	v_cndmask_b32_e32 v18, v20, v19, vcc
	v_cmp_le_u32_e32 vcc, v128, v87
	s_nop 1
	v_cndmask_b32_e32 v227, 0, v18, vcc
.LBB0_537:
	v_mov_b32_e32 v229, 0
	s_cmp_gt_u32 s2, 0x45f
	s_cbranch_scc0 .Lidxp_e35
	s_waitcnt lgkmcnt(0)
	v_mfma_f32_32x32x16_bf16 v[18:33], v[38:41], v[58:61], 0
	v_max_f32_e32 v2, 0, v2
	v_max_f32_e32 v3, 0, v3
	v_fma_f32 v2, v174, v2, 0
	v_max_f32_e32 v4, 0, v4
	v_fmac_f32_e32 v2, v173, v3
	v_max_f32_e32 v5, 0, v5
	v_fmac_f32_e32 v2, v172, v4
	v_max_f32_e32 v6, 0, v6
	v_fmac_f32_e32 v2, v171, v5
	v_max_f32_e32 v7, 0, v7
	v_mfma_f32_32x32x16_bf16 v[18:33], v[46:49], v[54:57], v[18:33]
	v_fmac_f32_e32 v2, v170, v6
	v_max_f32_e32 v8, 0, v8
	v_fmac_f32_e32 v2, v169, v7
	v_max_f32_e32 v9, 0, v9
	v_fmac_f32_e32 v2, v168, v8
	v_max_f32_e32 v10, 0, v10
	v_fmac_f32_e32 v2, v167, v9
	v_max_f32_e32 v11, 0, v11
	v_fmac_f32_e32 v2, v166, v10
	v_max_f32_e32 v12, 0, v12
	v_mfma_f32_32x32x16_bf16 v[18:33], v[34:37], v[50:53], v[18:33]
	v_fmac_f32_e32 v2, v165, v11
	v_max_f32_e32 v13, 0, v13
	v_fmac_f32_e32 v2, v164, v12
	v_max_f32_e32 v14, 0, v14
	v_fmac_f32_e32 v2, v163, v13
	v_fmac_f32_e32 v2, v162, v14
	v_max_f32_e32 v3, 0, v15
	v_fmac_f32_e32 v2, v161, v3
	v_max_f32_e32 v3, 0, v16
	v_fmac_f32_e32 v2, v160, v3
	v_mfma_f32_32x32x16_bf16 v[18:33], v[42:45], v[62:65], v[18:33]
	ds_read_b128 v[58:61], v74 offset:8192
	ds_read_b128 v[54:57], v75 offset:8192
	ds_read_b128 v[50:53], v76 offset:8192
	ds_read_b128 v[62:65], v77 offset:8192
	v_max_f32_e32 v3, 0, v17
	v_fmac_f32_e32 v2, v89, v3
	v_not_b32_e32 v3, v2
	v_or_b32_e32 v4, 0x80000000, v2
	v_cmp_gt_i32_e32 vcc, 0, v2
	s_nop 1
	v_cndmask_b32_e32 v2, v4, v3, vcc
	v_cmp_le_u32_e32 vcc, v129, v87
	s_nop 1
	v_cndmask_b32_e32 v228, 0, v2, vcc
.LBB0_541:
	v_mov_b32_e32 v230, 0
	s_cmp_gt_u32 s2, 0x47f
	s_cbranch_scc0 .Lidxp_e36
	s_waitcnt lgkmcnt(0)
	v_mfma_f32_32x32x16_bf16 v[2:17], v[38:41], v[58:61], 0
	v_max_f32_e32 v18, 0, v18
	v_max_f32_e32 v19, 0, v19
	v_fma_f32 v18, v174, v18, 0
	v_max_f32_e32 v20, 0, v20
	v_fmac_f32_e32 v18, v173, v19
	v_max_f32_e32 v21, 0, v21
	v_fmac_f32_e32 v18, v172, v20
	v_max_f32_e32 v22, 0, v22
	v_fmac_f32_e32 v18, v171, v21
	v_max_f32_e32 v23, 0, v23
	v_mfma_f32_32x32x16_bf16 v[2:17], v[46:49], v[54:57], v[2:17]
	v_fmac_f32_e32 v18, v170, v22
	v_max_f32_e32 v24, 0, v24
	v_fmac_f32_e32 v18, v169, v23
	v_max_f32_e32 v25, 0, v25
	v_fmac_f32_e32 v18, v168, v24
	v_max_f32_e32 v26, 0, v26
	v_fmac_f32_e32 v18, v167, v25
	v_max_f32_e32 v27, 0, v27
	v_fmac_f32_e32 v18, v166, v26
	v_max_f32_e32 v28, 0, v28
	v_mfma_f32_32x32x16_bf16 v[2:17], v[34:37], v[50:53], v[2:17]
	v_fmac_f32_e32 v18, v165, v27
	v_max_f32_e32 v29, 0, v29
	v_fmac_f32_e32 v18, v164, v28
	v_max_f32_e32 v30, 0, v30
	v_fmac_f32_e32 v18, v163, v29
	v_fmac_f32_e32 v18, v162, v30
	v_max_f32_e32 v19, 0, v31
	v_fmac_f32_e32 v18, v161, v19
	v_max_f32_e32 v19, 0, v32
	v_fmac_f32_e32 v18, v160, v19
	v_mfma_f32_32x32x16_bf16 v[2:17], v[42:45], v[62:65], v[2:17]
	ds_read_b128 v[58:61], v74 offset:12288
	ds_read_b128 v[54:57], v75 offset:12288
	ds_read_b128 v[50:53], v76 offset:12288
	ds_read_b128 v[62:65], v77 offset:12288
	v_max_f32_e32 v19, 0, v33
	v_fmac_f32_e32 v18, v89, v19
	v_not_b32_e32 v19, v18
	v_or_b32_e32 v20, 0x80000000, v18
	v_cmp_gt_i32_e32 vcc, 0, v18
	s_nop 1
	v_cndmask_b32_e32 v18, v20, v19, vcc
	v_cmp_le_u32_e32 vcc, v130, v87
	s_nop 1
	v_cndmask_b32_e32 v229, 0, v18, vcc
.LBB0_545:
	v_mov_b32_e32 v231, 0
	s_cmp_gt_u32 s2, 0x49f
	s_cbranch_scc0 .Lidxp_e37
	s_waitcnt lgkmcnt(0)
	v_mfma_f32_32x32x16_bf16 v[18:33], v[38:41], v[58:61], 0
	v_max_f32_e32 v2, 0, v2
	v_max_f32_e32 v3, 0, v3
	v_fma_f32 v2, v174, v2, 0
	v_max_f32_e32 v4, 0, v4
	v_fmac_f32_e32 v2, v173, v3
	v_max_f32_e32 v5, 0, v5
	v_fmac_f32_e32 v2, v172, v4
	v_max_f32_e32 v6, 0, v6
	v_fmac_f32_e32 v2, v171, v5
	v_max_f32_e32 v7, 0, v7
	v_mfma_f32_32x32x16_bf16 v[18:33], v[46:49], v[54:57], v[18:33]
	v_fmac_f32_e32 v2, v170, v6
	v_max_f32_e32 v8, 0, v8
	v_fmac_f32_e32 v2, v169, v7
	v_max_f32_e32 v9, 0, v9
	v_fmac_f32_e32 v2, v168, v8
	v_max_f32_e32 v10, 0, v10
	v_fmac_f32_e32 v2, v167, v9
	v_max_f32_e32 v11, 0, v11
	v_fmac_f32_e32 v2, v166, v10
	v_max_f32_e32 v12, 0, v12
	v_mfma_f32_32x32x16_bf16 v[18:33], v[34:37], v[50:53], v[18:33]
	v_fmac_f32_e32 v2, v165, v11
	v_max_f32_e32 v13, 0, v13
	v_fmac_f32_e32 v2, v164, v12
	v_max_f32_e32 v14, 0, v14
	v_fmac_f32_e32 v2, v163, v13
	v_fmac_f32_e32 v2, v162, v14
	v_max_f32_e32 v3, 0, v15
	v_fmac_f32_e32 v2, v161, v3
	v_max_f32_e32 v3, 0, v16
	v_fmac_f32_e32 v2, v160, v3
	v_mfma_f32_32x32x16_bf16 v[18:33], v[42:45], v[62:65], v[18:33]
	ds_read_b128 v[58:61], v74 offset:16384
	ds_read_b128 v[54:57], v75 offset:16384
	ds_read_b128 v[50:53], v76 offset:16384
	ds_read_b128 v[62:65], v77 offset:16384
	v_max_f32_e32 v3, 0, v17
	v_fmac_f32_e32 v2, v89, v3
	v_not_b32_e32 v3, v2
	v_or_b32_e32 v4, 0x80000000, v2
	v_cmp_gt_i32_e32 vcc, 0, v2
	s_nop 1
	v_cndmask_b32_e32 v2, v4, v3, vcc
	v_cmp_le_u32_e32 vcc, v131, v87
	s_nop 1
	v_cndmask_b32_e32 v230, 0, v2, vcc
.LBB0_549:
	v_mov_b32_e32 v232, 0
	s_cmp_gt_u32 s2, 0x4bf
	s_cbranch_scc0 .Lidxp_e38
	s_waitcnt lgkmcnt(0)
	v_mfma_f32_32x32x16_bf16 v[2:17], v[38:41], v[58:61], 0
	v_max_f32_e32 v18, 0, v18
	v_max_f32_e32 v19, 0, v19
	v_fma_f32 v18, v174, v18, 0
	v_max_f32_e32 v20, 0, v20
	v_fmac_f32_e32 v18, v173, v19
	v_max_f32_e32 v21, 0, v21
	v_fmac_f32_e32 v18, v172, v20
	v_max_f32_e32 v22, 0, v22
	v_fmac_f32_e32 v18, v171, v21
	v_max_f32_e32 v23, 0, v23
	v_mfma_f32_32x32x16_bf16 v[2:17], v[46:49], v[54:57], v[2:17]
	v_fmac_f32_e32 v18, v170, v22
	v_max_f32_e32 v24, 0, v24
	v_fmac_f32_e32 v18, v169, v23
	v_max_f32_e32 v25, 0, v25
	v_fmac_f32_e32 v18, v168, v24
	v_max_f32_e32 v26, 0, v26
	v_fmac_f32_e32 v18, v167, v25
	v_max_f32_e32 v27, 0, v27
	v_fmac_f32_e32 v18, v166, v26
	v_max_f32_e32 v28, 0, v28
	v_mfma_f32_32x32x16_bf16 v[2:17], v[34:37], v[50:53], v[2:17]
	v_fmac_f32_e32 v18, v165, v27
	v_max_f32_e32 v29, 0, v29
	v_fmac_f32_e32 v18, v164, v28
	v_max_f32_e32 v30, 0, v30
	v_fmac_f32_e32 v18, v163, v29
	v_fmac_f32_e32 v18, v162, v30
	v_max_f32_e32 v19, 0, v31
	v_fmac_f32_e32 v18, v161, v19
	v_max_f32_e32 v19, 0, v32
	v_fmac_f32_e32 v18, v160, v19
	v_mfma_f32_32x32x16_bf16 v[2:17], v[42:45], v[62:65], v[2:17]
	ds_read_b128 v[58:61], v74 offset:20480
	ds_read_b128 v[54:57], v75 offset:20480
	ds_read_b128 v[50:53], v76 offset:20480
	ds_read_b128 v[62:65], v77 offset:20480
	v_max_f32_e32 v19, 0, v33
	v_fmac_f32_e32 v18, v89, v19
	v_not_b32_e32 v19, v18
	v_or_b32_e32 v20, 0x80000000, v18
	v_cmp_gt_i32_e32 vcc, 0, v18
	s_nop 1
	v_cndmask_b32_e32 v18, v20, v19, vcc
	v_cmp_le_u32_e32 vcc, v132, v87
	s_nop 1
	v_cndmask_b32_e32 v231, 0, v18, vcc
.LBB0_553:
	v_mov_b32_e32 v233, 0
	s_cmp_gt_u32 s2, 0x4df
	s_cbranch_scc0 .Lidxp_e39
	s_waitcnt lgkmcnt(0)
	v_mfma_f32_32x32x16_bf16 v[18:33], v[38:41], v[58:61], 0
	v_max_f32_e32 v2, 0, v2
	v_max_f32_e32 v3, 0, v3
	v_fma_f32 v2, v174, v2, 0
	v_max_f32_e32 v4, 0, v4
	v_fmac_f32_e32 v2, v173, v3
	v_max_f32_e32 v5, 0, v5
	v_fmac_f32_e32 v2, v172, v4
	v_max_f32_e32 v6, 0, v6
	v_fmac_f32_e32 v2, v171, v5
	v_max_f32_e32 v7, 0, v7
	v_mfma_f32_32x32x16_bf16 v[18:33], v[46:49], v[54:57], v[18:33]
	v_fmac_f32_e32 v2, v170, v6
	v_max_f32_e32 v8, 0, v8
	v_fmac_f32_e32 v2, v169, v7
	v_max_f32_e32 v9, 0, v9
	v_fmac_f32_e32 v2, v168, v8
	v_max_f32_e32 v10, 0, v10
	v_fmac_f32_e32 v2, v167, v9
	v_max_f32_e32 v11, 0, v11
	v_fmac_f32_e32 v2, v166, v10
	v_max_f32_e32 v12, 0, v12
	v_mfma_f32_32x32x16_bf16 v[18:33], v[34:37], v[50:53], v[18:33]
	v_fmac_f32_e32 v2, v165, v11
	v_max_f32_e32 v13, 0, v13
	v_fmac_f32_e32 v2, v164, v12
	v_max_f32_e32 v14, 0, v14
	v_fmac_f32_e32 v2, v163, v13
	v_fmac_f32_e32 v2, v162, v14
	v_max_f32_e32 v3, 0, v15
	v_fmac_f32_e32 v2, v161, v3
	v_max_f32_e32 v3, 0, v16
	v_fmac_f32_e32 v2, v160, v3
	v_mfma_f32_32x32x16_bf16 v[18:33], v[42:45], v[62:65], v[18:33]
	ds_read_b128 v[58:61], v74 offset:24576
	ds_read_b128 v[54:57], v75 offset:24576
	ds_read_b128 v[50:53], v76 offset:24576
	ds_read_b128 v[62:65], v77 offset:24576
	v_max_f32_e32 v3, 0, v17
	v_fmac_f32_e32 v2, v89, v3
	v_not_b32_e32 v3, v2
	v_or_b32_e32 v4, 0x80000000, v2
	v_cmp_gt_i32_e32 vcc, 0, v2
	s_nop 1
	v_cndmask_b32_e32 v2, v4, v3, vcc
	v_cmp_le_u32_e32 vcc, v133, v87
	s_nop 1
	v_cndmask_b32_e32 v232, 0, v2, vcc
.LBB0_557:
	v_mov_b32_e32 v234, 0
	s_cmp_gt_u32 s2, 0x4ff
	s_cbranch_scc0 .Lidxp_e40
	s_waitcnt lgkmcnt(0)
	v_mfma_f32_32x32x16_bf16 v[2:17], v[38:41], v[58:61], 0
	v_max_f32_e32 v18, 0, v18
	v_max_f32_e32 v19, 0, v19
	v_fma_f32 v18, v174, v18, 0
	v_max_f32_e32 v20, 0, v20
	v_fmac_f32_e32 v18, v173, v19
	v_max_f32_e32 v21, 0, v21
	v_fmac_f32_e32 v18, v172, v20
	v_max_f32_e32 v22, 0, v22
	v_fmac_f32_e32 v18, v171, v21
	v_max_f32_e32 v23, 0, v23
	v_mfma_f32_32x32x16_bf16 v[2:17], v[46:49], v[54:57], v[2:17]
	v_fmac_f32_e32 v18, v170, v22
	v_max_f32_e32 v24, 0, v24
	v_fmac_f32_e32 v18, v169, v23
	v_max_f32_e32 v25, 0, v25
	v_fmac_f32_e32 v18, v168, v24
	v_max_f32_e32 v26, 0, v26
	v_fmac_f32_e32 v18, v167, v25
	v_max_f32_e32 v27, 0, v27
	v_fmac_f32_e32 v18, v166, v26
	v_max_f32_e32 v28, 0, v28
	v_mfma_f32_32x32x16_bf16 v[2:17], v[34:37], v[50:53], v[2:17]
	v_fmac_f32_e32 v18, v165, v27
	v_max_f32_e32 v29, 0, v29
	v_fmac_f32_e32 v18, v164, v28
	v_max_f32_e32 v30, 0, v30
	v_fmac_f32_e32 v18, v163, v29
	v_fmac_f32_e32 v18, v162, v30
	v_max_f32_e32 v19, 0, v31
	v_fmac_f32_e32 v18, v161, v19
	v_max_f32_e32 v19, 0, v32
	v_fmac_f32_e32 v18, v160, v19
	v_mfma_f32_32x32x16_bf16 v[2:17], v[42:45], v[62:65], v[2:17]
	ds_read_b128 v[58:61], v74 offset:28672
	ds_read_b128 v[54:57], v75 offset:28672
	ds_read_b128 v[50:53], v76 offset:28672
	ds_read_b128 v[62:65], v77 offset:28672
	v_max_f32_e32 v19, 0, v33
	v_fmac_f32_e32 v18, v89, v19
	v_not_b32_e32 v19, v18
	v_or_b32_e32 v20, 0x80000000, v18
	v_cmp_gt_i32_e32 vcc, 0, v18
	s_nop 1
	v_cndmask_b32_e32 v18, v20, v19, vcc
	v_cmp_le_u32_e32 vcc, v134, v87
	s_nop 1
	v_cndmask_b32_e32 v233, 0, v18, vcc
.LBB0_561:
	v_mov_b32_e32 v235, 0
	s_cmp_gt_u32 s2, 0x51f
	s_cbranch_scc0 .Lidxp_e41
	s_waitcnt lgkmcnt(0)
	s_waitcnt vmcnt(0)
	s_barrier
	v_cmp_le_u32_e32 vcc, v79, v80
	s_and_b64 vcc, exec, vcc
	s_cbranch_vccz .Lidxd_s5
	s_nop 0
	global_load_lds_dwordx4 v72, s[100:101]
	s_add_u32 m0, m0, 0x400
	s_add_u32 s100, s100, 0x1a000
	s_addc_u32 s101, s101, 0
	s_nop 0
	global_load_lds_dwordx4 v73, s[100:101]
	s_add_u32 m0, m0, 0x400
	s_add_u32 s100, s100, 0x1a000
	s_addc_u32 s101, s101, 0
	s_nop 0
	global_load_lds_dwordx4 v72, s[100:101]
	s_add_u32 m0, m0, 0x400
	s_add_u32 s100, s100, 0x1a000
	s_addc_u32 s101, s101, 0
	s_nop 0
	global_load_lds_dwordx4 v73, s[100:101]
	s_add_u32 m0, m0, 0x400
	s_add_u32 s100, s100, 0x1a000
	s_addc_u32 s101, s101, 0
	s_add_u32 m0, m0, 0x7000
	s_add_u32 s100, s100, 0x2d8000
	s_addc_u32 s101, s101, 0
	v_add_u32_e32 v79, 8, v79

.LBB0_565:
	v_mov_b32_e32 v236, 0
	s_cmp_gt_u32 s2, 0x53f
	s_cbranch_scc0 .Lidxp_e42
	s_waitcnt lgkmcnt(0)
	v_mfma_f32_32x32x16_bf16 v[2:17], v[38:41], v[58:61], 0
	v_max_f32_e32 v18, 0, v18
	v_max_f32_e32 v19, 0, v19
	v_fma_f32 v18, v174, v18, 0
	v_max_f32_e32 v20, 0, v20
	v_fmac_f32_e32 v18, v173, v19
	v_max_f32_e32 v21, 0, v21
	v_fmac_f32_e32 v18, v172, v20
	v_max_f32_e32 v22, 0, v22
	v_fmac_f32_e32 v18, v171, v21
	v_max_f32_e32 v23, 0, v23
	v_mfma_f32_32x32x16_bf16 v[2:17], v[46:49], v[54:57], v[2:17]
	v_fmac_f32_e32 v18, v170, v22
	v_max_f32_e32 v24, 0, v24
	v_fmac_f32_e32 v18, v169, v23
	v_max_f32_e32 v25, 0, v25
	v_fmac_f32_e32 v18, v168, v24
	v_max_f32_e32 v26, 0, v26
	v_fmac_f32_e32 v18, v167, v25
	v_max_f32_e32 v27, 0, v27
	v_fmac_f32_e32 v18, v166, v26
	v_max_f32_e32 v28, 0, v28
	v_mfma_f32_32x32x16_bf16 v[2:17], v[34:37], v[50:53], v[2:17]
	v_fmac_f32_e32 v18, v165, v27
	v_max_f32_e32 v29, 0, v29
	v_fmac_f32_e32 v18, v164, v28
	v_max_f32_e32 v30, 0, v30
	v_fmac_f32_e32 v18, v163, v29
	v_fmac_f32_e32 v18, v162, v30
	v_max_f32_e32 v19, 0, v31
	v_fmac_f32_e32 v18, v161, v19
	v_max_f32_e32 v19, 0, v32
	v_fmac_f32_e32 v18, v160, v19
	v_mfma_f32_32x32x16_bf16 v[2:17], v[42:45], v[62:65], v[2:17]
	ds_read_b128 v[58:61], v74 offset:36864
	ds_read_b128 v[54:57], v75 offset:36864
	ds_read_b128 v[50:53], v76 offset:36864
	ds_read_b128 v[62:65], v77 offset:36864
	v_max_f32_e32 v19, 0, v33
	v_fmac_f32_e32 v18, v89, v19
	v_not_b32_e32 v19, v18
	v_or_b32_e32 v20, 0x80000000, v18
	v_cmp_gt_i32_e32 vcc, 0, v18
	s_nop 1
	v_cndmask_b32_e32 v18, v20, v19, vcc
	v_cmp_le_u32_e32 vcc, v136, v87
	s_nop 1
	v_cndmask_b32_e32 v235, 0, v18, vcc
.LBB0_569:
	v_mov_b32_e32 v237, 0
	s_cmp_gt_u32 s2, 0x55f
	s_cbranch_scc0 .Lidxp_e43
	s_waitcnt lgkmcnt(0)
	v_mfma_f32_32x32x16_bf16 v[18:33], v[38:41], v[58:61], 0
	v_max_f32_e32 v2, 0, v2
	v_max_f32_e32 v3, 0, v3
	v_fma_f32 v2, v174, v2, 0
	v_max_f32_e32 v4, 0, v4
	v_fmac_f32_e32 v2, v173, v3
	v_max_f32_e32 v5, 0, v5
	v_fmac_f32_e32 v2, v172, v4
	v_max_f32_e32 v6, 0, v6
	v_fmac_f32_e32 v2, v171, v5
	v_max_f32_e32 v7, 0, v7
	v_mfma_f32_32x32x16_bf16 v[18:33], v[46:49], v[54:57], v[18:33]
	v_fmac_f32_e32 v2, v170, v6
	v_max_f32_e32 v8, 0, v8
	v_fmac_f32_e32 v2, v169, v7
	v_max_f32_e32 v9, 0, v9
	v_fmac_f32_e32 v2, v168, v8
	v_max_f32_e32 v10, 0, v10
	v_fmac_f32_e32 v2, v167, v9
	v_max_f32_e32 v11, 0, v11
	v_fmac_f32_e32 v2, v166, v10
	v_max_f32_e32 v12, 0, v12
	v_mfma_f32_32x32x16_bf16 v[18:33], v[34:37], v[50:53], v[18:33]
	v_fmac_f32_e32 v2, v165, v11
	v_max_f32_e32 v13, 0, v13
	v_fmac_f32_e32 v2, v164, v12
	v_max_f32_e32 v14, 0, v14
	v_fmac_f32_e32 v2, v163, v13
	v_fmac_f32_e32 v2, v162, v14
	v_max_f32_e32 v3, 0, v15
	v_fmac_f32_e32 v2, v161, v3
	v_max_f32_e32 v3, 0, v16
	v_fmac_f32_e32 v2, v160, v3
	v_mfma_f32_32x32x16_bf16 v[18:33], v[42:45], v[62:65], v[18:33]
	ds_read_b128 v[58:61], v74 offset:40960
	ds_read_b128 v[54:57], v75 offset:40960
	ds_read_b128 v[50:53], v76 offset:40960
	ds_read_b128 v[62:65], v77 offset:40960
	v_max_f32_e32 v3, 0, v17
	v_fmac_f32_e32 v2, v89, v3
	v_not_b32_e32 v3, v2
	v_or_b32_e32 v4, 0x80000000, v2
	v_cmp_gt_i32_e32 vcc, 0, v2
	s_nop 1
	v_cndmask_b32_e32 v2, v4, v3, vcc
	v_cmp_le_u32_e32 vcc, v137, v87
	s_nop 1
	v_cndmask_b32_e32 v236, 0, v2, vcc
.LBB0_573:
	v_mov_b32_e32 v238, 0
	s_cmp_gt_u32 s2, 0x57f
	s_cbranch_scc0 .Lidxp_e44
	s_waitcnt lgkmcnt(0)
	v_mfma_f32_32x32x16_bf16 v[2:17], v[38:41], v[58:61], 0
	v_max_f32_e32 v18, 0, v18
	v_max_f32_e32 v19, 0, v19
	v_fma_f32 v18, v174, v18, 0
	v_max_f32_e32 v20, 0, v20
	v_fmac_f32_e32 v18, v173, v19
	v_max_f32_e32 v21, 0, v21
	v_fmac_f32_e32 v18, v172, v20
	v_max_f32_e32 v22, 0, v22
	v_fmac_f32_e32 v18, v171, v21
	v_max_f32_e32 v23, 0, v23
	v_mfma_f32_32x32x16_bf16 v[2:17], v[46:49], v[54:57], v[2:17]
	v_fmac_f32_e32 v18, v170, v22
	v_max_f32_e32 v24, 0, v24
	v_fmac_f32_e32 v18, v169, v23
	v_max_f32_e32 v25, 0, v25
	v_fmac_f32_e32 v18, v168, v24
	v_max_f32_e32 v26, 0, v26
	v_fmac_f32_e32 v18, v167, v25
	v_max_f32_e32 v27, 0, v27
	v_fmac_f32_e32 v18, v166, v26
	v_max_f32_e32 v28, 0, v28
	v_mfma_f32_32x32x16_bf16 v[2:17], v[34:37], v[50:53], v[2:17]
	v_fmac_f32_e32 v18, v165, v27
	v_max_f32_e32 v29, 0, v29
	v_fmac_f32_e32 v18, v164, v28
	v_max_f32_e32 v30, 0, v30
	v_fmac_f32_e32 v18, v163, v29
	v_fmac_f32_e32 v18, v162, v30
	v_max_f32_e32 v19, 0, v31
	v_fmac_f32_e32 v18, v161, v19
	v_max_f32_e32 v19, 0, v32
	v_fmac_f32_e32 v18, v160, v19
	v_mfma_f32_32x32x16_bf16 v[2:17], v[42:45], v[62:65], v[2:17]
	ds_read_b128 v[58:61], v74 offset:45056
	ds_read_b128 v[54:57], v75 offset:45056
	ds_read_b128 v[50:53], v76 offset:45056
	ds_read_b128 v[62:65], v77 offset:45056
	v_max_f32_e32 v19, 0, v33
	v_fmac_f32_e32 v18, v89, v19
	v_not_b32_e32 v19, v18
	v_or_b32_e32 v20, 0x80000000, v18
	v_cmp_gt_i32_e32 vcc, 0, v18
	s_nop 1
	v_cndmask_b32_e32 v18, v20, v19, vcc
	v_cmp_le_u32_e32 vcc, v138, v87
	s_nop 1
	v_cndmask_b32_e32 v237, 0, v18, vcc
.LBB0_577:
	v_mov_b32_e32 v239, 0
	s_cmp_gt_u32 s2, 0x59f
	s_cbranch_scc0 .Lidxp_e45
	s_waitcnt lgkmcnt(0)
	v_mfma_f32_32x32x16_bf16 v[18:33], v[38:41], v[58:61], 0
	v_max_f32_e32 v2, 0, v2
	v_max_f32_e32 v3, 0, v3
	v_fma_f32 v2, v174, v2, 0
	v_max_f32_e32 v4, 0, v4
	v_fmac_f32_e32 v2, v173, v3
	v_max_f32_e32 v5, 0, v5
	v_fmac_f32_e32 v2, v172, v4
	v_max_f32_e32 v6, 0, v6
	v_fmac_f32_e32 v2, v171, v5
	v_max_f32_e32 v7, 0, v7
	v_mfma_f32_32x32x16_bf16 v[18:33], v[46:49], v[54:57], v[18:33]
	v_fmac_f32_e32 v2, v170, v6
	v_max_f32_e32 v8, 0, v8
	v_fmac_f32_e32 v2, v169, v7
	v_max_f32_e32 v9, 0, v9
	v_fmac_f32_e32 v2, v168, v8
	v_max_f32_e32 v10, 0, v10
	v_fmac_f32_e32 v2, v167, v9
	v_max_f32_e32 v11, 0, v11
	v_fmac_f32_e32 v2, v166, v10
	v_max_f32_e32 v12, 0, v12
	v_mfma_f32_32x32x16_bf16 v[18:33], v[34:37], v[50:53], v[18:33]
	v_fmac_f32_e32 v2, v165, v11
	v_max_f32_e32 v13, 0, v13
	v_fmac_f32_e32 v2, v164, v12
	v_max_f32_e32 v14, 0, v14
	v_fmac_f32_e32 v2, v163, v13
	v_fmac_f32_e32 v2, v162, v14
	v_max_f32_e32 v3, 0, v15
	v_fmac_f32_e32 v2, v161, v3
	v_max_f32_e32 v3, 0, v16
	v_fmac_f32_e32 v2, v160, v3
	v_mfma_f32_32x32x16_bf16 v[18:33], v[42:45], v[62:65], v[18:33]
	ds_read_b128 v[58:61], v74 offset:49152
	ds_read_b128 v[54:57], v75 offset:49152
	ds_read_b128 v[50:53], v76 offset:49152
	ds_read_b128 v[62:65], v77 offset:49152
	v_max_f32_e32 v3, 0, v17
	v_fmac_f32_e32 v2, v89, v3
	v_not_b32_e32 v3, v2
	v_or_b32_e32 v4, 0x80000000, v2
	v_cmp_gt_i32_e32 vcc, 0, v2
	s_nop 1
	v_cndmask_b32_e32 v2, v4, v3, vcc
	v_cmp_le_u32_e32 vcc, v139, v87
	s_nop 1
	v_cndmask_b32_e32 v238, 0, v2, vcc
.LBB0_581:
	v_mov_b32_e32 v240, 0
	s_cmp_gt_u32 s2, 0x5bf
	s_cbranch_scc0 .Lidxp_e46
	s_waitcnt lgkmcnt(0)
	v_mfma_f32_32x32x16_bf16 v[2:17], v[38:41], v[58:61], 0
	v_max_f32_e32 v18, 0, v18
	v_max_f32_e32 v19, 0, v19
	v_fma_f32 v18, v174, v18, 0
	v_max_f32_e32 v20, 0, v20
	v_fmac_f32_e32 v18, v173, v19
	v_max_f32_e32 v21, 0, v21
	v_fmac_f32_e32 v18, v172, v20
	v_max_f32_e32 v22, 0, v22
	v_fmac_f32_e32 v18, v171, v21
	v_max_f32_e32 v23, 0, v23
	v_mfma_f32_32x32x16_bf16 v[2:17], v[46:49], v[54:57], v[2:17]
	v_fmac_f32_e32 v18, v170, v22
	v_max_f32_e32 v24, 0, v24
	v_fmac_f32_e32 v18, v169, v23
	v_max_f32_e32 v25, 0, v25
	v_fmac_f32_e32 v18, v168, v24
	v_max_f32_e32 v26, 0, v26
	v_fmac_f32_e32 v18, v167, v25
	v_max_f32_e32 v27, 0, v27
	v_fmac_f32_e32 v18, v166, v26
	v_max_f32_e32 v28, 0, v28
	v_mfma_f32_32x32x16_bf16 v[2:17], v[34:37], v[50:53], v[2:17]
	v_fmac_f32_e32 v18, v165, v27
	v_max_f32_e32 v29, 0, v29
	v_fmac_f32_e32 v18, v164, v28
	v_max_f32_e32 v30, 0, v30
	v_fmac_f32_e32 v18, v163, v29
	v_fmac_f32_e32 v18, v162, v30
	v_max_f32_e32 v19, 0, v31
	v_fmac_f32_e32 v18, v161, v19
	v_max_f32_e32 v19, 0, v32
	v_fmac_f32_e32 v18, v160, v19
	v_mfma_f32_32x32x16_bf16 v[2:17], v[42:45], v[62:65], v[2:17]
	ds_read_b128 v[58:61], v74 offset:53248
	ds_read_b128 v[54:57], v75 offset:53248
	ds_read_b128 v[50:53], v76 offset:53248
	ds_read_b128 v[62:65], v77 offset:53248
	v_max_f32_e32 v19, 0, v33
	v_fmac_f32_e32 v18, v89, v19
	v_not_b32_e32 v19, v18
	v_or_b32_e32 v20, 0x80000000, v18
	v_cmp_gt_i32_e32 vcc, 0, v18
	s_nop 1
	v_cndmask_b32_e32 v18, v20, v19, vcc
	v_cmp_le_u32_e32 vcc, v140, v87
	s_nop 1
	v_cndmask_b32_e32 v239, 0, v18, vcc
.LBB0_585:
	v_mov_b32_e32 v241, 0
	s_cmp_gt_u32 s2, 0x5df
	s_cbranch_scc0 .Lidxp_e47
	s_waitcnt lgkmcnt(0)
	v_mfma_f32_32x32x16_bf16 v[18:33], v[38:41], v[58:61], 0
	v_max_f32_e32 v2, 0, v2
	v_max_f32_e32 v3, 0, v3
	v_fma_f32 v2, v174, v2, 0
	v_max_f32_e32 v4, 0, v4
	v_fmac_f32_e32 v2, v173, v3
	v_max_f32_e32 v5, 0, v5
	v_fmac_f32_e32 v2, v172, v4
	v_max_f32_e32 v6, 0, v6
	v_fmac_f32_e32 v2, v171, v5
	v_max_f32_e32 v7, 0, v7
	v_mfma_f32_32x32x16_bf16 v[18:33], v[46:49], v[54:57], v[18:33]
	v_fmac_f32_e32 v2, v170, v6
	v_max_f32_e32 v8, 0, v8
	v_fmac_f32_e32 v2, v169, v7
	v_max_f32_e32 v9, 0, v9
	v_fmac_f32_e32 v2, v168, v8
	v_max_f32_e32 v10, 0, v10
	v_fmac_f32_e32 v2, v167, v9
	v_max_f32_e32 v11, 0, v11
	v_fmac_f32_e32 v2, v166, v10
	v_max_f32_e32 v12, 0, v12
	v_mfma_f32_32x32x16_bf16 v[18:33], v[34:37], v[50:53], v[18:33]
	v_fmac_f32_e32 v2, v165, v11
	v_max_f32_e32 v13, 0, v13
	v_fmac_f32_e32 v2, v164, v12
	v_max_f32_e32 v14, 0, v14
	v_fmac_f32_e32 v2, v163, v13
	v_fmac_f32_e32 v2, v162, v14
	v_max_f32_e32 v3, 0, v15
	v_fmac_f32_e32 v2, v161, v3
	v_max_f32_e32 v3, 0, v16
	v_fmac_f32_e32 v2, v160, v3
	v_mfma_f32_32x32x16_bf16 v[18:33], v[42:45], v[62:65], v[18:33]
	ds_read_b128 v[58:61], v74 offset:57344
	ds_read_b128 v[54:57], v75 offset:57344
	ds_read_b128 v[50:53], v76 offset:57344
	ds_read_b128 v[62:65], v77 offset:57344
	v_max_f32_e32 v3, 0, v17
	v_fmac_f32_e32 v2, v89, v3
	v_not_b32_e32 v3, v2
	v_or_b32_e32 v4, 0x80000000, v2
	v_cmp_gt_i32_e32 vcc, 0, v2
	s_nop 1
	v_cndmask_b32_e32 v2, v4, v3, vcc
	v_cmp_le_u32_e32 vcc, v141, v87
	s_nop 1
	v_cndmask_b32_e32 v240, 0, v2, vcc
.LBB0_589:
	v_mov_b32_e32 v242, 0
	s_cmp_gt_u32 s2, 0x5ff
	s_cbranch_scc0 .Lidxp_e48
	s_waitcnt lgkmcnt(0)
	v_mfma_f32_32x32x16_bf16 v[2:17], v[38:41], v[58:61], 0
	v_max_f32_e32 v18, 0, v18
	v_max_f32_e32 v19, 0, v19
	v_fma_f32 v18, v174, v18, 0
	v_max_f32_e32 v20, 0, v20
	v_fmac_f32_e32 v18, v173, v19
	v_max_f32_e32 v21, 0, v21
	v_fmac_f32_e32 v18, v172, v20
	v_max_f32_e32 v22, 0, v22
	v_fmac_f32_e32 v18, v171, v21
	v_max_f32_e32 v23, 0, v23
	v_mfma_f32_32x32x16_bf16 v[2:17], v[46:49], v[54:57], v[2:17]
	v_fmac_f32_e32 v18, v170, v22
	v_max_f32_e32 v24, 0, v24
	v_fmac_f32_e32 v18, v169, v23
	v_max_f32_e32 v25, 0, v25
	v_fmac_f32_e32 v18, v168, v24
	v_max_f32_e32 v26, 0, v26
	v_fmac_f32_e32 v18, v167, v25
	v_max_f32_e32 v27, 0, v27
	v_fmac_f32_e32 v18, v166, v26
	v_max_f32_e32 v28, 0, v28
	v_mfma_f32_32x32x16_bf16 v[2:17], v[34:37], v[50:53], v[2:17]
	v_fmac_f32_e32 v18, v165, v27
	v_max_f32_e32 v29, 0, v29
	v_fmac_f32_e32 v18, v164, v28
	v_max_f32_e32 v30, 0, v30
	v_fmac_f32_e32 v18, v163, v29
	v_fmac_f32_e32 v18, v162, v30
	v_max_f32_e32 v19, 0, v31
	v_fmac_f32_e32 v18, v161, v19
	v_max_f32_e32 v19, 0, v32
	v_fmac_f32_e32 v18, v160, v19
	v_mfma_f32_32x32x16_bf16 v[2:17], v[42:45], v[62:65], v[2:17]
	ds_read_b128 v[58:61], v74 offset:61440
	ds_read_b128 v[54:57], v75 offset:61440
	ds_read_b128 v[50:53], v76 offset:61440
	ds_read_b128 v[62:65], v77 offset:61440
	v_max_f32_e32 v19, 0, v33
	v_fmac_f32_e32 v18, v89, v19
	v_not_b32_e32 v19, v18
	v_or_b32_e32 v20, 0x80000000, v18
	v_cmp_gt_i32_e32 vcc, 0, v18
	s_nop 1
	v_cndmask_b32_e32 v18, v20, v19, vcc
	v_cmp_le_u32_e32 vcc, v142, v87
	s_nop 1
	v_cndmask_b32_e32 v241, 0, v18, vcc
.LBB0_593:
	v_mov_b32_e32 v243, 0
	s_cmp_gt_u32 s2, 0x61f
	s_cbranch_scc0 .Lidxp_e49
	s_waitcnt lgkmcnt(0)
	s_waitcnt vmcnt(0)
	s_barrier
	v_cmp_le_u32_e32 vcc, v79, v80
	s_and_b64 vcc, exec, vcc
	s_cbranch_vccz .Lidxd_s6
	s_nop 0
	global_load_lds_dwordx4 v72, s[100:101]
	s_add_u32 m0, m0, 0x400
	s_add_u32 s100, s100, 0x1a000
	s_addc_u32 s101, s101, 0
	s_nop 0
	global_load_lds_dwordx4 v73, s[100:101]
	s_add_u32 m0, m0, 0x400
	s_add_u32 s100, s100, 0x1a000
	s_addc_u32 s101, s101, 0
	s_nop 0
	global_load_lds_dwordx4 v72, s[100:101]
	s_add_u32 m0, m0, 0x400
	s_add_u32 s100, s100, 0x1a000
	s_addc_u32 s101, s101, 0
	s_nop 0
	global_load_lds_dwordx4 v73, s[100:101]
	s_add_u32 m0, m0, 0x400
	s_add_u32 s100, s100, 0x1a000
	s_addc_u32 s101, s101, 0
	s_sub_u32 m0, m0, 0x9000
	s_add_u32 s100, s100, 0x2d8000
	s_addc_u32 s101, s101, 0
	v_add_u32_e32 v79, 8, v79

.LBB0_597:
	v_mov_b32_e32 v244, 0
	s_cmp_gt_u32 s2, 0x63f
	s_cbranch_scc0 .Lidxp_e50
	s_waitcnt lgkmcnt(0)
	v_mfma_f32_32x32x16_bf16 v[2:17], v[38:41], v[58:61], 0
	v_max_f32_e32 v18, 0, v18
	v_max_f32_e32 v19, 0, v19
	v_fma_f32 v18, v174, v18, 0
	v_max_f32_e32 v20, 0, v20
	v_fmac_f32_e32 v18, v173, v19
	v_max_f32_e32 v21, 0, v21
	v_fmac_f32_e32 v18, v172, v20
	v_max_f32_e32 v22, 0, v22
	v_fmac_f32_e32 v18, v171, v21
	v_max_f32_e32 v23, 0, v23
	v_mfma_f32_32x32x16_bf16 v[2:17], v[46:49], v[54:57], v[2:17]
	v_fmac_f32_e32 v18, v170, v22
	v_max_f32_e32 v24, 0, v24
	v_fmac_f32_e32 v18, v169, v23
	v_max_f32_e32 v25, 0, v25
	v_fmac_f32_e32 v18, v168, v24
	v_max_f32_e32 v26, 0, v26
	v_fmac_f32_e32 v18, v167, v25
	v_max_f32_e32 v27, 0, v27
	v_fmac_f32_e32 v18, v166, v26
	v_max_f32_e32 v28, 0, v28
	v_mfma_f32_32x32x16_bf16 v[2:17], v[34:37], v[50:53], v[2:17]
	v_fmac_f32_e32 v18, v165, v27
	v_max_f32_e32 v29, 0, v29
	v_fmac_f32_e32 v18, v164, v28
	v_max_f32_e32 v30, 0, v30
	v_fmac_f32_e32 v18, v163, v29
	v_fmac_f32_e32 v18, v162, v30
	v_max_f32_e32 v19, 0, v31
	v_fmac_f32_e32 v18, v161, v19
	v_max_f32_e32 v19, 0, v32
	v_fmac_f32_e32 v18, v160, v19
	v_mfma_f32_32x32x16_bf16 v[2:17], v[42:45], v[62:65], v[2:17]
	ds_read_b128 v[58:61], v74 offset:4096
	ds_read_b128 v[54:57], v75 offset:4096
	ds_read_b128 v[50:53], v76 offset:4096
	ds_read_b128 v[62:65], v77 offset:4096
	v_max_f32_e32 v19, 0, v33
	v_fmac_f32_e32 v18, v89, v19
	v_not_b32_e32 v19, v18
	v_or_b32_e32 v20, 0x80000000, v18
	v_cmp_gt_i32_e32 vcc, 0, v18
	s_nop 1
	v_cndmask_b32_e32 v18, v20, v19, vcc
	v_cmp_le_u32_e32 vcc, v144, v87
	s_nop 1
	v_cndmask_b32_e32 v243, 0, v18, vcc
.LBB0_601:
	v_mov_b32_e32 v245, 0
	s_cmp_gt_u32 s2, 0x65f
	s_cbranch_scc0 .Lidxp_e51
	s_waitcnt lgkmcnt(0)
	v_mfma_f32_32x32x16_bf16 v[18:33], v[38:41], v[58:61], 0
	v_max_f32_e32 v2, 0, v2
	v_max_f32_e32 v3, 0, v3
	v_fma_f32 v2, v174, v2, 0
	v_max_f32_e32 v4, 0, v4
	v_fmac_f32_e32 v2, v173, v3
	v_max_f32_e32 v5, 0, v5
	v_fmac_f32_e32 v2, v172, v4
	v_max_f32_e32 v6, 0, v6
	v_fmac_f32_e32 v2, v171, v5
	v_max_f32_e32 v7, 0, v7
	v_mfma_f32_32x32x16_bf16 v[18:33], v[46:49], v[54:57], v[18:33]
	v_fmac_f32_e32 v2, v170, v6
	v_max_f32_e32 v8, 0, v8
	v_fmac_f32_e32 v2, v169, v7
	v_max_f32_e32 v9, 0, v9
	v_fmac_f32_e32 v2, v168, v8
	v_max_f32_e32 v10, 0, v10
	v_fmac_f32_e32 v2, v167, v9
	v_max_f32_e32 v11, 0, v11
	v_fmac_f32_e32 v2, v166, v10
	v_max_f32_e32 v12, 0, v12
	v_mfma_f32_32x32x16_bf16 v[18:33], v[34:37], v[50:53], v[18:33]
	v_fmac_f32_e32 v2, v165, v11
	v_max_f32_e32 v13, 0, v13
	v_fmac_f32_e32 v2, v164, v12
	v_max_f32_e32 v14, 0, v14
	v_fmac_f32_e32 v2, v163, v13
	v_fmac_f32_e32 v2, v162, v14
	v_max_f32_e32 v3, 0, v15
	v_fmac_f32_e32 v2, v161, v3
	v_max_f32_e32 v3, 0, v16
	v_fmac_f32_e32 v2, v160, v3
	v_mfma_f32_32x32x16_bf16 v[18:33], v[42:45], v[62:65], v[18:33]
	ds_read_b128 v[58:61], v74 offset:8192
	ds_read_b128 v[54:57], v75 offset:8192
	ds_read_b128 v[50:53], v76 offset:8192
	ds_read_b128 v[62:65], v77 offset:8192
	v_max_f32_e32 v3, 0, v17
	v_fmac_f32_e32 v2, v89, v3
	v_not_b32_e32 v3, v2
	v_or_b32_e32 v4, 0x80000000, v2
	v_cmp_gt_i32_e32 vcc, 0, v2
	s_nop 1
	v_cndmask_b32_e32 v2, v4, v3, vcc
	v_cmp_le_u32_e32 vcc, v145, v87
	s_nop 1
	v_cndmask_b32_e32 v244, 0, v2, vcc
.LBB0_605:
	v_mov_b32_e32 v246, 0
	s_cmp_gt_u32 s2, 0x67f
	s_cbranch_scc0 .Lidxp_e52
	s_waitcnt lgkmcnt(0)
	v_mfma_f32_32x32x16_bf16 v[2:17], v[38:41], v[58:61], 0
	v_max_f32_e32 v18, 0, v18
	v_max_f32_e32 v19, 0, v19
	v_fma_f32 v18, v174, v18, 0
	v_max_f32_e32 v20, 0, v20
	v_fmac_f32_e32 v18, v173, v19
	v_max_f32_e32 v21, 0, v21
	v_fmac_f32_e32 v18, v172, v20
	v_max_f32_e32 v22, 0, v22
	v_fmac_f32_e32 v18, v171, v21
	v_max_f32_e32 v23, 0, v23
	v_mfma_f32_32x32x16_bf16 v[2:17], v[46:49], v[54:57], v[2:17]
	v_fmac_f32_e32 v18, v170, v22
	v_max_f32_e32 v24, 0, v24
	v_fmac_f32_e32 v18, v169, v23
	v_max_f32_e32 v25, 0, v25
	v_fmac_f32_e32 v18, v168, v24
	v_max_f32_e32 v26, 0, v26
	v_fmac_f32_e32 v18, v167, v25
	v_max_f32_e32 v27, 0, v27
	v_fmac_f32_e32 v18, v166, v26
	v_max_f32_e32 v28, 0, v28
	v_mfma_f32_32x32x16_bf16 v[2:17], v[34:37], v[50:53], v[2:17]
	v_fmac_f32_e32 v18, v165, v27
	v_max_f32_e32 v29, 0, v29
	v_fmac_f32_e32 v18, v164, v28
	v_max_f32_e32 v30, 0, v30
	v_fmac_f32_e32 v18, v163, v29
	v_fmac_f32_e32 v18, v162, v30
	v_max_f32_e32 v19, 0, v31
	v_fmac_f32_e32 v18, v161, v19
	v_max_f32_e32 v19, 0, v32
	v_fmac_f32_e32 v18, v160, v19
	v_mfma_f32_32x32x16_bf16 v[2:17], v[42:45], v[62:65], v[2:17]
	ds_read_b128 v[58:61], v74 offset:12288
	ds_read_b128 v[54:57], v75 offset:12288
	ds_read_b128 v[50:53], v76 offset:12288
	ds_read_b128 v[62:65], v77 offset:12288
	v_max_f32_e32 v19, 0, v33
	v_fmac_f32_e32 v18, v89, v19
	v_not_b32_e32 v19, v18
	v_or_b32_e32 v20, 0x80000000, v18
	v_cmp_gt_i32_e32 vcc, 0, v18
	s_nop 1
	v_cndmask_b32_e32 v18, v20, v19, vcc
	v_cmp_le_u32_e32 vcc, v146, v87
	s_nop 1
	v_cndmask_b32_e32 v245, 0, v18, vcc
.LBB0_609:
	v_mov_b32_e32 v247, 0
	s_cmp_gt_u32 s2, 0x69f
	s_cbranch_scc0 .Lidxp_e53
	s_waitcnt lgkmcnt(0)
	v_mfma_f32_32x32x16_bf16 v[18:33], v[38:41], v[58:61], 0
	v_max_f32_e32 v2, 0, v2
	v_max_f32_e32 v3, 0, v3
	v_fma_f32 v2, v174, v2, 0
	v_max_f32_e32 v4, 0, v4
	v_fmac_f32_e32 v2, v173, v3
	v_max_f32_e32 v5, 0, v5
	v_fmac_f32_e32 v2, v172, v4
	v_max_f32_e32 v6, 0, v6
	v_fmac_f32_e32 v2, v171, v5
	v_max_f32_e32 v7, 0, v7
	v_mfma_f32_32x32x16_bf16 v[18:33], v[46:49], v[54:57], v[18:33]
	v_fmac_f32_e32 v2, v170, v6
	v_max_f32_e32 v8, 0, v8
	v_fmac_f32_e32 v2, v169, v7
	v_max_f32_e32 v9, 0, v9
	v_fmac_f32_e32 v2, v168, v8
	v_max_f32_e32 v10, 0, v10
	v_fmac_f32_e32 v2, v167, v9
	v_max_f32_e32 v11, 0, v11
	v_fmac_f32_e32 v2, v166, v10
	v_max_f32_e32 v12, 0, v12
	v_mfma_f32_32x32x16_bf16 v[18:33], v[34:37], v[50:53], v[18:33]
	v_fmac_f32_e32 v2, v165, v11
	v_max_f32_e32 v13, 0, v13
	v_fmac_f32_e32 v2, v164, v12
	v_max_f32_e32 v14, 0, v14
	v_fmac_f32_e32 v2, v163, v13
	v_fmac_f32_e32 v2, v162, v14
	v_max_f32_e32 v3, 0, v15
	v_fmac_f32_e32 v2, v161, v3
	v_max_f32_e32 v3, 0, v16
	v_fmac_f32_e32 v2, v160, v3
	v_mfma_f32_32x32x16_bf16 v[18:33], v[42:45], v[62:65], v[18:33]
	ds_read_b128 v[58:61], v74 offset:16384
	ds_read_b128 v[54:57], v75 offset:16384
	ds_read_b128 v[50:53], v76 offset:16384
	ds_read_b128 v[62:65], v77 offset:16384
	v_max_f32_e32 v3, 0, v17
	v_fmac_f32_e32 v2, v89, v3
	v_not_b32_e32 v3, v2
	v_or_b32_e32 v4, 0x80000000, v2
	v_cmp_gt_i32_e32 vcc, 0, v2
	s_nop 1
	v_cndmask_b32_e32 v2, v4, v3, vcc
	v_cmp_le_u32_e32 vcc, v147, v87
	s_nop 1
	v_cndmask_b32_e32 v246, 0, v2, vcc
.LBB0_613:
	v_mov_b32_e32 v248, 0
	s_cmp_gt_u32 s2, 0x6bf
	s_cbranch_scc0 .Lidxp_e54
	s_waitcnt lgkmcnt(0)
	v_mfma_f32_32x32x16_bf16 v[2:17], v[38:41], v[58:61], 0
	v_max_f32_e32 v18, 0, v18
	v_max_f32_e32 v19, 0, v19
	v_fma_f32 v18, v174, v18, 0
	v_max_f32_e32 v20, 0, v20
	v_fmac_f32_e32 v18, v173, v19
	v_max_f32_e32 v21, 0, v21
	v_fmac_f32_e32 v18, v172, v20
	v_max_f32_e32 v22, 0, v22
	v_fmac_f32_e32 v18, v171, v21
	v_max_f32_e32 v23, 0, v23
	v_mfma_f32_32x32x16_bf16 v[2:17], v[46:49], v[54:57], v[2:17]
	v_fmac_f32_e32 v18, v170, v22
	v_max_f32_e32 v24, 0, v24
	v_fmac_f32_e32 v18, v169, v23
	v_max_f32_e32 v25, 0, v25
	v_fmac_f32_e32 v18, v168, v24
	v_max_f32_e32 v26, 0, v26
	v_fmac_f32_e32 v18, v167, v25
	v_max_f32_e32 v27, 0, v27
	v_fmac_f32_e32 v18, v166, v26
	v_max_f32_e32 v28, 0, v28
	v_mfma_f32_32x32x16_bf16 v[2:17], v[34:37], v[50:53], v[2:17]
	v_fmac_f32_e32 v18, v165, v27
	v_max_f32_e32 v29, 0, v29
	v_fmac_f32_e32 v18, v164, v28
	v_max_f32_e32 v30, 0, v30
	v_fmac_f32_e32 v18, v163, v29
	v_fmac_f32_e32 v18, v162, v30
	v_max_f32_e32 v19, 0, v31
	v_fmac_f32_e32 v18, v161, v19
	v_max_f32_e32 v19, 0, v32
	v_fmac_f32_e32 v18, v160, v19
	v_mfma_f32_32x32x16_bf16 v[2:17], v[42:45], v[62:65], v[2:17]
	ds_read_b128 v[58:61], v74 offset:20480
	ds_read_b128 v[54:57], v75 offset:20480
	ds_read_b128 v[50:53], v76 offset:20480
	ds_read_b128 v[62:65], v77 offset:20480
	v_max_f32_e32 v19, 0, v33
	v_fmac_f32_e32 v18, v89, v19
	v_not_b32_e32 v19, v18
	v_or_b32_e32 v20, 0x80000000, v18
	v_cmp_gt_i32_e32 vcc, 0, v18
	s_nop 1
	v_cndmask_b32_e32 v18, v20, v19, vcc
	v_cmp_le_u32_e32 vcc, v148, v87
	s_nop 1
	v_cndmask_b32_e32 v247, 0, v18, vcc
.LBB0_617:
	v_mov_b32_e32 v249, 0
	s_cmp_gt_u32 s2, 0x6df
	s_cbranch_scc0 .Lidxp_e55
	s_waitcnt lgkmcnt(0)
	v_mfma_f32_32x32x16_bf16 v[18:33], v[38:41], v[58:61], 0
	v_max_f32_e32 v2, 0, v2
	v_max_f32_e32 v3, 0, v3
	v_fma_f32 v2, v174, v2, 0
	v_max_f32_e32 v4, 0, v4
	v_fmac_f32_e32 v2, v173, v3
	v_max_f32_e32 v5, 0, v5
	v_fmac_f32_e32 v2, v172, v4
	v_max_f32_e32 v6, 0, v6
	v_fmac_f32_e32 v2, v171, v5
	v_max_f32_e32 v7, 0, v7
	v_mfma_f32_32x32x16_bf16 v[18:33], v[46:49], v[54:57], v[18:33]
	v_fmac_f32_e32 v2, v170, v6
	v_max_f32_e32 v8, 0, v8
	v_fmac_f32_e32 v2, v169, v7
	v_max_f32_e32 v9, 0, v9
	v_fmac_f32_e32 v2, v168, v8
	v_max_f32_e32 v10, 0, v10
	v_fmac_f32_e32 v2, v167, v9
	v_max_f32_e32 v11, 0, v11
	v_fmac_f32_e32 v2, v166, v10
	v_max_f32_e32 v12, 0, v12
	v_mfma_f32_32x32x16_bf16 v[18:33], v[34:37], v[50:53], v[18:33]
	v_fmac_f32_e32 v2, v165, v11
	v_max_f32_e32 v13, 0, v13
	v_fmac_f32_e32 v2, v164, v12
	v_max_f32_e32 v14, 0, v14
	v_fmac_f32_e32 v2, v163, v13
	v_fmac_f32_e32 v2, v162, v14
	v_max_f32_e32 v3, 0, v15
	v_fmac_f32_e32 v2, v161, v3
	v_max_f32_e32 v3, 0, v16
	v_fmac_f32_e32 v2, v160, v3
	v_mfma_f32_32x32x16_bf16 v[18:33], v[42:45], v[62:65], v[18:33]
	ds_read_b128 v[58:61], v74 offset:24576
	ds_read_b128 v[54:57], v75 offset:24576
	ds_read_b128 v[50:53], v76 offset:24576
	ds_read_b128 v[62:65], v77 offset:24576
	v_max_f32_e32 v3, 0, v17
	v_fmac_f32_e32 v2, v89, v3
	v_not_b32_e32 v3, v2
	v_or_b32_e32 v4, 0x80000000, v2
	v_cmp_gt_i32_e32 vcc, 0, v2
	s_nop 1
	v_cndmask_b32_e32 v2, v4, v3, vcc
	v_cmp_le_u32_e32 vcc, v149, v87
	s_nop 1
	v_cndmask_b32_e32 v248, 0, v2, vcc
.LBB0_621:
	v_mov_b32_e32 v250, 0
	s_cmp_gt_u32 s2, 0x6ff
	s_cbranch_scc0 .Lidxp_e56
	s_waitcnt lgkmcnt(0)
	v_mfma_f32_32x32x16_bf16 v[2:17], v[38:41], v[58:61], 0
	v_max_f32_e32 v18, 0, v18
	v_max_f32_e32 v19, 0, v19
	v_fma_f32 v18, v174, v18, 0
	v_max_f32_e32 v20, 0, v20
	v_fmac_f32_e32 v18, v173, v19
	v_max_f32_e32 v21, 0, v21
	v_fmac_f32_e32 v18, v172, v20
	v_max_f32_e32 v22, 0, v22
	v_fmac_f32_e32 v18, v171, v21
	v_max_f32_e32 v23, 0, v23
	v_mfma_f32_32x32x16_bf16 v[2:17], v[46:49], v[54:57], v[2:17]
	v_fmac_f32_e32 v18, v170, v22
	v_max_f32_e32 v24, 0, v24
	v_fmac_f32_e32 v18, v169, v23
	v_max_f32_e32 v25, 0, v25
	v_fmac_f32_e32 v18, v168, v24
	v_max_f32_e32 v26, 0, v26
	v_fmac_f32_e32 v18, v167, v25
	v_max_f32_e32 v27, 0, v27
	v_fmac_f32_e32 v18, v166, v26
	v_max_f32_e32 v28, 0, v28
	v_mfma_f32_32x32x16_bf16 v[2:17], v[34:37], v[50:53], v[2:17]
	v_fmac_f32_e32 v18, v165, v27
	v_max_f32_e32 v29, 0, v29
	v_fmac_f32_e32 v18, v164, v28
	v_max_f32_e32 v30, 0, v30
	v_fmac_f32_e32 v18, v163, v29
	v_fmac_f32_e32 v18, v162, v30
	v_max_f32_e32 v19, 0, v31
	v_fmac_f32_e32 v18, v161, v19
	v_max_f32_e32 v19, 0, v32
	v_fmac_f32_e32 v18, v160, v19
	v_mfma_f32_32x32x16_bf16 v[2:17], v[42:45], v[62:65], v[2:17]
	ds_read_b128 v[58:61], v74 offset:28672
	ds_read_b128 v[54:57], v75 offset:28672
	ds_read_b128 v[50:53], v76 offset:28672
	ds_read_b128 v[62:65], v77 offset:28672
	v_max_f32_e32 v19, 0, v33
	v_fmac_f32_e32 v18, v89, v19
	v_not_b32_e32 v19, v18
	v_or_b32_e32 v20, 0x80000000, v18
	v_cmp_gt_i32_e32 vcc, 0, v18
	s_nop 1
	v_cndmask_b32_e32 v18, v20, v19, vcc
	v_cmp_le_u32_e32 vcc, v150, v87
	s_nop 1
	v_cndmask_b32_e32 v249, 0, v18, vcc
.LBB0_625:
	v_mov_b32_e32 v199, 0
	s_cmp_gt_u32 s2, 0x71f
	s_cbranch_scc0 .Lidxp_e57
	s_waitcnt lgkmcnt(0)
	s_waitcnt vmcnt(0)
	s_barrier
	v_mfma_f32_32x32x16_bf16 v[18:33], v[38:41], v[58:61], 0
	v_max_f32_e32 v2, 0, v2
	v_max_f32_e32 v3, 0, v3
	v_fma_f32 v2, v174, v2, 0
	v_max_f32_e32 v4, 0, v4
	v_fmac_f32_e32 v2, v173, v3
	v_max_f32_e32 v5, 0, v5
	v_fmac_f32_e32 v2, v172, v4
	v_max_f32_e32 v6, 0, v6
	v_fmac_f32_e32 v2, v171, v5
	v_max_f32_e32 v7, 0, v7
	v_mfma_f32_32x32x16_bf16 v[18:33], v[46:49], v[54:57], v[18:33]
	v_fmac_f32_e32 v2, v170, v6
	v_max_f32_e32 v8, 0, v8
	v_fmac_f32_e32 v2, v169, v7
	v_max_f32_e32 v9, 0, v9
	v_fmac_f32_e32 v2, v168, v8
	v_max_f32_e32 v10, 0, v10
	v_fmac_f32_e32 v2, v167, v9
	v_max_f32_e32 v11, 0, v11
	v_fmac_f32_e32 v2, v166, v10
	v_max_f32_e32 v12, 0, v12
	v_mfma_f32_32x32x16_bf16 v[18:33], v[34:37], v[50:53], v[18:33]
	v_fmac_f32_e32 v2, v165, v11
	v_max_f32_e32 v13, 0, v13
	v_fmac_f32_e32 v2, v164, v12
	v_max_f32_e32 v14, 0, v14
	v_fmac_f32_e32 v2, v163, v13
	v_fmac_f32_e32 v2, v162, v14
	v_max_f32_e32 v3, 0, v15
	v_fmac_f32_e32 v2, v161, v3
	v_max_f32_e32 v3, 0, v16
	v_fmac_f32_e32 v2, v160, v3
	v_mfma_f32_32x32x16_bf16 v[18:33], v[42:45], v[62:65], v[18:33]
	ds_read_b128 v[58:61], v74 offset:32768
	ds_read_b128 v[54:57], v75 offset:32768
	ds_read_b128 v[50:53], v76 offset:32768
	ds_read_b128 v[62:65], v77 offset:32768
	v_max_f32_e32 v3, 0, v17
	v_fmac_f32_e32 v2, v89, v3
	v_not_b32_e32 v3, v2
	v_or_b32_e32 v4, 0x80000000, v2
	v_cmp_gt_i32_e32 vcc, 0, v2
	s_nop 1
	v_cndmask_b32_e32 v2, v4, v3, vcc
	v_cmp_le_u32_e32 vcc, v151, v87
	s_nop 1
	v_cndmask_b32_e32 v250, 0, v2, vcc
.LBB0_629:
	v_mov_b32_e32 v200, 0
	s_cmp_gt_u32 s2, 0x73f
	s_cbranch_scc0 .Lidxp_e58
	s_waitcnt lgkmcnt(0)
	v_mfma_f32_32x32x16_bf16 v[2:17], v[38:41], v[58:61], 0
	v_max_f32_e32 v18, 0, v18
	v_max_f32_e32 v19, 0, v19
	v_fma_f32 v18, v174, v18, 0
	v_max_f32_e32 v20, 0, v20
	v_fmac_f32_e32 v18, v173, v19
	v_max_f32_e32 v21, 0, v21
	v_fmac_f32_e32 v18, v172, v20
	v_max_f32_e32 v22, 0, v22
	v_fmac_f32_e32 v18, v171, v21
	v_max_f32_e32 v23, 0, v23
	v_mfma_f32_32x32x16_bf16 v[2:17], v[46:49], v[54:57], v[2:17]
	v_fmac_f32_e32 v18, v170, v22
	v_max_f32_e32 v24, 0, v24
	v_fmac_f32_e32 v18, v169, v23
	v_max_f32_e32 v25, 0, v25
	v_fmac_f32_e32 v18, v168, v24
	v_max_f32_e32 v26, 0, v26
	v_fmac_f32_e32 v18, v167, v25
	v_max_f32_e32 v27, 0, v27
	v_fmac_f32_e32 v18, v166, v26
	v_max_f32_e32 v28, 0, v28
	v_mfma_f32_32x32x16_bf16 v[2:17], v[34:37], v[50:53], v[2:17]
	v_fmac_f32_e32 v18, v165, v27
	v_max_f32_e32 v29, 0, v29
	v_fmac_f32_e32 v18, v164, v28
	v_max_f32_e32 v30, 0, v30
	v_fmac_f32_e32 v18, v163, v29
	v_fmac_f32_e32 v18, v162, v30
	v_max_f32_e32 v19, 0, v31
	v_fmac_f32_e32 v18, v161, v19
	v_max_f32_e32 v19, 0, v32
	v_fmac_f32_e32 v18, v160, v19
	v_mfma_f32_32x32x16_bf16 v[2:17], v[42:45], v[62:65], v[2:17]
	ds_read_b128 v[58:61], v74 offset:36864
	ds_read_b128 v[54:57], v75 offset:36864
	ds_read_b128 v[50:53], v76 offset:36864
	ds_read_b128 v[62:65], v77 offset:36864
	v_max_f32_e32 v19, 0, v33
	v_fmac_f32_e32 v18, v89, v19
	v_not_b32_e32 v19, v18
	v_or_b32_e32 v20, 0x80000000, v18
	v_cmp_gt_i32_e32 vcc, 0, v18
	s_nop 1
	v_cndmask_b32_e32 v18, v20, v19, vcc
	v_cmp_le_u32_e32 vcc, v152, v87
	s_nop 1
	v_cndmask_b32_e32 v199, 0, v18, vcc
.LBB0_633:
	v_mov_b32_e32 v207, 0
	s_cmp_gt_u32 s2, 0x75f
	s_cbranch_scc0 .Lidxp_e59
	s_waitcnt lgkmcnt(0)
	v_mfma_f32_32x32x16_bf16 v[18:33], v[38:41], v[58:61], 0
	v_max_f32_e32 v2, 0, v2
	v_max_f32_e32 v3, 0, v3
	v_fma_f32 v2, v174, v2, 0
	v_max_f32_e32 v4, 0, v4
	v_fmac_f32_e32 v2, v173, v3
	v_max_f32_e32 v5, 0, v5
	v_fmac_f32_e32 v2, v172, v4
	v_max_f32_e32 v6, 0, v6
	v_fmac_f32_e32 v2, v171, v5
	v_max_f32_e32 v7, 0, v7
	v_mfma_f32_32x32x16_bf16 v[18:33], v[46:49], v[54:57], v[18:33]
	v_fmac_f32_e32 v2, v170, v6
	v_max_f32_e32 v8, 0, v8
	v_fmac_f32_e32 v2, v169, v7
	v_max_f32_e32 v9, 0, v9
	v_fmac_f32_e32 v2, v168, v8
	v_max_f32_e32 v10, 0, v10
	v_fmac_f32_e32 v2, v167, v9
	v_max_f32_e32 v11, 0, v11
	v_fmac_f32_e32 v2, v166, v10
	v_max_f32_e32 v12, 0, v12
	v_mfma_f32_32x32x16_bf16 v[18:33], v[34:37], v[50:53], v[18:33]
	v_fmac_f32_e32 v2, v165, v11
	v_max_f32_e32 v13, 0, v13
	v_fmac_f32_e32 v2, v164, v12
	v_max_f32_e32 v14, 0, v14
	v_fmac_f32_e32 v2, v163, v13
	v_fmac_f32_e32 v2, v162, v14
	v_max_f32_e32 v3, 0, v15
	v_fmac_f32_e32 v2, v161, v3
	v_max_f32_e32 v3, 0, v16
	v_fmac_f32_e32 v2, v160, v3
	v_mfma_f32_32x32x16_bf16 v[18:33], v[42:45], v[62:65], v[18:33]
	ds_read_b128 v[58:61], v74 offset:40960
	ds_read_b128 v[54:57], v75 offset:40960
	ds_read_b128 v[50:53], v76 offset:40960
	ds_read_b128 v[62:65], v77 offset:40960
	v_max_f32_e32 v3, 0, v17
	v_fmac_f32_e32 v2, v89, v3
	v_not_b32_e32 v3, v2
	v_or_b32_e32 v4, 0x80000000, v2
	v_cmp_gt_i32_e32 vcc, 0, v2
	s_nop 1
	v_cndmask_b32_e32 v2, v4, v3, vcc
	v_cmp_le_u32_e32 vcc, v153, v87
	s_nop 1
	v_cndmask_b32_e32 v200, 0, v2, vcc
.LBB0_637:
	v_mov_b32_e32 v208, 0
	s_cmp_gt_u32 s2, 0x77f
	s_cbranch_scc0 .Lidxp_e60
	s_waitcnt lgkmcnt(0)
	v_mfma_f32_32x32x16_bf16 v[2:17], v[38:41], v[58:61], 0
	v_max_f32_e32 v18, 0, v18
	v_max_f32_e32 v19, 0, v19
	v_fma_f32 v18, v174, v18, 0
	v_max_f32_e32 v20, 0, v20
	v_fmac_f32_e32 v18, v173, v19
	v_max_f32_e32 v21, 0, v21
	v_fmac_f32_e32 v18, v172, v20
	v_max_f32_e32 v22, 0, v22
	v_fmac_f32_e32 v18, v171, v21
	v_max_f32_e32 v23, 0, v23
	v_mfma_f32_32x32x16_bf16 v[2:17], v[46:49], v[54:57], v[2:17]
	v_fmac_f32_e32 v18, v170, v22
	v_max_f32_e32 v24, 0, v24
	v_fmac_f32_e32 v18, v169, v23
	v_max_f32_e32 v25, 0, v25
	v_fmac_f32_e32 v18, v168, v24
	v_max_f32_e32 v26, 0, v26
	v_fmac_f32_e32 v18, v167, v25
	v_max_f32_e32 v27, 0, v27
	v_fmac_f32_e32 v18, v166, v26
	v_max_f32_e32 v28, 0, v28
	v_mfma_f32_32x32x16_bf16 v[2:17], v[34:37], v[50:53], v[2:17]
	v_fmac_f32_e32 v18, v165, v27
	v_max_f32_e32 v29, 0, v29
	v_fmac_f32_e32 v18, v164, v28
	v_max_f32_e32 v30, 0, v30
	v_fmac_f32_e32 v18, v163, v29
	v_fmac_f32_e32 v18, v162, v30
	v_max_f32_e32 v19, 0, v31
	v_fmac_f32_e32 v18, v161, v19
	v_max_f32_e32 v19, 0, v32
	v_fmac_f32_e32 v18, v160, v19
	v_mfma_f32_32x32x16_bf16 v[2:17], v[42:45], v[62:65], v[2:17]
	ds_read_b128 v[58:61], v74 offset:45056
	ds_read_b128 v[54:57], v75 offset:45056
	ds_read_b128 v[50:53], v76 offset:45056
	ds_read_b128 v[62:65], v77 offset:45056
	v_max_f32_e32 v19, 0, v33
	v_fmac_f32_e32 v18, v89, v19
	v_not_b32_e32 v19, v18
	v_or_b32_e32 v20, 0x80000000, v18
	v_cmp_gt_i32_e32 vcc, 0, v18
	s_nop 1
	v_cndmask_b32_e32 v18, v20, v19, vcc
	v_cmp_le_u32_e32 vcc, v154, v87
	s_nop 1
	v_cndmask_b32_e32 v207, 0, v18, vcc
.LBB0_641:
	v_mov_b32_e32 v210, 0
	s_cmp_gt_u32 s2, 0x79f
	s_cbranch_scc0 .Lidxp_e61
	s_waitcnt lgkmcnt(0)
	v_mfma_f32_32x32x16_bf16 v[18:33], v[38:41], v[58:61], 0
	v_max_f32_e32 v2, 0, v2
	v_max_f32_e32 v3, 0, v3
	v_fma_f32 v2, v174, v2, 0
	v_max_f32_e32 v4, 0, v4
	v_fmac_f32_e32 v2, v173, v3
	v_max_f32_e32 v5, 0, v5
	v_fmac_f32_e32 v2, v172, v4
	v_max_f32_e32 v6, 0, v6
	v_fmac_f32_e32 v2, v171, v5
	v_max_f32_e32 v7, 0, v7
	v_mfma_f32_32x32x16_bf16 v[18:33], v[46:49], v[54:57], v[18:33]
	v_fmac_f32_e32 v2, v170, v6
	v_max_f32_e32 v8, 0, v8
	v_fmac_f32_e32 v2, v169, v7
	v_max_f32_e32 v9, 0, v9
	v_fmac_f32_e32 v2, v168, v8
	v_max_f32_e32 v10, 0, v10
	v_fmac_f32_e32 v2, v167, v9
	v_max_f32_e32 v11, 0, v11
	v_fmac_f32_e32 v2, v166, v10
	v_max_f32_e32 v12, 0, v12
	v_mfma_f32_32x32x16_bf16 v[18:33], v[34:37], v[50:53], v[18:33]
	v_fmac_f32_e32 v2, v165, v11
	v_max_f32_e32 v13, 0, v13
	v_fmac_f32_e32 v2, v164, v12
	v_max_f32_e32 v14, 0, v14
	v_fmac_f32_e32 v2, v163, v13
	v_fmac_f32_e32 v2, v162, v14
	v_max_f32_e32 v3, 0, v15
	v_fmac_f32_e32 v2, v161, v3
	v_max_f32_e32 v3, 0, v16
	v_fmac_f32_e32 v2, v160, v3
	v_mfma_f32_32x32x16_bf16 v[18:33], v[42:45], v[62:65], v[18:33]
	ds_read_b128 v[58:61], v74 offset:49152
	ds_read_b128 v[54:57], v75 offset:49152
	ds_read_b128 v[50:53], v76 offset:49152
	ds_read_b128 v[62:65], v77 offset:49152
	v_max_f32_e32 v3, 0, v17
	v_fmac_f32_e32 v2, v89, v3
	v_not_b32_e32 v3, v2
	v_or_b32_e32 v4, 0x80000000, v2
	v_cmp_gt_i32_e32 vcc, 0, v2
	s_nop 1
	v_cndmask_b32_e32 v2, v4, v3, vcc
	v_cmp_le_u32_e32 vcc, v155, v87
	s_nop 1
	v_cndmask_b32_e32 v208, 0, v2, vcc
.LBB0_645:
	v_lshrrev_b32_e32 v201, 5, v177
	v_mov_b32_e32 v70, 0
	s_cmp_gt_u32 s2, 0x7bf
	s_cbranch_scc0 .Lidxp_e62
	s_waitcnt lgkmcnt(0)
	v_mfma_f32_32x32x16_bf16 v[2:17], v[38:41], v[58:61], 0
	v_max_f32_e32 v18, 0, v18
	v_max_f32_e32 v19, 0, v19
	v_fma_f32 v18, v174, v18, 0
	v_max_f32_e32 v20, 0, v20
	v_fmac_f32_e32 v18, v173, v19
	v_max_f32_e32 v21, 0, v21
	v_fmac_f32_e32 v18, v172, v20
	v_max_f32_e32 v22, 0, v22
	v_fmac_f32_e32 v18, v171, v21
	v_max_f32_e32 v23, 0, v23
	v_mfma_f32_32x32x16_bf16 v[2:17], v[46:49], v[54:57], v[2:17]
	v_fmac_f32_e32 v18, v170, v22
	v_max_f32_e32 v24, 0, v24
	v_fmac_f32_e32 v18, v169, v23
	v_max_f32_e32 v25, 0, v25
	v_fmac_f32_e32 v18, v168, v24
	v_max_f32_e32 v26, 0, v26
	v_fmac_f32_e32 v18, v167, v25
	v_max_f32_e32 v27, 0, v27
	v_fmac_f32_e32 v18, v166, v26
	v_max_f32_e32 v28, 0, v28
	v_mfma_f32_32x32x16_bf16 v[2:17], v[34:37], v[50:53], v[2:17]
	v_fmac_f32_e32 v18, v165, v27
	v_max_f32_e32 v29, 0, v29
	v_fmac_f32_e32 v18, v164, v28
	v_max_f32_e32 v30, 0, v30
	v_fmac_f32_e32 v18, v163, v29
	v_fmac_f32_e32 v18, v162, v30
	v_max_f32_e32 v19, 0, v31
	v_fmac_f32_e32 v18, v161, v19
	v_max_f32_e32 v19, 0, v32
	v_fmac_f32_e32 v18, v160, v19
	v_mfma_f32_32x32x16_bf16 v[2:17], v[42:45], v[62:65], v[2:17]
	ds_read_b128 v[58:61], v74 offset:53248
	ds_read_b128 v[54:57], v75 offset:53248
	ds_read_b128 v[50:53], v76 offset:53248
	ds_read_b128 v[62:65], v77 offset:53248
	v_max_f32_e32 v19, 0, v33
	v_fmac_f32_e32 v18, v89, v19
	v_not_b32_e32 v19, v18
	v_or_b32_e32 v20, 0x80000000, v18
	v_cmp_gt_i32_e32 vcc, 0, v18
	s_nop 1
	v_cndmask_b32_e32 v18, v20, v19, vcc
	v_cmp_le_u32_e32 vcc, v156, v87
	s_nop 1
	v_cndmask_b32_e32 v210, 0, v18, vcc
.LBB0_649:
	v_mov_b32_e32 v66, 0
	v_mov_b32_e32 v18, 0
	s_cmp_gt_u32 s2, 0x7df
	s_cbranch_scc0 .Lidxp_e63
	s_waitcnt lgkmcnt(0)
	v_mfma_f32_32x32x16_bf16 v[18:33], v[38:41], v[58:61], 0
	v_max_f32_e32 v2, 0, v2
	v_max_f32_e32 v3, 0, v3
	v_fma_f32 v2, v174, v2, 0
	v_max_f32_e32 v4, 0, v4
	v_fmac_f32_e32 v2, v173, v3
	v_max_f32_e32 v5, 0, v5
	v_fmac_f32_e32 v2, v172, v4
	v_max_f32_e32 v6, 0, v6
	v_fmac_f32_e32 v2, v171, v5
	v_max_f32_e32 v7, 0, v7
	v_mfma_f32_32x32x16_bf16 v[18:33], v[46:49], v[54:57], v[18:33]
	v_fmac_f32_e32 v2, v170, v6
	v_max_f32_e32 v8, 0, v8
	v_fmac_f32_e32 v2, v169, v7
	v_max_f32_e32 v9, 0, v9
	v_fmac_f32_e32 v2, v168, v8
	v_max_f32_e32 v10, 0, v10
	v_fmac_f32_e32 v2, v167, v9
	v_max_f32_e32 v11, 0, v11
	v_fmac_f32_e32 v2, v166, v10
	v_max_f32_e32 v12, 0, v12
	v_mfma_f32_32x32x16_bf16 v[18:33], v[34:37], v[50:53], v[18:33]
	v_fmac_f32_e32 v2, v165, v11
	v_max_f32_e32 v13, 0, v13
	v_fmac_f32_e32 v2, v164, v12
	v_max_f32_e32 v14, 0, v14
	v_fmac_f32_e32 v2, v163, v13
	v_fmac_f32_e32 v2, v162, v14
	v_max_f32_e32 v3, 0, v15
	v_fmac_f32_e32 v2, v161, v3
	v_max_f32_e32 v3, 0, v16
	v_fmac_f32_e32 v2, v160, v3
	v_mfma_f32_32x32x16_bf16 v[18:33], v[42:45], v[62:65], v[18:33]
	v_max_f32_e32 v3, 0, v17
	v_fmac_f32_e32 v2, v89, v3
	v_not_b32_e32 v3, v2
	v_or_b32_e32 v4, 0x80000000, v2
	v_cmp_gt_i32_e32 vcc, 0, v2
	s_nop 1
	v_cndmask_b32_e32 v2, v4, v3, vcc
	v_cmp_le_u32_e32 vcc, v157, v87
	s_nop 1
	v_cndmask_b32_e32 v70, 0, v2, vcc
.LBB0_651:
	s_nop 11
	v_max_f32_e32 v18, 0, v18
	v_max_f32_e32 v19, 0, v19
	v_fma_f32 v18, v174, v18, 0
	v_max_f32_e32 v20, 0, v20
	v_fmac_f32_e32 v18, v173, v19
	v_max_f32_e32 v21, 0, v21
	v_fmac_f32_e32 v18, v172, v20
	v_max_f32_e32 v22, 0, v22
	v_fmac_f32_e32 v18, v171, v21
	v_max_f32_e32 v23, 0, v23
	v_fmac_f32_e32 v18, v170, v22
	v_max_f32_e32 v24, 0, v24
	v_fmac_f32_e32 v18, v169, v23
	v_max_f32_e32 v25, 0, v25
	v_fmac_f32_e32 v18, v168, v24
	v_max_f32_e32 v26, 0, v26
	v_fmac_f32_e32 v18, v167, v25
	v_max_f32_e32 v27, 0, v27
	v_fmac_f32_e32 v18, v166, v26
	v_max_f32_e32 v28, 0, v28
	v_fmac_f32_e32 v18, v165, v27
	v_max_f32_e32 v29, 0, v29
	v_fmac_f32_e32 v18, v164, v28
	v_max_f32_e32 v30, 0, v30
	v_fmac_f32_e32 v18, v163, v29
	v_max_f32_e32 v31, 0, v31
	v_fmac_f32_e32 v18, v162, v30
	v_max_f32_e32 v32, 0, v32
	v_fmac_f32_e32 v18, v161, v31
	v_fmac_f32_e32 v18, v160, v32
	v_max_f32_e32 v19, 0, v33
	v_fmac_f32_e32 v18, v89, v19
	v_not_b32_e32 v19, v18
	v_or_b32_e32 v20, 0x80000000, v18
	v_cmp_gt_i32_e32 vcc, 0, v18
	s_nop 1
	v_cndmask_b32_e32 v18, v20, v19, vcc
	v_cmp_le_u32_e32 vcc, v158, v87
	s_nop 1
	v_cndmask_b32_e32 v18, 0, v18, vcc
	s_branch .Lidxp_end
.Lidxp_e1:
	s_nop 11
	v_max_f32_e32 v2, 0, v2
	v_fma_f32 v2, v174, v2, 0
	v_max_f32_e32 v3, 0, v3
	v_fmac_f32_e32 v2, v173, v3
	v_max_f32_e32 v3, 0, v4
	v_fmac_f32_e32 v2, v172, v3
	v_max_f32_e32 v3, 0, v5
	v_fmac_f32_e32 v2, v171, v3
	v_max_f32_e32 v3, 0, v6
	v_fmac_f32_e32 v2, v170, v3
	v_max_f32_e32 v3, 0, v7
	v_fmac_f32_e32 v2, v169, v3
	v_max_f32_e32 v3, 0, v8
	v_fmac_f32_e32 v2, v168, v3
	v_max_f32_e32 v3, 0, v9
	v_fmac_f32_e32 v2, v167, v3
	v_max_f32_e32 v3, 0, v10
	v_fmac_f32_e32 v2, v166, v3
	v_max_f32_e32 v3, 0, v11
	v_fmac_f32_e32 v2, v165, v3
	v_max_f32_e32 v3, 0, v12
	v_fmac_f32_e32 v2, v164, v3
	v_max_f32_e32 v3, 0, v13
	v_fmac_f32_e32 v2, v163, v3
	v_max_f32_e32 v3, 0, v14
	v_fmac_f32_e32 v2, v162, v3
	v_max_f32_e32 v3, 0, v15
	v_fmac_f32_e32 v2, v161, v3
	v_max_f32_e32 v3, 0, v16
	v_fmac_f32_e32 v2, v160, v3
	v_max_f32_e32 v3, 0, v17
	v_fmac_f32_e32 v2, v89, v3
	v_not_b32_e32 v3, v2
	v_or_b32_e32 v4, 0x80000000, v2
	v_cmp_gt_i32_e32 vcc, 0, v2
	s_nop 1
	v_cndmask_b32_e32 v2, v4, v3, vcc
	v_cmp_le_u32_e32 vcc, v93, v87
	s_nop 1
	v_cndmask_b32_e32 v81, 0, v2, vcc
	s_branch .Lidxp_w2
.Lidxp_e2:
	v_max_f32_e32 v18, 0, v18
	v_max_f32_e32 v19, 0, v19
	v_fma_f32 v18, v174, v18, 0
	v_max_f32_e32 v20, 0, v20
	v_fmac_f32_e32 v18, v173, v19
	v_max_f32_e32 v21, 0, v21
	v_fmac_f32_e32 v18, v172, v20
	v_max_f32_e32 v22, 0, v22
	v_fmac_f32_e32 v18, v171, v21
	v_max_f32_e32 v23, 0, v23
	v_fmac_f32_e32 v18, v170, v22
	v_max_f32_e32 v24, 0, v24
	v_fmac_f32_e32 v18, v169, v23
	v_max_f32_e32 v25, 0, v25
	v_fmac_f32_e32 v18, v168, v24
	v_max_f32_e32 v26, 0, v26
	v_fmac_f32_e32 v18, v167, v25
	v_max_f32_e32 v27, 0, v27
	v_fmac_f32_e32 v18, v166, v26
	v_max_f32_e32 v28, 0, v28
	v_fmac_f32_e32 v18, v165, v27
	v_max_f32_e32 v29, 0, v29
	v_fmac_f32_e32 v18, v164, v28
	v_max_f32_e32 v30, 0, v30
	v_fmac_f32_e32 v18, v163, v29
	v_fmac_f32_e32 v18, v162, v30
	v_max_f32_e32 v19, 0, v31
	v_fmac_f32_e32 v18, v161, v19
	v_max_f32_e32 v19, 0, v32
	v_fmac_f32_e32 v18, v160, v19
	v_max_f32_e32 v19, 0, v33
	v_fmac_f32_e32 v18, v89, v19
	v_not_b32_e32 v19, v18
	v_or_b32_e32 v20, 0x80000000, v18
	v_cmp_gt_i32_e32 vcc, 0, v18
	s_nop 1
	v_cndmask_b32_e32 v18, v20, v19, vcc
	v_cmp_le_u32_e32 vcc, v96, v87
	s_nop 1
	v_cndmask_b32_e32 v175, 0, v18, vcc
	s_branch .Lidxp_w3
.Lidxp_e3:
	v_max_f32_e32 v2, 0, v2
	v_max_f32_e32 v3, 0, v3
	v_fma_f32 v2, v174, v2, 0
	v_max_f32_e32 v4, 0, v4
	v_fmac_f32_e32 v2, v173, v3
	v_max_f32_e32 v5, 0, v5
	v_fmac_f32_e32 v2, v172, v4
	v_max_f32_e32 v6, 0, v6
	v_fmac_f32_e32 v2, v171, v5
	v_max_f32_e32 v7, 0, v7
	v_fmac_f32_e32 v2, v170, v6
	v_max_f32_e32 v8, 0, v8
	v_fmac_f32_e32 v2, v169, v7
	v_max_f32_e32 v9, 0, v9
	v_fmac_f32_e32 v2, v168, v8
	v_max_f32_e32 v10, 0, v10
	v_fmac_f32_e32 v2, v167, v9
	v_max_f32_e32 v11, 0, v11
	v_fmac_f32_e32 v2, v166, v10
	v_max_f32_e32 v12, 0, v12
	v_fmac_f32_e32 v2, v165, v11
	v_max_f32_e32 v13, 0, v13
	v_fmac_f32_e32 v2, v164, v12
	v_max_f32_e32 v14, 0, v14
	v_fmac_f32_e32 v2, v163, v13
	v_fmac_f32_e32 v2, v162, v14
	v_max_f32_e32 v3, 0, v15
	v_fmac_f32_e32 v2, v161, v3
	v_max_f32_e32 v3, 0, v16
	v_fmac_f32_e32 v2, v160, v3
	v_max_f32_e32 v3, 0, v17
	v_fmac_f32_e32 v2, v89, v3
	v_not_b32_e32 v3, v2
	v_or_b32_e32 v4, 0x80000000, v2
	v_cmp_gt_i32_e32 vcc, 0, v2
	s_nop 1
	v_cndmask_b32_e32 v2, v4, v3, vcc
	v_cmp_le_u32_e32 vcc, v97, v87
	s_nop 1
	v_cndmask_b32_e32 v176, 0, v2, vcc
	s_branch .Lidxp_w4
.Lidxp_e4:
	v_max_f32_e32 v18, 0, v18
	v_max_f32_e32 v19, 0, v19
	v_fma_f32 v18, v174, v18, 0
	v_max_f32_e32 v20, 0, v20
	v_fmac_f32_e32 v18, v173, v19
	v_max_f32_e32 v21, 0, v21
	v_fmac_f32_e32 v18, v172, v20
	v_max_f32_e32 v22, 0, v22
	v_fmac_f32_e32 v18, v171, v21
	v_max_f32_e32 v23, 0, v23
	v_fmac_f32_e32 v18, v170, v22
	v_max_f32_e32 v24, 0, v24
	v_fmac_f32_e32 v18, v169, v23
	v_max_f32_e32 v25, 0, v25
	v_fmac_f32_e32 v18, v168, v24
	v_max_f32_e32 v26, 0, v26
	v_fmac_f32_e32 v18, v167, v25
	v_max_f32_e32 v27, 0, v27
	v_fmac_f32_e32 v18, v166, v26
	v_max_f32_e32 v28, 0, v28
	v_fmac_f32_e32 v18, v165, v27
	v_max_f32_e32 v29, 0, v29
	v_fmac_f32_e32 v18, v164, v28
	v_max_f32_e32 v30, 0, v30
	v_fmac_f32_e32 v18, v163, v29
	v_fmac_f32_e32 v18, v162, v30
	v_max_f32_e32 v19, 0, v31
	v_fmac_f32_e32 v18, v161, v19
	v_max_f32_e32 v19, 0, v32
	v_fmac_f32_e32 v18, v160, v19
	v_max_f32_e32 v19, 0, v33
	v_fmac_f32_e32 v18, v89, v19
	v_not_b32_e32 v19, v18
	v_or_b32_e32 v20, 0x80000000, v18
	v_cmp_gt_i32_e32 vcc, 0, v18
	s_nop 1
	v_cndmask_b32_e32 v18, v20, v19, vcc
	v_cmp_le_u32_e32 vcc, v98, v87
	s_nop 1
	v_cndmask_b32_e32 v179, 0, v18, vcc
	s_branch .Lidxp_w5
.Lidxp_e5:
	v_max_f32_e32 v2, 0, v2
	v_max_f32_e32 v3, 0, v3
	v_fma_f32 v2, v174, v2, 0
	v_max_f32_e32 v4, 0, v4
	v_fmac_f32_e32 v2, v173, v3
	v_max_f32_e32 v5, 0, v5
	v_fmac_f32_e32 v2, v172, v4
	v_max_f32_e32 v6, 0, v6
	v_fmac_f32_e32 v2, v171, v5
	v_max_f32_e32 v7, 0, v7
	v_fmac_f32_e32 v2, v170, v6
	v_max_f32_e32 v8, 0, v8
	v_fmac_f32_e32 v2, v169, v7
	v_max_f32_e32 v9, 0, v9
	v_fmac_f32_e32 v2, v168, v8
	v_max_f32_e32 v10, 0, v10
	v_fmac_f32_e32 v2, v167, v9
	v_max_f32_e32 v11, 0, v11
	v_fmac_f32_e32 v2, v166, v10
	v_max_f32_e32 v12, 0, v12
	v_fmac_f32_e32 v2, v165, v11
	v_max_f32_e32 v13, 0, v13
	v_fmac_f32_e32 v2, v164, v12
	v_max_f32_e32 v14, 0, v14
	v_fmac_f32_e32 v2, v163, v13
	v_fmac_f32_e32 v2, v162, v14
	v_max_f32_e32 v3, 0, v15
	v_fmac_f32_e32 v2, v161, v3
	v_max_f32_e32 v3, 0, v16
	v_fmac_f32_e32 v2, v160, v3
	v_max_f32_e32 v3, 0, v17
	v_fmac_f32_e32 v2, v89, v3
	v_not_b32_e32 v3, v2
	v_or_b32_e32 v4, 0x80000000, v2
	v_cmp_gt_i32_e32 vcc, 0, v2
	s_nop 1
	v_cndmask_b32_e32 v2, v4, v3, vcc
	v_cmp_le_u32_e32 vcc, v99, v87
	s_nop 1
	v_cndmask_b32_e32 v180, 0, v2, vcc
	s_branch .Lidxp_w6
.Lidxp_e6:
	v_max_f32_e32 v18, 0, v18
	v_max_f32_e32 v19, 0, v19
	v_fma_f32 v18, v174, v18, 0
	v_max_f32_e32 v20, 0, v20
	v_fmac_f32_e32 v18, v173, v19
	v_max_f32_e32 v21, 0, v21
	v_fmac_f32_e32 v18, v172, v20
	v_max_f32_e32 v22, 0, v22
	v_fmac_f32_e32 v18, v171, v21
	v_max_f32_e32 v23, 0, v23
	v_fmac_f32_e32 v18, v170, v22
	v_max_f32_e32 v24, 0, v24
	v_fmac_f32_e32 v18, v169, v23
	v_max_f32_e32 v25, 0, v25
	v_fmac_f32_e32 v18, v168, v24
	v_max_f32_e32 v26, 0, v26
	v_fmac_f32_e32 v18, v167, v25
	v_max_f32_e32 v27, 0, v27
	v_fmac_f32_e32 v18, v166, v26
	v_max_f32_e32 v28, 0, v28
	v_fmac_f32_e32 v18, v165, v27
	v_max_f32_e32 v29, 0, v29
	v_fmac_f32_e32 v18, v164, v28
	v_max_f32_e32 v30, 0, v30
	v_fmac_f32_e32 v18, v163, v29
	v_fmac_f32_e32 v18, v162, v30
	v_max_f32_e32 v19, 0, v31
	v_fmac_f32_e32 v18, v161, v19
	v_max_f32_e32 v19, 0, v32
	v_fmac_f32_e32 v18, v160, v19
	v_max_f32_e32 v19, 0, v33
	v_fmac_f32_e32 v18, v89, v19
	v_not_b32_e32 v19, v18
	v_or_b32_e32 v20, 0x80000000, v18
	v_cmp_gt_i32_e32 vcc, 0, v18
	s_nop 1
	v_cndmask_b32_e32 v18, v20, v19, vcc
	v_cmp_le_u32_e32 vcc, v100, v87
	s_nop 1
	v_cndmask_b32_e32 v181, 0, v18, vcc
	s_branch .Lidxp_w7
.Lidxp_e7:
	v_max_f32_e32 v2, 0, v2
	v_max_f32_e32 v3, 0, v3
	v_fma_f32 v2, v174, v2, 0
	v_max_f32_e32 v4, 0, v4
	v_fmac_f32_e32 v2, v173, v3
	v_max_f32_e32 v5, 0, v5
	v_fmac_f32_e32 v2, v172, v4
	v_max_f32_e32 v6, 0, v6
	v_fmac_f32_e32 v2, v171, v5
	v_max_f32_e32 v7, 0, v7
	v_fmac_f32_e32 v2, v170, v6
	v_max_f32_e32 v8, 0, v8
	v_fmac_f32_e32 v2, v169, v7
	v_max_f32_e32 v9, 0, v9
	v_fmac_f32_e32 v2, v168, v8
	v_max_f32_e32 v10, 0, v10
	v_fmac_f32_e32 v2, v167, v9
	v_max_f32_e32 v11, 0, v11
	v_fmac_f32_e32 v2, v166, v10
	v_max_f32_e32 v12, 0, v12
	v_fmac_f32_e32 v2, v165, v11
	v_max_f32_e32 v13, 0, v13
	v_fmac_f32_e32 v2, v164, v12
	v_max_f32_e32 v14, 0, v14
	v_fmac_f32_e32 v2, v163, v13
	v_fmac_f32_e32 v2, v162, v14
	v_max_f32_e32 v3, 0, v15
	v_fmac_f32_e32 v2, v161, v3
	v_max_f32_e32 v3, 0, v16
	v_fmac_f32_e32 v2, v160, v3
	v_max_f32_e32 v3, 0, v17
	v_fmac_f32_e32 v2, v89, v3
	v_not_b32_e32 v3, v2
	v_or_b32_e32 v4, 0x80000000, v2
	v_cmp_gt_i32_e32 vcc, 0, v2
	s_nop 1
	v_cndmask_b32_e32 v2, v4, v3, vcc
	v_cmp_le_u32_e32 vcc, v101, v87
	s_nop 1
	v_cndmask_b32_e32 v182, 0, v2, vcc
	s_branch .Lidxp_w8
.Lidxp_e8:
	v_max_f32_e32 v18, 0, v18
	v_max_f32_e32 v19, 0, v19
	v_fma_f32 v18, v174, v18, 0
	v_max_f32_e32 v20, 0, v20
	v_fmac_f32_e32 v18, v173, v19
	v_max_f32_e32 v21, 0, v21
	v_fmac_f32_e32 v18, v172, v20
	v_max_f32_e32 v22, 0, v22
	v_fmac_f32_e32 v18, v171, v21
	v_max_f32_e32 v23, 0, v23
	v_fmac_f32_e32 v18, v170, v22
	v_max_f32_e32 v24, 0, v24
	v_fmac_f32_e32 v18, v169, v23
	v_max_f32_e32 v25, 0, v25
	v_fmac_f32_e32 v18, v168, v24
	v_max_f32_e32 v26, 0, v26
	v_fmac_f32_e32 v18, v167, v25
	v_max_f32_e32 v27, 0, v27
	v_fmac_f32_e32 v18, v166, v26
	v_max_f32_e32 v28, 0, v28
	v_fmac_f32_e32 v18, v165, v27
	v_max_f32_e32 v29, 0, v29
	v_fmac_f32_e32 v18, v164, v28
	v_max_f32_e32 v30, 0, v30
	v_fmac_f32_e32 v18, v163, v29
	v_fmac_f32_e32 v18, v162, v30
	v_max_f32_e32 v19, 0, v31
	v_fmac_f32_e32 v18, v161, v19
	v_max_f32_e32 v19, 0, v32
	v_fmac_f32_e32 v18, v160, v19
	v_max_f32_e32 v19, 0, v33
	v_fmac_f32_e32 v18, v89, v19
	v_not_b32_e32 v19, v18
	v_or_b32_e32 v20, 0x80000000, v18
	v_cmp_gt_i32_e32 vcc, 0, v18
	s_nop 1
	v_cndmask_b32_e32 v18, v20, v19, vcc
	v_cmp_le_u32_e32 vcc, v102, v87
	s_nop 1
	v_cndmask_b32_e32 v183, 0, v18, vcc
	s_branch .Lidxp_w9
.Lidxp_e9:
	v_max_f32_e32 v2, 0, v2
	v_max_f32_e32 v3, 0, v3
	v_fma_f32 v2, v174, v2, 0
	v_max_f32_e32 v4, 0, v4
	v_fmac_f32_e32 v2, v173, v3
	v_max_f32_e32 v5, 0, v5
	v_fmac_f32_e32 v2, v172, v4
	v_max_f32_e32 v6, 0, v6
	v_fmac_f32_e32 v2, v171, v5
	v_max_f32_e32 v7, 0, v7
	v_fmac_f32_e32 v2, v170, v6
	v_max_f32_e32 v8, 0, v8
	v_fmac_f32_e32 v2, v169, v7
	v_max_f32_e32 v9, 0, v9
	v_fmac_f32_e32 v2, v168, v8
	v_max_f32_e32 v10, 0, v10
	v_fmac_f32_e32 v2, v167, v9
	v_max_f32_e32 v11, 0, v11
	v_fmac_f32_e32 v2, v166, v10
	v_max_f32_e32 v12, 0, v12
	v_fmac_f32_e32 v2, v165, v11
	v_max_f32_e32 v13, 0, v13
	v_fmac_f32_e32 v2, v164, v12
	v_max_f32_e32 v14, 0, v14
	v_fmac_f32_e32 v2, v163, v13
	v_fmac_f32_e32 v2, v162, v14
	v_max_f32_e32 v3, 0, v15
	v_fmac_f32_e32 v2, v161, v3
	v_max_f32_e32 v3, 0, v16
	v_fmac_f32_e32 v2, v160, v3
	v_max_f32_e32 v3, 0, v17
	v_fmac_f32_e32 v2, v89, v3
	v_not_b32_e32 v3, v2
	v_or_b32_e32 v4, 0x80000000, v2
	v_cmp_gt_i32_e32 vcc, 0, v2
	s_nop 1
	v_cndmask_b32_e32 v2, v4, v3, vcc
	v_cmp_le_u32_e32 vcc, v103, v87
	s_nop 1
	v_cndmask_b32_e32 v184, 0, v2, vcc
	s_branch .Lidxp_w10
.Lidxp_e10:
	v_max_f32_e32 v18, 0, v18
	v_max_f32_e32 v19, 0, v19
	v_fma_f32 v18, v174, v18, 0
	v_max_f32_e32 v20, 0, v20
	v_fmac_f32_e32 v18, v173, v19
	v_max_f32_e32 v21, 0, v21
	v_fmac_f32_e32 v18, v172, v20
	v_max_f32_e32 v22, 0, v22
	v_fmac_f32_e32 v18, v171, v21
	v_max_f32_e32 v23, 0, v23
	v_fmac_f32_e32 v18, v170, v22
	v_max_f32_e32 v24, 0, v24
	v_fmac_f32_e32 v18, v169, v23
	v_max_f32_e32 v25, 0, v25
	v_fmac_f32_e32 v18, v168, v24
	v_max_f32_e32 v26, 0, v26
	v_fmac_f32_e32 v18, v167, v25
	v_max_f32_e32 v27, 0, v27
	v_fmac_f32_e32 v18, v166, v26
	v_max_f32_e32 v28, 0, v28
	v_fmac_f32_e32 v18, v165, v27
	v_max_f32_e32 v29, 0, v29
	v_fmac_f32_e32 v18, v164, v28
	v_max_f32_e32 v30, 0, v30
	v_fmac_f32_e32 v18, v163, v29
	v_fmac_f32_e32 v18, v162, v30
	v_max_f32_e32 v19, 0, v31
	v_fmac_f32_e32 v18, v161, v19
	v_max_f32_e32 v19, 0, v32
	v_fmac_f32_e32 v18, v160, v19
	v_max_f32_e32 v19, 0, v33
	v_fmac_f32_e32 v18, v89, v19
	v_not_b32_e32 v19, v18
	v_or_b32_e32 v20, 0x80000000, v18
	v_cmp_gt_i32_e32 vcc, 0, v18
	s_nop 1
	v_cndmask_b32_e32 v18, v20, v19, vcc
	v_cmp_le_u32_e32 vcc, v104, v87
	s_nop 1
	v_cndmask_b32_e32 v185, 0, v18, vcc
	s_branch .Lidxp_w11
.Lidxp_e11:
	v_max_f32_e32 v2, 0, v2
	v_max_f32_e32 v3, 0, v3
	v_fma_f32 v2, v174, v2, 0
	v_max_f32_e32 v4, 0, v4
	v_fmac_f32_e32 v2, v173, v3
	v_max_f32_e32 v5, 0, v5
	v_fmac_f32_e32 v2, v172, v4
	v_max_f32_e32 v6, 0, v6
	v_fmac_f32_e32 v2, v171, v5
	v_max_f32_e32 v7, 0, v7
	v_fmac_f32_e32 v2, v170, v6
	v_max_f32_e32 v8, 0, v8
	v_fmac_f32_e32 v2, v169, v7
	v_max_f32_e32 v9, 0, v9
	v_fmac_f32_e32 v2, v168, v8
	v_max_f32_e32 v10, 0, v10
	v_fmac_f32_e32 v2, v167, v9
	v_max_f32_e32 v11, 0, v11
	v_fmac_f32_e32 v2, v166, v10
	v_max_f32_e32 v12, 0, v12
	v_fmac_f32_e32 v2, v165, v11
	v_max_f32_e32 v13, 0, v13
	v_fmac_f32_e32 v2, v164, v12
	v_max_f32_e32 v14, 0, v14
	v_fmac_f32_e32 v2, v163, v13
	v_fmac_f32_e32 v2, v162, v14
	v_max_f32_e32 v3, 0, v15
	v_fmac_f32_e32 v2, v161, v3
	v_max_f32_e32 v3, 0, v16
	v_fmac_f32_e32 v2, v160, v3
	v_max_f32_e32 v3, 0, v17
	v_fmac_f32_e32 v2, v89, v3
	v_not_b32_e32 v3, v2
	v_or_b32_e32 v4, 0x80000000, v2
	v_cmp_gt_i32_e32 vcc, 0, v2
	s_nop 1
	v_cndmask_b32_e32 v2, v4, v3, vcc
	v_cmp_le_u32_e32 vcc, v105, v87
	s_nop 1
	v_cndmask_b32_e32 v186, 0, v2, vcc
	s_branch .Lidxp_w12
.Lidxp_e12:
	v_max_f32_e32 v18, 0, v18
	v_max_f32_e32 v19, 0, v19
	v_fma_f32 v18, v174, v18, 0
	v_max_f32_e32 v20, 0, v20
	v_fmac_f32_e32 v18, v173, v19
	v_max_f32_e32 v21, 0, v21
	v_fmac_f32_e32 v18, v172, v20
	v_max_f32_e32 v22, 0, v22
	v_fmac_f32_e32 v18, v171, v21
	v_max_f32_e32 v23, 0, v23
	v_fmac_f32_e32 v18, v170, v22
	v_max_f32_e32 v24, 0, v24
	v_fmac_f32_e32 v18, v169, v23
	v_max_f32_e32 v25, 0, v25
	v_fmac_f32_e32 v18, v168, v24
	v_max_f32_e32 v26, 0, v26
	v_fmac_f32_e32 v18, v167, v25
	v_max_f32_e32 v27, 0, v27
	v_fmac_f32_e32 v18, v166, v26
	v_max_f32_e32 v28, 0, v28
	v_fmac_f32_e32 v18, v165, v27
	v_max_f32_e32 v29, 0, v29
	v_fmac_f32_e32 v18, v164, v28
	v_max_f32_e32 v30, 0, v30
	v_fmac_f32_e32 v18, v163, v29
	v_fmac_f32_e32 v18, v162, v30
	v_max_f32_e32 v19, 0, v31
	v_fmac_f32_e32 v18, v161, v19
	v_max_f32_e32 v19, 0, v32
	v_fmac_f32_e32 v18, v160, v19
	v_max_f32_e32 v19, 0, v33
	v_fmac_f32_e32 v18, v89, v19
	v_not_b32_e32 v19, v18
	v_or_b32_e32 v20, 0x80000000, v18
	v_cmp_gt_i32_e32 vcc, 0, v18
	s_nop 1
	v_cndmask_b32_e32 v18, v20, v19, vcc
	v_cmp_le_u32_e32 vcc, v106, v87
	s_nop 1
	v_cndmask_b32_e32 v187, 0, v18, vcc
	s_branch .Lidxp_w13
.Lidxp_e13:
	v_max_f32_e32 v2, 0, v2
	v_max_f32_e32 v3, 0, v3
	v_fma_f32 v2, v174, v2, 0
	v_max_f32_e32 v4, 0, v4
	v_fmac_f32_e32 v2, v173, v3
	v_max_f32_e32 v5, 0, v5
	v_fmac_f32_e32 v2, v172, v4
	v_max_f32_e32 v6, 0, v6
	v_fmac_f32_e32 v2, v171, v5
	v_max_f32_e32 v7, 0, v7
	v_fmac_f32_e32 v2, v170, v6
	v_max_f32_e32 v8, 0, v8
	v_fmac_f32_e32 v2, v169, v7
	v_max_f32_e32 v9, 0, v9
	v_fmac_f32_e32 v2, v168, v8
	v_max_f32_e32 v10, 0, v10
	v_fmac_f32_e32 v2, v167, v9
	v_max_f32_e32 v11, 0, v11
	v_fmac_f32_e32 v2, v166, v10
	v_max_f32_e32 v12, 0, v12
	v_fmac_f32_e32 v2, v165, v11
	v_max_f32_e32 v13, 0, v13
	v_fmac_f32_e32 v2, v164, v12
	v_max_f32_e32 v14, 0, v14
	v_fmac_f32_e32 v2, v163, v13
	v_fmac_f32_e32 v2, v162, v14
	v_max_f32_e32 v3, 0, v15
	v_fmac_f32_e32 v2, v161, v3
	v_max_f32_e32 v3, 0, v16
	v_fmac_f32_e32 v2, v160, v3
	v_max_f32_e32 v3, 0, v17
	v_fmac_f32_e32 v2, v89, v3
	v_not_b32_e32 v3, v2
	v_or_b32_e32 v4, 0x80000000, v2
	v_cmp_gt_i32_e32 vcc, 0, v2
	s_nop 1
	v_cndmask_b32_e32 v2, v4, v3, vcc
	v_cmp_le_u32_e32 vcc, v107, v87
	s_nop 1
	v_cndmask_b32_e32 v188, 0, v2, vcc
	s_branch .Lidxp_w14
.Lidxp_e14:
	v_max_f32_e32 v18, 0, v18
	v_max_f32_e32 v19, 0, v19
	v_fma_f32 v18, v174, v18, 0
	v_max_f32_e32 v20, 0, v20
	v_fmac_f32_e32 v18, v173, v19
	v_max_f32_e32 v21, 0, v21
	v_fmac_f32_e32 v18, v172, v20
	v_max_f32_e32 v22, 0, v22
	v_fmac_f32_e32 v18, v171, v21
	v_max_f32_e32 v23, 0, v23
	v_fmac_f32_e32 v18, v170, v22
	v_max_f32_e32 v24, 0, v24
	v_fmac_f32_e32 v18, v169, v23
	v_max_f32_e32 v25, 0, v25
	v_fmac_f32_e32 v18, v168, v24
	v_max_f32_e32 v26, 0, v26
	v_fmac_f32_e32 v18, v167, v25
	v_max_f32_e32 v27, 0, v27
	v_fmac_f32_e32 v18, v166, v26
	v_max_f32_e32 v28, 0, v28
	v_fmac_f32_e32 v18, v165, v27
	v_max_f32_e32 v29, 0, v29
	v_fmac_f32_e32 v18, v164, v28
	v_max_f32_e32 v30, 0, v30
	v_fmac_f32_e32 v18, v163, v29
	v_fmac_f32_e32 v18, v162, v30
	v_max_f32_e32 v19, 0, v31
	v_fmac_f32_e32 v18, v161, v19
	v_max_f32_e32 v19, 0, v32
	v_fmac_f32_e32 v18, v160, v19
	v_max_f32_e32 v19, 0, v33
	v_fmac_f32_e32 v18, v89, v19
	v_not_b32_e32 v19, v18
	v_or_b32_e32 v20, 0x80000000, v18
	v_cmp_gt_i32_e32 vcc, 0, v18
	s_nop 1
	v_cndmask_b32_e32 v18, v20, v19, vcc
	v_cmp_le_u32_e32 vcc, v108, v87
	s_nop 1
	v_cndmask_b32_e32 v189, 0, v18, vcc
	s_branch .Lidxp_w15
.Lidxp_e15:
	v_max_f32_e32 v2, 0, v2
	v_max_f32_e32 v3, 0, v3
	v_fma_f32 v2, v174, v2, 0
	v_max_f32_e32 v4, 0, v4
	v_fmac_f32_e32 v2, v173, v3
	v_max_f32_e32 v5, 0, v5
	v_fmac_f32_e32 v2, v172, v4
	v_max_f32_e32 v6, 0, v6
	v_fmac_f32_e32 v2, v171, v5
	v_max_f32_e32 v7, 0, v7
	v_fmac_f32_e32 v2, v170, v6
	v_max_f32_e32 v8, 0, v8
	v_fmac_f32_e32 v2, v169, v7
	v_max_f32_e32 v9, 0, v9
	v_fmac_f32_e32 v2, v168, v8
	v_max_f32_e32 v10, 0, v10
	v_fmac_f32_e32 v2, v167, v9
	v_max_f32_e32 v11, 0, v11
	v_fmac_f32_e32 v2, v166, v10
	v_max_f32_e32 v12, 0, v12
	v_fmac_f32_e32 v2, v165, v11
	v_max_f32_e32 v13, 0, v13
	v_fmac_f32_e32 v2, v164, v12
	v_max_f32_e32 v14, 0, v14
	v_fmac_f32_e32 v2, v163, v13
	v_fmac_f32_e32 v2, v162, v14
	v_max_f32_e32 v3, 0, v15
	v_fmac_f32_e32 v2, v161, v3
	v_max_f32_e32 v3, 0, v16
	v_fmac_f32_e32 v2, v160, v3
	v_max_f32_e32 v3, 0, v17
	v_fmac_f32_e32 v2, v89, v3
	v_not_b32_e32 v3, v2
	v_or_b32_e32 v4, 0x80000000, v2
	v_cmp_gt_i32_e32 vcc, 0, v2
	s_nop 1
	v_cndmask_b32_e32 v2, v4, v3, vcc
	v_cmp_le_u32_e32 vcc, v109, v87
	s_nop 1
	v_cndmask_b32_e32 v190, 0, v2, vcc
	s_branch .Lidxp_w16
.Lidxp_e16:
	v_max_f32_e32 v18, 0, v18
	v_max_f32_e32 v19, 0, v19
	v_fma_f32 v18, v174, v18, 0
	v_max_f32_e32 v20, 0, v20
	v_fmac_f32_e32 v18, v173, v19
	v_max_f32_e32 v21, 0, v21
	v_fmac_f32_e32 v18, v172, v20
	v_max_f32_e32 v22, 0, v22
	v_fmac_f32_e32 v18, v171, v21
	v_max_f32_e32 v23, 0, v23
	v_fmac_f32_e32 v18, v170, v22
	v_max_f32_e32 v24, 0, v24
	v_fmac_f32_e32 v18, v169, v23
	v_max_f32_e32 v25, 0, v25
	v_fmac_f32_e32 v18, v168, v24
	v_max_f32_e32 v26, 0, v26
	v_fmac_f32_e32 v18, v167, v25
	v_max_f32_e32 v27, 0, v27
	v_fmac_f32_e32 v18, v166, v26
	v_max_f32_e32 v28, 0, v28
	v_fmac_f32_e32 v18, v165, v27
	v_max_f32_e32 v29, 0, v29
	v_fmac_f32_e32 v18, v164, v28
	v_max_f32_e32 v30, 0, v30
	v_fmac_f32_e32 v18, v163, v29
	v_fmac_f32_e32 v18, v162, v30
	v_max_f32_e32 v19, 0, v31
	v_fmac_f32_e32 v18, v161, v19
	v_max_f32_e32 v19, 0, v32
	v_fmac_f32_e32 v18, v160, v19
	v_max_f32_e32 v19, 0, v33
	v_fmac_f32_e32 v18, v89, v19
	v_not_b32_e32 v19, v18
	v_or_b32_e32 v20, 0x80000000, v18
	v_cmp_gt_i32_e32 vcc, 0, v18
	s_nop 1
	v_cndmask_b32_e32 v18, v20, v19, vcc
	v_cmp_le_u32_e32 vcc, v110, v87
	s_nop 1
	v_cndmask_b32_e32 v191, 0, v18, vcc
	s_branch .Lidxp_w17
.Lidxp_e17:
	v_max_f32_e32 v2, 0, v2
	v_max_f32_e32 v3, 0, v3
	v_fma_f32 v2, v174, v2, 0
	v_max_f32_e32 v4, 0, v4
	v_fmac_f32_e32 v2, v173, v3
	v_max_f32_e32 v5, 0, v5
	v_fmac_f32_e32 v2, v172, v4
	v_max_f32_e32 v6, 0, v6
	v_fmac_f32_e32 v2, v171, v5
	v_max_f32_e32 v7, 0, v7
	v_fmac_f32_e32 v2, v170, v6
	v_max_f32_e32 v8, 0, v8
	v_fmac_f32_e32 v2, v169, v7
	v_max_f32_e32 v9, 0, v9
	v_fmac_f32_e32 v2, v168, v8
	v_max_f32_e32 v10, 0, v10
	v_fmac_f32_e32 v2, v167, v9
	v_max_f32_e32 v11, 0, v11
	v_fmac_f32_e32 v2, v166, v10
	v_max_f32_e32 v12, 0, v12
	v_fmac_f32_e32 v2, v165, v11
	v_max_f32_e32 v13, 0, v13
	v_fmac_f32_e32 v2, v164, v12
	v_max_f32_e32 v14, 0, v14
	v_fmac_f32_e32 v2, v163, v13
	v_fmac_f32_e32 v2, v162, v14
	v_max_f32_e32 v3, 0, v15
	v_fmac_f32_e32 v2, v161, v3
	v_max_f32_e32 v3, 0, v16
	v_fmac_f32_e32 v2, v160, v3
	v_max_f32_e32 v3, 0, v17
	v_fmac_f32_e32 v2, v89, v3
	v_not_b32_e32 v3, v2
	v_or_b32_e32 v4, 0x80000000, v2
	v_cmp_gt_i32_e32 vcc, 0, v2
	s_nop 1
	v_cndmask_b32_e32 v2, v4, v3, vcc
	v_cmp_le_u32_e32 vcc, v111, v87
	s_nop 1
	v_cndmask_b32_e32 v192, 0, v2, vcc
	s_branch .Lidxp_w18
.Lidxp_e18:
	v_max_f32_e32 v18, 0, v18
	v_max_f32_e32 v19, 0, v19
	v_fma_f32 v18, v174, v18, 0
	v_max_f32_e32 v20, 0, v20
	v_fmac_f32_e32 v18, v173, v19
	v_max_f32_e32 v21, 0, v21
	v_fmac_f32_e32 v18, v172, v20
	v_max_f32_e32 v22, 0, v22
	v_fmac_f32_e32 v18, v171, v21
	v_max_f32_e32 v23, 0, v23
	v_fmac_f32_e32 v18, v170, v22
	v_max_f32_e32 v24, 0, v24
	v_fmac_f32_e32 v18, v169, v23
	v_max_f32_e32 v25, 0, v25
	v_fmac_f32_e32 v18, v168, v24
	v_max_f32_e32 v26, 0, v26
	v_fmac_f32_e32 v18, v167, v25
	v_max_f32_e32 v27, 0, v27
	v_fmac_f32_e32 v18, v166, v26
	v_max_f32_e32 v28, 0, v28
	v_fmac_f32_e32 v18, v165, v27
	v_max_f32_e32 v29, 0, v29
	v_fmac_f32_e32 v18, v164, v28
	v_max_f32_e32 v30, 0, v30
	v_fmac_f32_e32 v18, v163, v29
	v_fmac_f32_e32 v18, v162, v30
	v_max_f32_e32 v19, 0, v31
	v_fmac_f32_e32 v18, v161, v19
	v_max_f32_e32 v19, 0, v32
	v_fmac_f32_e32 v18, v160, v19
	v_max_f32_e32 v19, 0, v33
	v_fmac_f32_e32 v18, v89, v19
	v_not_b32_e32 v19, v18
	v_or_b32_e32 v20, 0x80000000, v18
	v_cmp_gt_i32_e32 vcc, 0, v18
	s_nop 1
	v_cndmask_b32_e32 v18, v20, v19, vcc
	v_cmp_le_u32_e32 vcc, v112, v87
	s_nop 1
	v_cndmask_b32_e32 v193, 0, v18, vcc
	s_branch .Lidxp_w19
.Lidxp_e19:
	v_max_f32_e32 v2, 0, v2
	v_max_f32_e32 v3, 0, v3
	v_fma_f32 v2, v174, v2, 0
	v_max_f32_e32 v4, 0, v4
	v_fmac_f32_e32 v2, v173, v3
	v_max_f32_e32 v5, 0, v5
	v_fmac_f32_e32 v2, v172, v4
	v_max_f32_e32 v6, 0, v6
	v_fmac_f32_e32 v2, v171, v5
	v_max_f32_e32 v7, 0, v7
	v_fmac_f32_e32 v2, v170, v6
	v_max_f32_e32 v8, 0, v8
	v_fmac_f32_e32 v2, v169, v7
	v_max_f32_e32 v9, 0, v9
	v_fmac_f32_e32 v2, v168, v8
	v_max_f32_e32 v10, 0, v10
	v_fmac_f32_e32 v2, v167, v9
	v_max_f32_e32 v11, 0, v11
	v_fmac_f32_e32 v2, v166, v10
	v_max_f32_e32 v12, 0, v12
	v_fmac_f32_e32 v2, v165, v11
	v_max_f32_e32 v13, 0, v13
	v_fmac_f32_e32 v2, v164, v12
	v_max_f32_e32 v14, 0, v14
	v_fmac_f32_e32 v2, v163, v13
	v_fmac_f32_e32 v2, v162, v14
	v_max_f32_e32 v3, 0, v15
	v_fmac_f32_e32 v2, v161, v3
	v_max_f32_e32 v3, 0, v16
	v_fmac_f32_e32 v2, v160, v3
	v_max_f32_e32 v3, 0, v17
	v_fmac_f32_e32 v2, v89, v3
	v_not_b32_e32 v3, v2
	v_or_b32_e32 v4, 0x80000000, v2
	v_cmp_gt_i32_e32 vcc, 0, v2
	s_nop 1
	v_cndmask_b32_e32 v2, v4, v3, vcc
	v_cmp_le_u32_e32 vcc, v113, v87
	s_nop 1
	v_cndmask_b32_e32 v194, 0, v2, vcc
	s_branch .Lidxp_w20
.Lidxp_e20:
	v_max_f32_e32 v18, 0, v18
	v_max_f32_e32 v19, 0, v19
	v_fma_f32 v18, v174, v18, 0
	v_max_f32_e32 v20, 0, v20
	v_fmac_f32_e32 v18, v173, v19
	v_max_f32_e32 v21, 0, v21
	v_fmac_f32_e32 v18, v172, v20
	v_max_f32_e32 v22, 0, v22
	v_fmac_f32_e32 v18, v171, v21
	v_max_f32_e32 v23, 0, v23
	v_fmac_f32_e32 v18, v170, v22
	v_max_f32_e32 v24, 0, v24
	v_fmac_f32_e32 v18, v169, v23
	v_max_f32_e32 v25, 0, v25
	v_fmac_f32_e32 v18, v168, v24
	v_max_f32_e32 v26, 0, v26
	v_fmac_f32_e32 v18, v167, v25
	v_max_f32_e32 v27, 0, v27
	v_fmac_f32_e32 v18, v166, v26
	v_max_f32_e32 v28, 0, v28
	v_fmac_f32_e32 v18, v165, v27
	v_max_f32_e32 v29, 0, v29
	v_fmac_f32_e32 v18, v164, v28
	v_max_f32_e32 v30, 0, v30
	v_fmac_f32_e32 v18, v163, v29
	v_fmac_f32_e32 v18, v162, v30
	v_max_f32_e32 v19, 0, v31
	v_fmac_f32_e32 v18, v161, v19
	v_max_f32_e32 v19, 0, v32
	v_fmac_f32_e32 v18, v160, v19
	v_max_f32_e32 v19, 0, v33
	v_fmac_f32_e32 v18, v89, v19
	v_not_b32_e32 v19, v18
	v_or_b32_e32 v20, 0x80000000, v18
	v_cmp_gt_i32_e32 vcc, 0, v18
	s_nop 1
	v_cndmask_b32_e32 v18, v20, v19, vcc
	v_cmp_le_u32_e32 vcc, v114, v87
	s_nop 1
	v_cndmask_b32_e32 v195, 0, v18, vcc
	s_branch .Lidxp_w21
.Lidxp_e21:
	v_max_f32_e32 v2, 0, v2
	v_max_f32_e32 v3, 0, v3
	v_fma_f32 v2, v174, v2, 0
	v_max_f32_e32 v4, 0, v4
	v_fmac_f32_e32 v2, v173, v3
	v_max_f32_e32 v5, 0, v5
	v_fmac_f32_e32 v2, v172, v4
	v_max_f32_e32 v6, 0, v6
	v_fmac_f32_e32 v2, v171, v5
	v_max_f32_e32 v7, 0, v7
	v_fmac_f32_e32 v2, v170, v6
	v_max_f32_e32 v8, 0, v8
	v_fmac_f32_e32 v2, v169, v7
	v_max_f32_e32 v9, 0, v9
	v_fmac_f32_e32 v2, v168, v8
	v_max_f32_e32 v10, 0, v10
	v_fmac_f32_e32 v2, v167, v9
	v_max_f32_e32 v11, 0, v11
	v_fmac_f32_e32 v2, v166, v10
	v_max_f32_e32 v12, 0, v12
	v_fmac_f32_e32 v2, v165, v11
	v_max_f32_e32 v13, 0, v13
	v_fmac_f32_e32 v2, v164, v12
	v_max_f32_e32 v14, 0, v14
	v_fmac_f32_e32 v2, v163, v13
	v_fmac_f32_e32 v2, v162, v14
	v_max_f32_e32 v3, 0, v15
	v_fmac_f32_e32 v2, v161, v3
	v_max_f32_e32 v3, 0, v16
	v_fmac_f32_e32 v2, v160, v3
	v_max_f32_e32 v3, 0, v17
	v_fmac_f32_e32 v2, v89, v3
	v_not_b32_e32 v3, v2
	v_or_b32_e32 v4, 0x80000000, v2
	v_cmp_gt_i32_e32 vcc, 0, v2
	s_nop 1
	v_cndmask_b32_e32 v2, v4, v3, vcc
	v_cmp_le_u32_e32 vcc, v115, v87
	s_nop 1
	v_cndmask_b32_e32 v196, 0, v2, vcc
	s_branch .Lidxp_w22
.Lidxp_e22:
	v_max_f32_e32 v18, 0, v18
	v_max_f32_e32 v19, 0, v19
	v_fma_f32 v18, v174, v18, 0
	v_max_f32_e32 v20, 0, v20
	v_fmac_f32_e32 v18, v173, v19
	v_max_f32_e32 v21, 0, v21
	v_fmac_f32_e32 v18, v172, v20
	v_max_f32_e32 v22, 0, v22
	v_fmac_f32_e32 v18, v171, v21
	v_max_f32_e32 v23, 0, v23
	v_fmac_f32_e32 v18, v170, v22
	v_max_f32_e32 v24, 0, v24
	v_fmac_f32_e32 v18, v169, v23
	v_max_f32_e32 v25, 0, v25
	v_fmac_f32_e32 v18, v168, v24
	v_max_f32_e32 v26, 0, v26
	v_fmac_f32_e32 v18, v167, v25
	v_max_f32_e32 v27, 0, v27
	v_fmac_f32_e32 v18, v166, v26
	v_max_f32_e32 v28, 0, v28
	v_fmac_f32_e32 v18, v165, v27
	v_max_f32_e32 v29, 0, v29
	v_fmac_f32_e32 v18, v164, v28
	v_max_f32_e32 v30, 0, v30
	v_fmac_f32_e32 v18, v163, v29
	v_fmac_f32_e32 v18, v162, v30
	v_max_f32_e32 v19, 0, v31
	v_fmac_f32_e32 v18, v161, v19
	v_max_f32_e32 v19, 0, v32
	v_fmac_f32_e32 v18, v160, v19
	v_max_f32_e32 v19, 0, v33
	v_fmac_f32_e32 v18, v89, v19
	v_not_b32_e32 v19, v18
	v_or_b32_e32 v20, 0x80000000, v18
	v_cmp_gt_i32_e32 vcc, 0, v18
	s_nop 1
	v_cndmask_b32_e32 v18, v20, v19, vcc
	v_cmp_le_u32_e32 vcc, v116, v87
	s_nop 1
	v_cndmask_b32_e32 v197, 0, v18, vcc
	s_branch .Lidxp_w23
.Lidxp_e23:
	v_max_f32_e32 v2, 0, v2
	v_max_f32_e32 v3, 0, v3
	v_fma_f32 v2, v174, v2, 0
	v_max_f32_e32 v4, 0, v4
	v_fmac_f32_e32 v2, v173, v3
	v_max_f32_e32 v5, 0, v5
	v_fmac_f32_e32 v2, v172, v4
	v_max_f32_e32 v6, 0, v6
	v_fmac_f32_e32 v2, v171, v5
	v_max_f32_e32 v7, 0, v7
	v_fmac_f32_e32 v2, v170, v6
	v_max_f32_e32 v8, 0, v8
	v_fmac_f32_e32 v2, v169, v7
	v_max_f32_e32 v9, 0, v9
	v_fmac_f32_e32 v2, v168, v8
	v_max_f32_e32 v10, 0, v10
	v_fmac_f32_e32 v2, v167, v9
	v_max_f32_e32 v11, 0, v11
	v_fmac_f32_e32 v2, v166, v10
	v_max_f32_e32 v12, 0, v12
	v_fmac_f32_e32 v2, v165, v11
	v_max_f32_e32 v13, 0, v13
	v_fmac_f32_e32 v2, v164, v12
	v_max_f32_e32 v14, 0, v14
	v_fmac_f32_e32 v2, v163, v13
	v_fmac_f32_e32 v2, v162, v14
	v_max_f32_e32 v3, 0, v15
	v_fmac_f32_e32 v2, v161, v3
	v_max_f32_e32 v3, 0, v16
	v_fmac_f32_e32 v2, v160, v3
	v_max_f32_e32 v3, 0, v17
	v_fmac_f32_e32 v2, v89, v3
	v_not_b32_e32 v3, v2
	v_or_b32_e32 v4, 0x80000000, v2
	v_cmp_gt_i32_e32 vcc, 0, v2
	s_nop 1
	v_cndmask_b32_e32 v2, v4, v3, vcc
	v_cmp_le_u32_e32 vcc, v117, v87
	s_nop 1
	v_cndmask_b32_e32 v216, 0, v2, vcc
	s_branch .Lidxp_w24
.Lidxp_e24:
	v_max_f32_e32 v18, 0, v18
	v_max_f32_e32 v19, 0, v19
	v_fma_f32 v18, v174, v18, 0
	v_max_f32_e32 v20, 0, v20
	v_fmac_f32_e32 v18, v173, v19
	v_max_f32_e32 v21, 0, v21
	v_fmac_f32_e32 v18, v172, v20
	v_max_f32_e32 v22, 0, v22
	v_fmac_f32_e32 v18, v171, v21
	v_max_f32_e32 v23, 0, v23
	v_fmac_f32_e32 v18, v170, v22
	v_max_f32_e32 v24, 0, v24
	v_fmac_f32_e32 v18, v169, v23
	v_max_f32_e32 v25, 0, v25
	v_fmac_f32_e32 v18, v168, v24
	v_max_f32_e32 v26, 0, v26
	v_fmac_f32_e32 v18, v167, v25
	v_max_f32_e32 v27, 0, v27
	v_fmac_f32_e32 v18, v166, v26
	v_max_f32_e32 v28, 0, v28
	v_fmac_f32_e32 v18, v165, v27
	v_max_f32_e32 v29, 0, v29
	v_fmac_f32_e32 v18, v164, v28
	v_max_f32_e32 v30, 0, v30
	v_fmac_f32_e32 v18, v163, v29
	v_fmac_f32_e32 v18, v162, v30
	v_max_f32_e32 v19, 0, v31
	v_fmac_f32_e32 v18, v161, v19
	v_max_f32_e32 v19, 0, v32
	v_fmac_f32_e32 v18, v160, v19
	v_max_f32_e32 v19, 0, v33
	v_fmac_f32_e32 v18, v89, v19
	v_not_b32_e32 v19, v18
	v_or_b32_e32 v20, 0x80000000, v18
	v_cmp_gt_i32_e32 vcc, 0, v18
	s_nop 1
	v_cndmask_b32_e32 v18, v20, v19, vcc
	v_cmp_le_u32_e32 vcc, v118, v87
	s_nop 1
	v_cndmask_b32_e32 v217, 0, v18, vcc
	s_branch .Lidxp_w25
.Lidxp_e25:
	v_max_f32_e32 v2, 0, v2
	v_max_f32_e32 v3, 0, v3
	v_fma_f32 v2, v174, v2, 0
	v_max_f32_e32 v4, 0, v4
	v_fmac_f32_e32 v2, v173, v3
	v_max_f32_e32 v5, 0, v5
	v_fmac_f32_e32 v2, v172, v4
	v_max_f32_e32 v6, 0, v6
	v_fmac_f32_e32 v2, v171, v5
	v_max_f32_e32 v7, 0, v7
	v_fmac_f32_e32 v2, v170, v6
	v_max_f32_e32 v8, 0, v8
	v_fmac_f32_e32 v2, v169, v7
	v_max_f32_e32 v9, 0, v9
	v_fmac_f32_e32 v2, v168, v8
	v_max_f32_e32 v10, 0, v10
	v_fmac_f32_e32 v2, v167, v9
	v_max_f32_e32 v11, 0, v11
	v_fmac_f32_e32 v2, v166, v10
	v_max_f32_e32 v12, 0, v12
	v_fmac_f32_e32 v2, v165, v11
	v_max_f32_e32 v13, 0, v13
	v_fmac_f32_e32 v2, v164, v12
	v_max_f32_e32 v14, 0, v14
	v_fmac_f32_e32 v2, v163, v13
	v_fmac_f32_e32 v2, v162, v14
	v_max_f32_e32 v3, 0, v15
	v_fmac_f32_e32 v2, v161, v3
	v_max_f32_e32 v3, 0, v16
	v_fmac_f32_e32 v2, v160, v3
	v_max_f32_e32 v3, 0, v17
	v_fmac_f32_e32 v2, v89, v3
	v_not_b32_e32 v3, v2
	v_or_b32_e32 v4, 0x80000000, v2
	v_cmp_gt_i32_e32 vcc, 0, v2
	s_nop 1
	v_cndmask_b32_e32 v2, v4, v3, vcc
	v_cmp_le_u32_e32 vcc, v119, v87
	s_nop 1
	v_cndmask_b32_e32 v218, 0, v2, vcc
	s_branch .Lidxp_w26
.Lidxp_e26:
	v_max_f32_e32 v18, 0, v18
	v_max_f32_e32 v19, 0, v19
	v_fma_f32 v18, v174, v18, 0
	v_max_f32_e32 v20, 0, v20
	v_fmac_f32_e32 v18, v173, v19
	v_max_f32_e32 v21, 0, v21
	v_fmac_f32_e32 v18, v172, v20
	v_max_f32_e32 v22, 0, v22
	v_fmac_f32_e32 v18, v171, v21
	v_max_f32_e32 v23, 0, v23
	v_fmac_f32_e32 v18, v170, v22
	v_max_f32_e32 v24, 0, v24
	v_fmac_f32_e32 v18, v169, v23
	v_max_f32_e32 v25, 0, v25
	v_fmac_f32_e32 v18, v168, v24
	v_max_f32_e32 v26, 0, v26
	v_fmac_f32_e32 v18, v167, v25
	v_max_f32_e32 v27, 0, v27
	v_fmac_f32_e32 v18, v166, v26
	v_max_f32_e32 v28, 0, v28
	v_fmac_f32_e32 v18, v165, v27
	v_max_f32_e32 v29, 0, v29
	v_fmac_f32_e32 v18, v164, v28
	v_max_f32_e32 v30, 0, v30
	v_fmac_f32_e32 v18, v163, v29
	v_fmac_f32_e32 v18, v162, v30
	v_max_f32_e32 v19, 0, v31
	v_fmac_f32_e32 v18, v161, v19
	v_max_f32_e32 v19, 0, v32
	v_fmac_f32_e32 v18, v160, v19
	v_max_f32_e32 v19, 0, v33
	v_fmac_f32_e32 v18, v89, v19
	v_not_b32_e32 v19, v18
	v_or_b32_e32 v20, 0x80000000, v18
	v_cmp_gt_i32_e32 vcc, 0, v18
	s_nop 1
	v_cndmask_b32_e32 v18, v20, v19, vcc
	v_cmp_le_u32_e32 vcc, v120, v87
	s_nop 1
	v_cndmask_b32_e32 v219, 0, v18, vcc
	s_branch .Lidxp_w27
.Lidxp_e27:
	v_max_f32_e32 v2, 0, v2
	v_max_f32_e32 v3, 0, v3
	v_fma_f32 v2, v174, v2, 0
	v_max_f32_e32 v4, 0, v4
	v_fmac_f32_e32 v2, v173, v3
	v_max_f32_e32 v5, 0, v5
	v_fmac_f32_e32 v2, v172, v4
	v_max_f32_e32 v6, 0, v6
	v_fmac_f32_e32 v2, v171, v5
	v_max_f32_e32 v7, 0, v7
	v_fmac_f32_e32 v2, v170, v6
	v_max_f32_e32 v8, 0, v8
	v_fmac_f32_e32 v2, v169, v7
	v_max_f32_e32 v9, 0, v9
	v_fmac_f32_e32 v2, v168, v8
	v_max_f32_e32 v10, 0, v10
	v_fmac_f32_e32 v2, v167, v9
	v_max_f32_e32 v11, 0, v11
	v_fmac_f32_e32 v2, v166, v10
	v_max_f32_e32 v12, 0, v12
	v_fmac_f32_e32 v2, v165, v11
	v_max_f32_e32 v13, 0, v13
	v_fmac_f32_e32 v2, v164, v12
	v_max_f32_e32 v14, 0, v14
	v_fmac_f32_e32 v2, v163, v13
	v_fmac_f32_e32 v2, v162, v14
	v_max_f32_e32 v3, 0, v15
	v_fmac_f32_e32 v2, v161, v3
	v_max_f32_e32 v3, 0, v16
	v_fmac_f32_e32 v2, v160, v3
	v_max_f32_e32 v3, 0, v17
	v_fmac_f32_e32 v2, v89, v3
	v_not_b32_e32 v3, v2
	v_or_b32_e32 v4, 0x80000000, v2
	v_cmp_gt_i32_e32 vcc, 0, v2
	s_nop 1
	v_cndmask_b32_e32 v2, v4, v3, vcc
	v_cmp_le_u32_e32 vcc, v121, v87
	s_nop 1
	v_cndmask_b32_e32 v220, 0, v2, vcc
	s_branch .Lidxp_w28
.Lidxp_e28:
	v_max_f32_e32 v18, 0, v18
	v_max_f32_e32 v19, 0, v19
	v_fma_f32 v18, v174, v18, 0
	v_max_f32_e32 v20, 0, v20
	v_fmac_f32_e32 v18, v173, v19
	v_max_f32_e32 v21, 0, v21
	v_fmac_f32_e32 v18, v172, v20
	v_max_f32_e32 v22, 0, v22
	v_fmac_f32_e32 v18, v171, v21
	v_max_f32_e32 v23, 0, v23
	v_fmac_f32_e32 v18, v170, v22
	v_max_f32_e32 v24, 0, v24
	v_fmac_f32_e32 v18, v169, v23
	v_max_f32_e32 v25, 0, v25
	v_fmac_f32_e32 v18, v168, v24
	v_max_f32_e32 v26, 0, v26
	v_fmac_f32_e32 v18, v167, v25
	v_max_f32_e32 v27, 0, v27
	v_fmac_f32_e32 v18, v166, v26
	v_max_f32_e32 v28, 0, v28
	v_fmac_f32_e32 v18, v165, v27
	v_max_f32_e32 v29, 0, v29
	v_fmac_f32_e32 v18, v164, v28
	v_max_f32_e32 v30, 0, v30
	v_fmac_f32_e32 v18, v163, v29
	v_fmac_f32_e32 v18, v162, v30
	v_max_f32_e32 v19, 0, v31
	v_fmac_f32_e32 v18, v161, v19
	v_max_f32_e32 v19, 0, v32
	v_fmac_f32_e32 v18, v160, v19
	v_max_f32_e32 v19, 0, v33
	v_fmac_f32_e32 v18, v89, v19
	v_not_b32_e32 v19, v18
	v_or_b32_e32 v20, 0x80000000, v18
	v_cmp_gt_i32_e32 vcc, 0, v18
	s_nop 1
	v_cndmask_b32_e32 v18, v20, v19, vcc
	v_cmp_le_u32_e32 vcc, v122, v87
	s_nop 1
	v_cndmask_b32_e32 v221, 0, v18, vcc
	s_branch .Lidxp_w29
.Lidxp_e29:
	v_max_f32_e32 v2, 0, v2
	v_max_f32_e32 v3, 0, v3
	v_fma_f32 v2, v174, v2, 0
	v_max_f32_e32 v4, 0, v4
	v_fmac_f32_e32 v2, v173, v3
	v_max_f32_e32 v5, 0, v5
	v_fmac_f32_e32 v2, v172, v4
	v_max_f32_e32 v6, 0, v6
	v_fmac_f32_e32 v2, v171, v5
	v_max_f32_e32 v7, 0, v7
	v_fmac_f32_e32 v2, v170, v6
	v_max_f32_e32 v8, 0, v8
	v_fmac_f32_e32 v2, v169, v7
	v_max_f32_e32 v9, 0, v9
	v_fmac_f32_e32 v2, v168, v8
	v_max_f32_e32 v10, 0, v10
	v_fmac_f32_e32 v2, v167, v9
	v_max_f32_e32 v11, 0, v11
	v_fmac_f32_e32 v2, v166, v10
	v_max_f32_e32 v12, 0, v12
	v_fmac_f32_e32 v2, v165, v11
	v_max_f32_e32 v13, 0, v13
	v_fmac_f32_e32 v2, v164, v12
	v_max_f32_e32 v14, 0, v14
	v_fmac_f32_e32 v2, v163, v13
	v_fmac_f32_e32 v2, v162, v14
	v_max_f32_e32 v3, 0, v15
	v_fmac_f32_e32 v2, v161, v3
	v_max_f32_e32 v3, 0, v16
	v_fmac_f32_e32 v2, v160, v3
	v_max_f32_e32 v3, 0, v17
	v_fmac_f32_e32 v2, v89, v3
	v_not_b32_e32 v3, v2
	v_or_b32_e32 v4, 0x80000000, v2
	v_cmp_gt_i32_e32 vcc, 0, v2
	s_nop 1
	v_cndmask_b32_e32 v2, v4, v3, vcc
	v_cmp_le_u32_e32 vcc, v123, v87
	s_nop 1
	v_cndmask_b32_e32 v222, 0, v2, vcc
	s_branch .Lidxp_w30
.Lidxp_e30:
	v_max_f32_e32 v18, 0, v18
	v_max_f32_e32 v19, 0, v19
	v_fma_f32 v18, v174, v18, 0
	v_max_f32_e32 v20, 0, v20
	v_fmac_f32_e32 v18, v173, v19
	v_max_f32_e32 v21, 0, v21
	v_fmac_f32_e32 v18, v172, v20
	v_max_f32_e32 v22, 0, v22
	v_fmac_f32_e32 v18, v171, v21
	v_max_f32_e32 v23, 0, v23
	v_fmac_f32_e32 v18, v170, v22
	v_max_f32_e32 v24, 0, v24
	v_fmac_f32_e32 v18, v169, v23
	v_max_f32_e32 v25, 0, v25
	v_fmac_f32_e32 v18, v168, v24
	v_max_f32_e32 v26, 0, v26
	v_fmac_f32_e32 v18, v167, v25
	v_max_f32_e32 v27, 0, v27
	v_fmac_f32_e32 v18, v166, v26
	v_max_f32_e32 v28, 0, v28
	v_fmac_f32_e32 v18, v165, v27
	v_max_f32_e32 v29, 0, v29
	v_fmac_f32_e32 v18, v164, v28
	v_max_f32_e32 v30, 0, v30
	v_fmac_f32_e32 v18, v163, v29
	v_fmac_f32_e32 v18, v162, v30
	v_max_f32_e32 v19, 0, v31
	v_fmac_f32_e32 v18, v161, v19
	v_max_f32_e32 v19, 0, v32
	v_fmac_f32_e32 v18, v160, v19
	v_max_f32_e32 v19, 0, v33
	v_fmac_f32_e32 v18, v89, v19
	v_not_b32_e32 v19, v18
	v_or_b32_e32 v20, 0x80000000, v18
	v_cmp_gt_i32_e32 vcc, 0, v18
	s_nop 1
	v_cndmask_b32_e32 v18, v20, v19, vcc
	v_cmp_le_u32_e32 vcc, v124, v87
	s_nop 1
	v_cndmask_b32_e32 v223, 0, v18, vcc
	s_branch .Lidxp_w31
.Lidxp_e31:
	v_max_f32_e32 v2, 0, v2
	v_max_f32_e32 v3, 0, v3
	v_fma_f32 v2, v174, v2, 0
	v_max_f32_e32 v4, 0, v4
	v_fmac_f32_e32 v2, v173, v3
	v_max_f32_e32 v5, 0, v5
	v_fmac_f32_e32 v2, v172, v4
	v_max_f32_e32 v6, 0, v6
	v_fmac_f32_e32 v2, v171, v5
	v_max_f32_e32 v7, 0, v7
	v_fmac_f32_e32 v2, v170, v6
	v_max_f32_e32 v8, 0, v8
	v_fmac_f32_e32 v2, v169, v7
	v_max_f32_e32 v9, 0, v9
	v_fmac_f32_e32 v2, v168, v8
	v_max_f32_e32 v10, 0, v10
	v_fmac_f32_e32 v2, v167, v9
	v_max_f32_e32 v11, 0, v11
	v_fmac_f32_e32 v2, v166, v10
	v_max_f32_e32 v12, 0, v12
	v_fmac_f32_e32 v2, v165, v11
	v_max_f32_e32 v13, 0, v13
	v_fmac_f32_e32 v2, v164, v12
	v_max_f32_e32 v14, 0, v14
	v_fmac_f32_e32 v2, v163, v13
	v_fmac_f32_e32 v2, v162, v14
	v_max_f32_e32 v3, 0, v15
	v_fmac_f32_e32 v2, v161, v3
	v_max_f32_e32 v3, 0, v16
	v_fmac_f32_e32 v2, v160, v3
	v_max_f32_e32 v3, 0, v17
	v_fmac_f32_e32 v2, v89, v3
	v_not_b32_e32 v3, v2
	v_or_b32_e32 v4, 0x80000000, v2
	v_cmp_gt_i32_e32 vcc, 0, v2
	s_nop 1
	v_cndmask_b32_e32 v2, v4, v3, vcc
	v_cmp_le_u32_e32 vcc, v125, v87
	s_nop 1
	v_cndmask_b32_e32 v224, 0, v2, vcc
	s_branch .Lidxp_w32
.Lidxp_e32:
	v_max_f32_e32 v18, 0, v18
	v_max_f32_e32 v19, 0, v19
	v_fma_f32 v18, v174, v18, 0
	v_max_f32_e32 v20, 0, v20
	v_fmac_f32_e32 v18, v173, v19
	v_max_f32_e32 v21, 0, v21
	v_fmac_f32_e32 v18, v172, v20
	v_max_f32_e32 v22, 0, v22
	v_fmac_f32_e32 v18, v171, v21
	v_max_f32_e32 v23, 0, v23
	v_fmac_f32_e32 v18, v170, v22
	v_max_f32_e32 v24, 0, v24
	v_fmac_f32_e32 v18, v169, v23
	v_max_f32_e32 v25, 0, v25
	v_fmac_f32_e32 v18, v168, v24
	v_max_f32_e32 v26, 0, v26
	v_fmac_f32_e32 v18, v167, v25
	v_max_f32_e32 v27, 0, v27
	v_fmac_f32_e32 v18, v166, v26
	v_max_f32_e32 v28, 0, v28
	v_fmac_f32_e32 v18, v165, v27
	v_max_f32_e32 v29, 0, v29
	v_fmac_f32_e32 v18, v164, v28
	v_max_f32_e32 v30, 0, v30
	v_fmac_f32_e32 v18, v163, v29
	v_fmac_f32_e32 v18, v162, v30
	v_max_f32_e32 v19, 0, v31
	v_fmac_f32_e32 v18, v161, v19
	v_max_f32_e32 v19, 0, v32
	v_fmac_f32_e32 v18, v160, v19
	v_max_f32_e32 v19, 0, v33
	v_fmac_f32_e32 v18, v89, v19
	v_not_b32_e32 v19, v18
	v_or_b32_e32 v20, 0x80000000, v18
	v_cmp_gt_i32_e32 vcc, 0, v18
	s_nop 1
	v_cndmask_b32_e32 v18, v20, v19, vcc
	v_cmp_le_u32_e32 vcc, v126, v87
	s_nop 1
	v_cndmask_b32_e32 v225, 0, v18, vcc
	s_branch .Lidxp_w33
.Lidxp_e33:
	v_max_f32_e32 v2, 0, v2
	v_max_f32_e32 v3, 0, v3
	v_fma_f32 v2, v174, v2, 0
	v_max_f32_e32 v4, 0, v4
	v_fmac_f32_e32 v2, v173, v3
	v_max_f32_e32 v5, 0, v5
	v_fmac_f32_e32 v2, v172, v4
	v_max_f32_e32 v6, 0, v6
	v_fmac_f32_e32 v2, v171, v5
	v_max_f32_e32 v7, 0, v7
	v_fmac_f32_e32 v2, v170, v6
	v_max_f32_e32 v8, 0, v8
	v_fmac_f32_e32 v2, v169, v7
	v_max_f32_e32 v9, 0, v9
	v_fmac_f32_e32 v2, v168, v8
	v_max_f32_e32 v10, 0, v10
	v_fmac_f32_e32 v2, v167, v9
	v_max_f32_e32 v11, 0, v11
	v_fmac_f32_e32 v2, v166, v10
	v_max_f32_e32 v12, 0, v12
	v_fmac_f32_e32 v2, v165, v11
	v_max_f32_e32 v13, 0, v13
	v_fmac_f32_e32 v2, v164, v12
	v_max_f32_e32 v14, 0, v14
	v_fmac_f32_e32 v2, v163, v13
	v_fmac_f32_e32 v2, v162, v14
	v_max_f32_e32 v3, 0, v15
	v_fmac_f32_e32 v2, v161, v3
	v_max_f32_e32 v3, 0, v16
	v_fmac_f32_e32 v2, v160, v3
	v_max_f32_e32 v3, 0, v17
	v_fmac_f32_e32 v2, v89, v3
	v_not_b32_e32 v3, v2
	v_or_b32_e32 v4, 0x80000000, v2
	v_cmp_gt_i32_e32 vcc, 0, v2
	s_nop 1
	v_cndmask_b32_e32 v2, v4, v3, vcc
	v_cmp_le_u32_e32 vcc, v127, v87
	s_nop 1
	v_cndmask_b32_e32 v226, 0, v2, vcc
	s_branch .Lidxp_w34
.Lidxp_e34:
	v_max_f32_e32 v18, 0, v18
	v_max_f32_e32 v19, 0, v19
	v_fma_f32 v18, v174, v18, 0
	v_max_f32_e32 v20, 0, v20
	v_fmac_f32_e32 v18, v173, v19
	v_max_f32_e32 v21, 0, v21
	v_fmac_f32_e32 v18, v172, v20
	v_max_f32_e32 v22, 0, v22
	v_fmac_f32_e32 v18, v171, v21
	v_max_f32_e32 v23, 0, v23
	v_fmac_f32_e32 v18, v170, v22
	v_max_f32_e32 v24, 0, v24
	v_fmac_f32_e32 v18, v169, v23
	v_max_f32_e32 v25, 0, v25
	v_fmac_f32_e32 v18, v168, v24
	v_max_f32_e32 v26, 0, v26
	v_fmac_f32_e32 v18, v167, v25
	v_max_f32_e32 v27, 0, v27
	v_fmac_f32_e32 v18, v166, v26
	v_max_f32_e32 v28, 0, v28
	v_fmac_f32_e32 v18, v165, v27
	v_max_f32_e32 v29, 0, v29
	v_fmac_f32_e32 v18, v164, v28
	v_max_f32_e32 v30, 0, v30
	v_fmac_f32_e32 v18, v163, v29
	v_fmac_f32_e32 v18, v162, v30
	v_max_f32_e32 v19, 0, v31
	v_fmac_f32_e32 v18, v161, v19
	v_max_f32_e32 v19, 0, v32
	v_fmac_f32_e32 v18, v160, v19
	v_max_f32_e32 v19, 0, v33
	v_fmac_f32_e32 v18, v89, v19
	v_not_b32_e32 v19, v18
	v_or_b32_e32 v20, 0x80000000, v18
	v_cmp_gt_i32_e32 vcc, 0, v18
	s_nop 1
	v_cndmask_b32_e32 v18, v20, v19, vcc
	v_cmp_le_u32_e32 vcc, v128, v87
	s_nop 1
	v_cndmask_b32_e32 v227, 0, v18, vcc
	s_branch .Lidxp_w35
.Lidxp_e35:
	v_max_f32_e32 v2, 0, v2
	v_max_f32_e32 v3, 0, v3
	v_fma_f32 v2, v174, v2, 0
	v_max_f32_e32 v4, 0, v4
	v_fmac_f32_e32 v2, v173, v3
	v_max_f32_e32 v5, 0, v5
	v_fmac_f32_e32 v2, v172, v4
	v_max_f32_e32 v6, 0, v6
	v_fmac_f32_e32 v2, v171, v5
	v_max_f32_e32 v7, 0, v7
	v_fmac_f32_e32 v2, v170, v6
	v_max_f32_e32 v8, 0, v8
	v_fmac_f32_e32 v2, v169, v7
	v_max_f32_e32 v9, 0, v9
	v_fmac_f32_e32 v2, v168, v8
	v_max_f32_e32 v10, 0, v10
	v_fmac_f32_e32 v2, v167, v9
	v_max_f32_e32 v11, 0, v11
	v_fmac_f32_e32 v2, v166, v10
	v_max_f32_e32 v12, 0, v12
	v_fmac_f32_e32 v2, v165, v11
	v_max_f32_e32 v13, 0, v13
	v_fmac_f32_e32 v2, v164, v12
	v_max_f32_e32 v14, 0, v14
	v_fmac_f32_e32 v2, v163, v13
	v_fmac_f32_e32 v2, v162, v14
	v_max_f32_e32 v3, 0, v15
	v_fmac_f32_e32 v2, v161, v3
	v_max_f32_e32 v3, 0, v16
	v_fmac_f32_e32 v2, v160, v3
	v_max_f32_e32 v3, 0, v17
	v_fmac_f32_e32 v2, v89, v3
	v_not_b32_e32 v3, v2
	v_or_b32_e32 v4, 0x80000000, v2
	v_cmp_gt_i32_e32 vcc, 0, v2
	s_nop 1
	v_cndmask_b32_e32 v2, v4, v3, vcc
	v_cmp_le_u32_e32 vcc, v129, v87
	s_nop 1
	v_cndmask_b32_e32 v228, 0, v2, vcc
	s_branch .Lidxp_w36
.Lidxp_e36:
	v_max_f32_e32 v18, 0, v18
	v_max_f32_e32 v19, 0, v19
	v_fma_f32 v18, v174, v18, 0
	v_max_f32_e32 v20, 0, v20
	v_fmac_f32_e32 v18, v173, v19
	v_max_f32_e32 v21, 0, v21
	v_fmac_f32_e32 v18, v172, v20
	v_max_f32_e32 v22, 0, v22
	v_fmac_f32_e32 v18, v171, v21
	v_max_f32_e32 v23, 0, v23
	v_fmac_f32_e32 v18, v170, v22
	v_max_f32_e32 v24, 0, v24
	v_fmac_f32_e32 v18, v169, v23
	v_max_f32_e32 v25, 0, v25
	v_fmac_f32_e32 v18, v168, v24
	v_max_f32_e32 v26, 0, v26
	v_fmac_f32_e32 v18, v167, v25
	v_max_f32_e32 v27, 0, v27
	v_fmac_f32_e32 v18, v166, v26
	v_max_f32_e32 v28, 0, v28
	v_fmac_f32_e32 v18, v165, v27
	v_max_f32_e32 v29, 0, v29
	v_fmac_f32_e32 v18, v164, v28
	v_max_f32_e32 v30, 0, v30
	v_fmac_f32_e32 v18, v163, v29
	v_fmac_f32_e32 v18, v162, v30
	v_max_f32_e32 v19, 0, v31
	v_fmac_f32_e32 v18, v161, v19
	v_max_f32_e32 v19, 0, v32
	v_fmac_f32_e32 v18, v160, v19
	v_max_f32_e32 v19, 0, v33
	v_fmac_f32_e32 v18, v89, v19
	v_not_b32_e32 v19, v18
	v_or_b32_e32 v20, 0x80000000, v18
	v_cmp_gt_i32_e32 vcc, 0, v18
	s_nop 1
	v_cndmask_b32_e32 v18, v20, v19, vcc
	v_cmp_le_u32_e32 vcc, v130, v87
	s_nop 1
	v_cndmask_b32_e32 v229, 0, v18, vcc
	s_branch .Lidxp_w37
.Lidxp_e37:
	v_max_f32_e32 v2, 0, v2
	v_max_f32_e32 v3, 0, v3
	v_fma_f32 v2, v174, v2, 0
	v_max_f32_e32 v4, 0, v4
	v_fmac_f32_e32 v2, v173, v3
	v_max_f32_e32 v5, 0, v5
	v_fmac_f32_e32 v2, v172, v4
	v_max_f32_e32 v6, 0, v6
	v_fmac_f32_e32 v2, v171, v5
	v_max_f32_e32 v7, 0, v7
	v_fmac_f32_e32 v2, v170, v6
	v_max_f32_e32 v8, 0, v8
	v_fmac_f32_e32 v2, v169, v7
	v_max_f32_e32 v9, 0, v9
	v_fmac_f32_e32 v2, v168, v8
	v_max_f32_e32 v10, 0, v10
	v_fmac_f32_e32 v2, v167, v9
	v_max_f32_e32 v11, 0, v11
	v_fmac_f32_e32 v2, v166, v10
	v_max_f32_e32 v12, 0, v12
	v_fmac_f32_e32 v2, v165, v11
	v_max_f32_e32 v13, 0, v13
	v_fmac_f32_e32 v2, v164, v12
	v_max_f32_e32 v14, 0, v14
	v_fmac_f32_e32 v2, v163, v13
	v_fmac_f32_e32 v2, v162, v14
	v_max_f32_e32 v3, 0, v15
	v_fmac_f32_e32 v2, v161, v3
	v_max_f32_e32 v3, 0, v16
	v_fmac_f32_e32 v2, v160, v3
	v_max_f32_e32 v3, 0, v17
	v_fmac_f32_e32 v2, v89, v3
	v_not_b32_e32 v3, v2
	v_or_b32_e32 v4, 0x80000000, v2
	v_cmp_gt_i32_e32 vcc, 0, v2
	s_nop 1
	v_cndmask_b32_e32 v2, v4, v3, vcc
	v_cmp_le_u32_e32 vcc, v131, v87
	s_nop 1
	v_cndmask_b32_e32 v230, 0, v2, vcc
	s_branch .Lidxp_w38
.Lidxp_e38:
	v_max_f32_e32 v18, 0, v18
	v_max_f32_e32 v19, 0, v19
	v_fma_f32 v18, v174, v18, 0
	v_max_f32_e32 v20, 0, v20
	v_fmac_f32_e32 v18, v173, v19
	v_max_f32_e32 v21, 0, v21
	v_fmac_f32_e32 v18, v172, v20
	v_max_f32_e32 v22, 0, v22
	v_fmac_f32_e32 v18, v171, v21
	v_max_f32_e32 v23, 0, v23
	v_fmac_f32_e32 v18, v170, v22
	v_max_f32_e32 v24, 0, v24
	v_fmac_f32_e32 v18, v169, v23
	v_max_f32_e32 v25, 0, v25
	v_fmac_f32_e32 v18, v168, v24
	v_max_f32_e32 v26, 0, v26
	v_fmac_f32_e32 v18, v167, v25
	v_max_f32_e32 v27, 0, v27
	v_fmac_f32_e32 v18, v166, v26
	v_max_f32_e32 v28, 0, v28
	v_fmac_f32_e32 v18, v165, v27
	v_max_f32_e32 v29, 0, v29
	v_fmac_f32_e32 v18, v164, v28
	v_max_f32_e32 v30, 0, v30
	v_fmac_f32_e32 v18, v163, v29
	v_fmac_f32_e32 v18, v162, v30
	v_max_f32_e32 v19, 0, v31
	v_fmac_f32_e32 v18, v161, v19
	v_max_f32_e32 v19, 0, v32
	v_fmac_f32_e32 v18, v160, v19
	v_max_f32_e32 v19, 0, v33
	v_fmac_f32_e32 v18, v89, v19
	v_not_b32_e32 v19, v18
	v_or_b32_e32 v20, 0x80000000, v18
	v_cmp_gt_i32_e32 vcc, 0, v18
	s_nop 1
	v_cndmask_b32_e32 v18, v20, v19, vcc
	v_cmp_le_u32_e32 vcc, v132, v87
	s_nop 1
	v_cndmask_b32_e32 v231, 0, v18, vcc
	s_branch .Lidxp_w39
.Lidxp_e39:
	v_max_f32_e32 v2, 0, v2
	v_max_f32_e32 v3, 0, v3
	v_fma_f32 v2, v174, v2, 0
	v_max_f32_e32 v4, 0, v4
	v_fmac_f32_e32 v2, v173, v3
	v_max_f32_e32 v5, 0, v5
	v_fmac_f32_e32 v2, v172, v4
	v_max_f32_e32 v6, 0, v6
	v_fmac_f32_e32 v2, v171, v5
	v_max_f32_e32 v7, 0, v7
	v_fmac_f32_e32 v2, v170, v6
	v_max_f32_e32 v8, 0, v8
	v_fmac_f32_e32 v2, v169, v7
	v_max_f32_e32 v9, 0, v9
	v_fmac_f32_e32 v2, v168, v8
	v_max_f32_e32 v10, 0, v10
	v_fmac_f32_e32 v2, v167, v9
	v_max_f32_e32 v11, 0, v11
	v_fmac_f32_e32 v2, v166, v10
	v_max_f32_e32 v12, 0, v12
	v_fmac_f32_e32 v2, v165, v11
	v_max_f32_e32 v13, 0, v13
	v_fmac_f32_e32 v2, v164, v12
	v_max_f32_e32 v14, 0, v14
	v_fmac_f32_e32 v2, v163, v13
	v_fmac_f32_e32 v2, v162, v14
	v_max_f32_e32 v3, 0, v15
	v_fmac_f32_e32 v2, v161, v3
	v_max_f32_e32 v3, 0, v16
	v_fmac_f32_e32 v2, v160, v3
	v_max_f32_e32 v3, 0, v17
	v_fmac_f32_e32 v2, v89, v3
	v_not_b32_e32 v3, v2
	v_or_b32_e32 v4, 0x80000000, v2
	v_cmp_gt_i32_e32 vcc, 0, v2
	s_nop 1
	v_cndmask_b32_e32 v2, v4, v3, vcc
	v_cmp_le_u32_e32 vcc, v133, v87
	s_nop 1
	v_cndmask_b32_e32 v232, 0, v2, vcc
	s_branch .Lidxp_w40
.Lidxp_e40:
	v_max_f32_e32 v18, 0, v18
	v_max_f32_e32 v19, 0, v19
	v_fma_f32 v18, v174, v18, 0
	v_max_f32_e32 v20, 0, v20
	v_fmac_f32_e32 v18, v173, v19
	v_max_f32_e32 v21, 0, v21
	v_fmac_f32_e32 v18, v172, v20
	v_max_f32_e32 v22, 0, v22
	v_fmac_f32_e32 v18, v171, v21
	v_max_f32_e32 v23, 0, v23
	v_fmac_f32_e32 v18, v170, v22
	v_max_f32_e32 v24, 0, v24
	v_fmac_f32_e32 v18, v169, v23
	v_max_f32_e32 v25, 0, v25
	v_fmac_f32_e32 v18, v168, v24
	v_max_f32_e32 v26, 0, v26
	v_fmac_f32_e32 v18, v167, v25
	v_max_f32_e32 v27, 0, v27
	v_fmac_f32_e32 v18, v166, v26
	v_max_f32_e32 v28, 0, v28
	v_fmac_f32_e32 v18, v165, v27
	v_max_f32_e32 v29, 0, v29
	v_fmac_f32_e32 v18, v164, v28
	v_max_f32_e32 v30, 0, v30
	v_fmac_f32_e32 v18, v163, v29
	v_fmac_f32_e32 v18, v162, v30
	v_max_f32_e32 v19, 0, v31
	v_fmac_f32_e32 v18, v161, v19
	v_max_f32_e32 v19, 0, v32
	v_fmac_f32_e32 v18, v160, v19
	v_max_f32_e32 v19, 0, v33
	v_fmac_f32_e32 v18, v89, v19
	v_not_b32_e32 v19, v18
	v_or_b32_e32 v20, 0x80000000, v18
	v_cmp_gt_i32_e32 vcc, 0, v18
	s_nop 1
	v_cndmask_b32_e32 v18, v20, v19, vcc
	v_cmp_le_u32_e32 vcc, v134, v87
	s_nop 1
	v_cndmask_b32_e32 v233, 0, v18, vcc
	s_branch .Lidxp_w41
.Lidxp_e41:
	v_max_f32_e32 v2, 0, v2
	v_max_f32_e32 v3, 0, v3
	v_fma_f32 v2, v174, v2, 0
	v_max_f32_e32 v4, 0, v4
	v_fmac_f32_e32 v2, v173, v3
	v_max_f32_e32 v5, 0, v5
	v_fmac_f32_e32 v2, v172, v4
	v_max_f32_e32 v6, 0, v6
	v_fmac_f32_e32 v2, v171, v5
	v_max_f32_e32 v7, 0, v7
	v_fmac_f32_e32 v2, v170, v6
	v_max_f32_e32 v8, 0, v8
	v_fmac_f32_e32 v2, v169, v7
	v_max_f32_e32 v9, 0, v9
	v_fmac_f32_e32 v2, v168, v8
	v_max_f32_e32 v10, 0, v10
	v_fmac_f32_e32 v2, v167, v9
	v_max_f32_e32 v11, 0, v11
	v_fmac_f32_e32 v2, v166, v10
	v_max_f32_e32 v12, 0, v12
	v_fmac_f32_e32 v2, v165, v11
	v_max_f32_e32 v13, 0, v13
	v_fmac_f32_e32 v2, v164, v12
	v_max_f32_e32 v14, 0, v14
	v_fmac_f32_e32 v2, v163, v13
	v_fmac_f32_e32 v2, v162, v14
	v_max_f32_e32 v3, 0, v15
	v_fmac_f32_e32 v2, v161, v3
	v_max_f32_e32 v3, 0, v16
	v_fmac_f32_e32 v2, v160, v3
	v_max_f32_e32 v3, 0, v17
	v_fmac_f32_e32 v2, v89, v3
	v_not_b32_e32 v3, v2
	v_or_b32_e32 v4, 0x80000000, v2
	v_cmp_gt_i32_e32 vcc, 0, v2
	s_nop 1
	v_cndmask_b32_e32 v2, v4, v3, vcc
	v_cmp_le_u32_e32 vcc, v135, v87
	s_nop 1
	v_cndmask_b32_e32 v234, 0, v2, vcc
	s_branch .Lidxp_w42
.Lidxp_e42:
	v_max_f32_e32 v18, 0, v18
	v_max_f32_e32 v19, 0, v19
	v_fma_f32 v18, v174, v18, 0
	v_max_f32_e32 v20, 0, v20
	v_fmac_f32_e32 v18, v173, v19
	v_max_f32_e32 v21, 0, v21
	v_fmac_f32_e32 v18, v172, v20
	v_max_f32_e32 v22, 0, v22
	v_fmac_f32_e32 v18, v171, v21
	v_max_f32_e32 v23, 0, v23
	v_fmac_f32_e32 v18, v170, v22
	v_max_f32_e32 v24, 0, v24
	v_fmac_f32_e32 v18, v169, v23
	v_max_f32_e32 v25, 0, v25
	v_fmac_f32_e32 v18, v168, v24
	v_max_f32_e32 v26, 0, v26
	v_fmac_f32_e32 v18, v167, v25
	v_max_f32_e32 v27, 0, v27
	v_fmac_f32_e32 v18, v166, v26
	v_max_f32_e32 v28, 0, v28
	v_fmac_f32_e32 v18, v165, v27
	v_max_f32_e32 v29, 0, v29
	v_fmac_f32_e32 v18, v164, v28
	v_max_f32_e32 v30, 0, v30
	v_fmac_f32_e32 v18, v163, v29
	v_fmac_f32_e32 v18, v162, v30
	v_max_f32_e32 v19, 0, v31
	v_fmac_f32_e32 v18, v161, v19
	v_max_f32_e32 v19, 0, v32
	v_fmac_f32_e32 v18, v160, v19
	v_max_f32_e32 v19, 0, v33
	v_fmac_f32_e32 v18, v89, v19
	v_not_b32_e32 v19, v18
	v_or_b32_e32 v20, 0x80000000, v18
	v_cmp_gt_i32_e32 vcc, 0, v18
	s_nop 1
	v_cndmask_b32_e32 v18, v20, v19, vcc
	v_cmp_le_u32_e32 vcc, v136, v87
	s_nop 1
	v_cndmask_b32_e32 v235, 0, v18, vcc
	s_branch .Lidxp_w43
.Lidxp_e43:
	v_max_f32_e32 v2, 0, v2
	v_max_f32_e32 v3, 0, v3
	v_fma_f32 v2, v174, v2, 0
	v_max_f32_e32 v4, 0, v4
	v_fmac_f32_e32 v2, v173, v3
	v_max_f32_e32 v5, 0, v5
	v_fmac_f32_e32 v2, v172, v4
	v_max_f32_e32 v6, 0, v6
	v_fmac_f32_e32 v2, v171, v5
	v_max_f32_e32 v7, 0, v7
	v_fmac_f32_e32 v2, v170, v6
	v_max_f32_e32 v8, 0, v8
	v_fmac_f32_e32 v2, v169, v7
	v_max_f32_e32 v9, 0, v9
	v_fmac_f32_e32 v2, v168, v8
	v_max_f32_e32 v10, 0, v10
	v_fmac_f32_e32 v2, v167, v9
	v_max_f32_e32 v11, 0, v11
	v_fmac_f32_e32 v2, v166, v10
	v_max_f32_e32 v12, 0, v12
	v_fmac_f32_e32 v2, v165, v11
	v_max_f32_e32 v13, 0, v13
	v_fmac_f32_e32 v2, v164, v12
	v_max_f32_e32 v14, 0, v14
	v_fmac_f32_e32 v2, v163, v13
	v_fmac_f32_e32 v2, v162, v14
	v_max_f32_e32 v3, 0, v15
	v_fmac_f32_e32 v2, v161, v3
	v_max_f32_e32 v3, 0, v16
	v_fmac_f32_e32 v2, v160, v3
	v_max_f32_e32 v3, 0, v17
	v_fmac_f32_e32 v2, v89, v3
	v_not_b32_e32 v3, v2
	v_or_b32_e32 v4, 0x80000000, v2
	v_cmp_gt_i32_e32 vcc, 0, v2
	s_nop 1
	v_cndmask_b32_e32 v2, v4, v3, vcc
	v_cmp_le_u32_e32 vcc, v137, v87
	s_nop 1
	v_cndmask_b32_e32 v236, 0, v2, vcc
	s_branch .Lidxp_w44
.Lidxp_e44:
	v_max_f32_e32 v18, 0, v18
	v_max_f32_e32 v19, 0, v19
	v_fma_f32 v18, v174, v18, 0
	v_max_f32_e32 v20, 0, v20
	v_fmac_f32_e32 v18, v173, v19
	v_max_f32_e32 v21, 0, v21
	v_fmac_f32_e32 v18, v172, v20
	v_max_f32_e32 v22, 0, v22
	v_fmac_f32_e32 v18, v171, v21
	v_max_f32_e32 v23, 0, v23
	v_fmac_f32_e32 v18, v170, v22
	v_max_f32_e32 v24, 0, v24
	v_fmac_f32_e32 v18, v169, v23
	v_max_f32_e32 v25, 0, v25
	v_fmac_f32_e32 v18, v168, v24
	v_max_f32_e32 v26, 0, v26
	v_fmac_f32_e32 v18, v167, v25
	v_max_f32_e32 v27, 0, v27
	v_fmac_f32_e32 v18, v166, v26
	v_max_f32_e32 v28, 0, v28
	v_fmac_f32_e32 v18, v165, v27
	v_max_f32_e32 v29, 0, v29
	v_fmac_f32_e32 v18, v164, v28
	v_max_f32_e32 v30, 0, v30
	v_fmac_f32_e32 v18, v163, v29
	v_fmac_f32_e32 v18, v162, v30
	v_max_f32_e32 v19, 0, v31
	v_fmac_f32_e32 v18, v161, v19
	v_max_f32_e32 v19, 0, v32
	v_fmac_f32_e32 v18, v160, v19
	v_max_f32_e32 v19, 0, v33
	v_fmac_f32_e32 v18, v89, v19
	v_not_b32_e32 v19, v18
	v_or_b32_e32 v20, 0x80000000, v18
	v_cmp_gt_i32_e32 vcc, 0, v18
	s_nop 1
	v_cndmask_b32_e32 v18, v20, v19, vcc
	v_cmp_le_u32_e32 vcc, v138, v87
	s_nop 1
	v_cndmask_b32_e32 v237, 0, v18, vcc
	s_branch .Lidxp_w45
.Lidxp_e45:
	v_max_f32_e32 v2, 0, v2
	v_max_f32_e32 v3, 0, v3
	v_fma_f32 v2, v174, v2, 0
	v_max_f32_e32 v4, 0, v4
	v_fmac_f32_e32 v2, v173, v3
	v_max_f32_e32 v5, 0, v5
	v_fmac_f32_e32 v2, v172, v4
	v_max_f32_e32 v6, 0, v6
	v_fmac_f32_e32 v2, v171, v5
	v_max_f32_e32 v7, 0, v7
	v_fmac_f32_e32 v2, v170, v6
	v_max_f32_e32 v8, 0, v8
	v_fmac_f32_e32 v2, v169, v7
	v_max_f32_e32 v9, 0, v9
	v_fmac_f32_e32 v2, v168, v8
	v_max_f32_e32 v10, 0, v10
	v_fmac_f32_e32 v2, v167, v9
	v_max_f32_e32 v11, 0, v11
	v_fmac_f32_e32 v2, v166, v10
	v_max_f32_e32 v12, 0, v12
	v_fmac_f32_e32 v2, v165, v11
	v_max_f32_e32 v13, 0, v13
	v_fmac_f32_e32 v2, v164, v12
	v_max_f32_e32 v14, 0, v14
	v_fmac_f32_e32 v2, v163, v13
	v_fmac_f32_e32 v2, v162, v14
	v_max_f32_e32 v3, 0, v15
	v_fmac_f32_e32 v2, v161, v3
	v_max_f32_e32 v3, 0, v16
	v_fmac_f32_e32 v2, v160, v3
	v_max_f32_e32 v3, 0, v17
	v_fmac_f32_e32 v2, v89, v3
	v_not_b32_e32 v3, v2
	v_or_b32_e32 v4, 0x80000000, v2
	v_cmp_gt_i32_e32 vcc, 0, v2
	s_nop 1
	v_cndmask_b32_e32 v2, v4, v3, vcc
	v_cmp_le_u32_e32 vcc, v139, v87
	s_nop 1
	v_cndmask_b32_e32 v238, 0, v2, vcc
	s_branch .Lidxp_w46
.Lidxp_e46:
	v_max_f32_e32 v18, 0, v18
	v_max_f32_e32 v19, 0, v19
	v_fma_f32 v18, v174, v18, 0
	v_max_f32_e32 v20, 0, v20
	v_fmac_f32_e32 v18, v173, v19
	v_max_f32_e32 v21, 0, v21
	v_fmac_f32_e32 v18, v172, v20
	v_max_f32_e32 v22, 0, v22
	v_fmac_f32_e32 v18, v171, v21
	v_max_f32_e32 v23, 0, v23
	v_fmac_f32_e32 v18, v170, v22
	v_max_f32_e32 v24, 0, v24
	v_fmac_f32_e32 v18, v169, v23
	v_max_f32_e32 v25, 0, v25
	v_fmac_f32_e32 v18, v168, v24
	v_max_f32_e32 v26, 0, v26
	v_fmac_f32_e32 v18, v167, v25
	v_max_f32_e32 v27, 0, v27
	v_fmac_f32_e32 v18, v166, v26
	v_max_f32_e32 v28, 0, v28
	v_fmac_f32_e32 v18, v165, v27
	v_max_f32_e32 v29, 0, v29
	v_fmac_f32_e32 v18, v164, v28
	v_max_f32_e32 v30, 0, v30
	v_fmac_f32_e32 v18, v163, v29
	v_fmac_f32_e32 v18, v162, v30
	v_max_f32_e32 v19, 0, v31
	v_fmac_f32_e32 v18, v161, v19
	v_max_f32_e32 v19, 0, v32
	v_fmac_f32_e32 v18, v160, v19
	v_max_f32_e32 v19, 0, v33
	v_fmac_f32_e32 v18, v89, v19
	v_not_b32_e32 v19, v18
	v_or_b32_e32 v20, 0x80000000, v18
	v_cmp_gt_i32_e32 vcc, 0, v18
	s_nop 1
	v_cndmask_b32_e32 v18, v20, v19, vcc
	v_cmp_le_u32_e32 vcc, v140, v87
	s_nop 1
	v_cndmask_b32_e32 v239, 0, v18, vcc
	s_branch .Lidxp_w47
.Lidxp_e47:
	v_max_f32_e32 v2, 0, v2
	v_max_f32_e32 v3, 0, v3
	v_fma_f32 v2, v174, v2, 0
	v_max_f32_e32 v4, 0, v4
	v_fmac_f32_e32 v2, v173, v3
	v_max_f32_e32 v5, 0, v5
	v_fmac_f32_e32 v2, v172, v4
	v_max_f32_e32 v6, 0, v6
	v_fmac_f32_e32 v2, v171, v5
	v_max_f32_e32 v7, 0, v7
	v_fmac_f32_e32 v2, v170, v6
	v_max_f32_e32 v8, 0, v8
	v_fmac_f32_e32 v2, v169, v7
	v_max_f32_e32 v9, 0, v9
	v_fmac_f32_e32 v2, v168, v8
	v_max_f32_e32 v10, 0, v10
	v_fmac_f32_e32 v2, v167, v9
	v_max_f32_e32 v11, 0, v11
	v_fmac_f32_e32 v2, v166, v10
	v_max_f32_e32 v12, 0, v12
	v_fmac_f32_e32 v2, v165, v11
	v_max_f32_e32 v13, 0, v13
	v_fmac_f32_e32 v2, v164, v12
	v_max_f32_e32 v14, 0, v14
	v_fmac_f32_e32 v2, v163, v13
	v_fmac_f32_e32 v2, v162, v14
	v_max_f32_e32 v3, 0, v15
	v_fmac_f32_e32 v2, v161, v3
	v_max_f32_e32 v3, 0, v16
	v_fmac_f32_e32 v2, v160, v3
	v_max_f32_e32 v3, 0, v17
	v_fmac_f32_e32 v2, v89, v3
	v_not_b32_e32 v3, v2
	v_or_b32_e32 v4, 0x80000000, v2
	v_cmp_gt_i32_e32 vcc, 0, v2
	s_nop 1
	v_cndmask_b32_e32 v2, v4, v3, vcc
	v_cmp_le_u32_e32 vcc, v141, v87
	s_nop 1
	v_cndmask_b32_e32 v240, 0, v2, vcc
	s_branch .Lidxp_w48
.Lidxp_e48:
	v_max_f32_e32 v18, 0, v18
	v_max_f32_e32 v19, 0, v19
	v_fma_f32 v18, v174, v18, 0
	v_max_f32_e32 v20, 0, v20
	v_fmac_f32_e32 v18, v173, v19
	v_max_f32_e32 v21, 0, v21
	v_fmac_f32_e32 v18, v172, v20
	v_max_f32_e32 v22, 0, v22
	v_fmac_f32_e32 v18, v171, v21
	v_max_f32_e32 v23, 0, v23
	v_fmac_f32_e32 v18, v170, v22
	v_max_f32_e32 v24, 0, v24
	v_fmac_f32_e32 v18, v169, v23
	v_max_f32_e32 v25, 0, v25
	v_fmac_f32_e32 v18, v168, v24
	v_max_f32_e32 v26, 0, v26
	v_fmac_f32_e32 v18, v167, v25
	v_max_f32_e32 v27, 0, v27
	v_fmac_f32_e32 v18, v166, v26
	v_max_f32_e32 v28, 0, v28
	v_fmac_f32_e32 v18, v165, v27
	v_max_f32_e32 v29, 0, v29
	v_fmac_f32_e32 v18, v164, v28
	v_max_f32_e32 v30, 0, v30
	v_fmac_f32_e32 v18, v163, v29
	v_fmac_f32_e32 v18, v162, v30
	v_max_f32_e32 v19, 0, v31
	v_fmac_f32_e32 v18, v161, v19
	v_max_f32_e32 v19, 0, v32
	v_fmac_f32_e32 v18, v160, v19
	v_max_f32_e32 v19, 0, v33
	v_fmac_f32_e32 v18, v89, v19
	v_not_b32_e32 v19, v18
	v_or_b32_e32 v20, 0x80000000, v18
	v_cmp_gt_i32_e32 vcc, 0, v18
	s_nop 1
	v_cndmask_b32_e32 v18, v20, v19, vcc
	v_cmp_le_u32_e32 vcc, v142, v87
	s_nop 1
	v_cndmask_b32_e32 v241, 0, v18, vcc
	s_branch .Lidxp_w49
.Lidxp_e49:
	v_max_f32_e32 v2, 0, v2
	v_max_f32_e32 v3, 0, v3
	v_fma_f32 v2, v174, v2, 0
	v_max_f32_e32 v4, 0, v4
	v_fmac_f32_e32 v2, v173, v3
	v_max_f32_e32 v5, 0, v5
	v_fmac_f32_e32 v2, v172, v4
	v_max_f32_e32 v6, 0, v6
	v_fmac_f32_e32 v2, v171, v5
	v_max_f32_e32 v7, 0, v7
	v_fmac_f32_e32 v2, v170, v6
	v_max_f32_e32 v8, 0, v8
	v_fmac_f32_e32 v2, v169, v7
	v_max_f32_e32 v9, 0, v9
	v_fmac_f32_e32 v2, v168, v8
	v_max_f32_e32 v10, 0, v10
	v_fmac_f32_e32 v2, v167, v9
	v_max_f32_e32 v11, 0, v11
	v_fmac_f32_e32 v2, v166, v10
	v_max_f32_e32 v12, 0, v12
	v_fmac_f32_e32 v2, v165, v11
	v_max_f32_e32 v13, 0, v13
	v_fmac_f32_e32 v2, v164, v12
	v_max_f32_e32 v14, 0, v14
	v_fmac_f32_e32 v2, v163, v13
	v_fmac_f32_e32 v2, v162, v14
	v_max_f32_e32 v3, 0, v15
	v_fmac_f32_e32 v2, v161, v3
	v_max_f32_e32 v3, 0, v16
	v_fmac_f32_e32 v2, v160, v3
	v_max_f32_e32 v3, 0, v17
	v_fmac_f32_e32 v2, v89, v3
	v_not_b32_e32 v3, v2
	v_or_b32_e32 v4, 0x80000000, v2
	v_cmp_gt_i32_e32 vcc, 0, v2
	s_nop 1
	v_cndmask_b32_e32 v2, v4, v3, vcc
	v_cmp_le_u32_e32 vcc, v143, v87
	s_nop 1
	v_cndmask_b32_e32 v242, 0, v2, vcc
	s_branch .Lidxp_w50
.Lidxp_e50:
	v_max_f32_e32 v18, 0, v18
	v_max_f32_e32 v19, 0, v19
	v_fma_f32 v18, v174, v18, 0
	v_max_f32_e32 v20, 0, v20
	v_fmac_f32_e32 v18, v173, v19
	v_max_f32_e32 v21, 0, v21
	v_fmac_f32_e32 v18, v172, v20
	v_max_f32_e32 v22, 0, v22
	v_fmac_f32_e32 v18, v171, v21
	v_max_f32_e32 v23, 0, v23
	v_fmac_f32_e32 v18, v170, v22
	v_max_f32_e32 v24, 0, v24
	v_fmac_f32_e32 v18, v169, v23
	v_max_f32_e32 v25, 0, v25
	v_fmac_f32_e32 v18, v168, v24
	v_max_f32_e32 v26, 0, v26
	v_fmac_f32_e32 v18, v167, v25
	v_max_f32_e32 v27, 0, v27
	v_fmac_f32_e32 v18, v166, v26
	v_max_f32_e32 v28, 0, v28
	v_fmac_f32_e32 v18, v165, v27
	v_max_f32_e32 v29, 0, v29
	v_fmac_f32_e32 v18, v164, v28
	v_max_f32_e32 v30, 0, v30
	v_fmac_f32_e32 v18, v163, v29
	v_fmac_f32_e32 v18, v162, v30
	v_max_f32_e32 v19, 0, v31
	v_fmac_f32_e32 v18, v161, v19
	v_max_f32_e32 v19, 0, v32
	v_fmac_f32_e32 v18, v160, v19
	v_max_f32_e32 v19, 0, v33
	v_fmac_f32_e32 v18, v89, v19
	v_not_b32_e32 v19, v18
	v_or_b32_e32 v20, 0x80000000, v18
	v_cmp_gt_i32_e32 vcc, 0, v18
	s_nop 1
	v_cndmask_b32_e32 v18, v20, v19, vcc
	v_cmp_le_u32_e32 vcc, v144, v87
	s_nop 1
	v_cndmask_b32_e32 v243, 0, v18, vcc
	s_branch .Lidxp_w51
.Lidxp_e51:
	v_max_f32_e32 v2, 0, v2
	v_max_f32_e32 v3, 0, v3
	v_fma_f32 v2, v174, v2, 0
	v_max_f32_e32 v4, 0, v4
	v_fmac_f32_e32 v2, v173, v3
	v_max_f32_e32 v5, 0, v5
	v_fmac_f32_e32 v2, v172, v4
	v_max_f32_e32 v6, 0, v6
	v_fmac_f32_e32 v2, v171, v5
	v_max_f32_e32 v7, 0, v7
	v_fmac_f32_e32 v2, v170, v6
	v_max_f32_e32 v8, 0, v8
	v_fmac_f32_e32 v2, v169, v7
	v_max_f32_e32 v9, 0, v9
	v_fmac_f32_e32 v2, v168, v8
	v_max_f32_e32 v10, 0, v10
	v_fmac_f32_e32 v2, v167, v9
	v_max_f32_e32 v11, 0, v11
	v_fmac_f32_e32 v2, v166, v10
	v_max_f32_e32 v12, 0, v12
	v_fmac_f32_e32 v2, v165, v11
	v_max_f32_e32 v13, 0, v13
	v_fmac_f32_e32 v2, v164, v12
	v_max_f32_e32 v14, 0, v14
	v_fmac_f32_e32 v2, v163, v13
	v_fmac_f32_e32 v2, v162, v14
	v_max_f32_e32 v3, 0, v15
	v_fmac_f32_e32 v2, v161, v3
	v_max_f32_e32 v3, 0, v16
	v_fmac_f32_e32 v2, v160, v3
	v_max_f32_e32 v3, 0, v17
	v_fmac_f32_e32 v2, v89, v3
	v_not_b32_e32 v3, v2
	v_or_b32_e32 v4, 0x80000000, v2
	v_cmp_gt_i32_e32 vcc, 0, v2
	s_nop 1
	v_cndmask_b32_e32 v2, v4, v3, vcc
	v_cmp_le_u32_e32 vcc, v145, v87
	s_nop 1
	v_cndmask_b32_e32 v244, 0, v2, vcc
	s_branch .Lidxp_w52
.Lidxp_e52:
	v_max_f32_e32 v18, 0, v18
	v_max_f32_e32 v19, 0, v19
	v_fma_f32 v18, v174, v18, 0
	v_max_f32_e32 v20, 0, v20
	v_fmac_f32_e32 v18, v173, v19
	v_max_f32_e32 v21, 0, v21
	v_fmac_f32_e32 v18, v172, v20
	v_max_f32_e32 v22, 0, v22
	v_fmac_f32_e32 v18, v171, v21
	v_max_f32_e32 v23, 0, v23
	v_fmac_f32_e32 v18, v170, v22
	v_max_f32_e32 v24, 0, v24
	v_fmac_f32_e32 v18, v169, v23
	v_max_f32_e32 v25, 0, v25
	v_fmac_f32_e32 v18, v168, v24
	v_max_f32_e32 v26, 0, v26
	v_fmac_f32_e32 v18, v167, v25
	v_max_f32_e32 v27, 0, v27
	v_fmac_f32_e32 v18, v166, v26
	v_max_f32_e32 v28, 0, v28
	v_fmac_f32_e32 v18, v165, v27
	v_max_f32_e32 v29, 0, v29
	v_fmac_f32_e32 v18, v164, v28
	v_max_f32_e32 v30, 0, v30
	v_fmac_f32_e32 v18, v163, v29
	v_fmac_f32_e32 v18, v162, v30
	v_max_f32_e32 v19, 0, v31
	v_fmac_f32_e32 v18, v161, v19
	v_max_f32_e32 v19, 0, v32
	v_fmac_f32_e32 v18, v160, v19
	v_max_f32_e32 v19, 0, v33
	v_fmac_f32_e32 v18, v89, v19
	v_not_b32_e32 v19, v18
	v_or_b32_e32 v20, 0x80000000, v18
	v_cmp_gt_i32_e32 vcc, 0, v18
	s_nop 1
	v_cndmask_b32_e32 v18, v20, v19, vcc
	v_cmp_le_u32_e32 vcc, v146, v87
	s_nop 1
	v_cndmask_b32_e32 v245, 0, v18, vcc
	s_branch .Lidxp_w53
.Lidxp_e53:
	v_max_f32_e32 v2, 0, v2
	v_max_f32_e32 v3, 0, v3
	v_fma_f32 v2, v174, v2, 0
	v_max_f32_e32 v4, 0, v4
	v_fmac_f32_e32 v2, v173, v3
	v_max_f32_e32 v5, 0, v5
	v_fmac_f32_e32 v2, v172, v4
	v_max_f32_e32 v6, 0, v6
	v_fmac_f32_e32 v2, v171, v5
	v_max_f32_e32 v7, 0, v7
	v_fmac_f32_e32 v2, v170, v6
	v_max_f32_e32 v8, 0, v8
	v_fmac_f32_e32 v2, v169, v7
	v_max_f32_e32 v9, 0, v9
	v_fmac_f32_e32 v2, v168, v8
	v_max_f32_e32 v10, 0, v10
	v_fmac_f32_e32 v2, v167, v9
	v_max_f32_e32 v11, 0, v11
	v_fmac_f32_e32 v2, v166, v10
	v_max_f32_e32 v12, 0, v12
	v_fmac_f32_e32 v2, v165, v11
	v_max_f32_e32 v13, 0, v13
	v_fmac_f32_e32 v2, v164, v12
	v_max_f32_e32 v14, 0, v14
	v_fmac_f32_e32 v2, v163, v13
	v_fmac_f32_e32 v2, v162, v14
	v_max_f32_e32 v3, 0, v15
	v_fmac_f32_e32 v2, v161, v3
	v_max_f32_e32 v3, 0, v16
	v_fmac_f32_e32 v2, v160, v3
	v_max_f32_e32 v3, 0, v17
	v_fmac_f32_e32 v2, v89, v3
	v_not_b32_e32 v3, v2
	v_or_b32_e32 v4, 0x80000000, v2
	v_cmp_gt_i32_e32 vcc, 0, v2
	s_nop 1
	v_cndmask_b32_e32 v2, v4, v3, vcc
	v_cmp_le_u32_e32 vcc, v147, v87
	s_nop 1
	v_cndmask_b32_e32 v246, 0, v2, vcc
	s_branch .Lidxp_w54
.Lidxp_e54:
	v_max_f32_e32 v18, 0, v18
	v_max_f32_e32 v19, 0, v19
	v_fma_f32 v18, v174, v18, 0
	v_max_f32_e32 v20, 0, v20
	v_fmac_f32_e32 v18, v173, v19
	v_max_f32_e32 v21, 0, v21
	v_fmac_f32_e32 v18, v172, v20
	v_max_f32_e32 v22, 0, v22
	v_fmac_f32_e32 v18, v171, v21
	v_max_f32_e32 v23, 0, v23
	v_fmac_f32_e32 v18, v170, v22
	v_max_f32_e32 v24, 0, v24
	v_fmac_f32_e32 v18, v169, v23
	v_max_f32_e32 v25, 0, v25
	v_fmac_f32_e32 v18, v168, v24
	v_max_f32_e32 v26, 0, v26
	v_fmac_f32_e32 v18, v167, v25
	v_max_f32_e32 v27, 0, v27
	v_fmac_f32_e32 v18, v166, v26
	v_max_f32_e32 v28, 0, v28
	v_fmac_f32_e32 v18, v165, v27
	v_max_f32_e32 v29, 0, v29
	v_fmac_f32_e32 v18, v164, v28
	v_max_f32_e32 v30, 0, v30
	v_fmac_f32_e32 v18, v163, v29
	v_fmac_f32_e32 v18, v162, v30
	v_max_f32_e32 v19, 0, v31
	v_fmac_f32_e32 v18, v161, v19
	v_max_f32_e32 v19, 0, v32
	v_fmac_f32_e32 v18, v160, v19
	v_max_f32_e32 v19, 0, v33
	v_fmac_f32_e32 v18, v89, v19
	v_not_b32_e32 v19, v18
	v_or_b32_e32 v20, 0x80000000, v18
	v_cmp_gt_i32_e32 vcc, 0, v18
	s_nop 1
	v_cndmask_b32_e32 v18, v20, v19, vcc
	v_cmp_le_u32_e32 vcc, v148, v87
	s_nop 1
	v_cndmask_b32_e32 v247, 0, v18, vcc
	s_branch .Lidxp_w55
.Lidxp_e55:
	v_max_f32_e32 v2, 0, v2
	v_max_f32_e32 v3, 0, v3
	v_fma_f32 v2, v174, v2, 0
	v_max_f32_e32 v4, 0, v4
	v_fmac_f32_e32 v2, v173, v3
	v_max_f32_e32 v5, 0, v5
	v_fmac_f32_e32 v2, v172, v4
	v_max_f32_e32 v6, 0, v6
	v_fmac_f32_e32 v2, v171, v5
	v_max_f32_e32 v7, 0, v7
	v_fmac_f32_e32 v2, v170, v6
	v_max_f32_e32 v8, 0, v8
	v_fmac_f32_e32 v2, v169, v7
	v_max_f32_e32 v9, 0, v9
	v_fmac_f32_e32 v2, v168, v8
	v_max_f32_e32 v10, 0, v10
	v_fmac_f32_e32 v2, v167, v9
	v_max_f32_e32 v11, 0, v11
	v_fmac_f32_e32 v2, v166, v10
	v_max_f32_e32 v12, 0, v12
	v_fmac_f32_e32 v2, v165, v11
	v_max_f32_e32 v13, 0, v13
	v_fmac_f32_e32 v2, v164, v12
	v_max_f32_e32 v14, 0, v14
	v_fmac_f32_e32 v2, v163, v13
	v_fmac_f32_e32 v2, v162, v14
	v_max_f32_e32 v3, 0, v15
	v_fmac_f32_e32 v2, v161, v3
	v_max_f32_e32 v3, 0, v16
	v_fmac_f32_e32 v2, v160, v3
	v_max_f32_e32 v3, 0, v17
	v_fmac_f32_e32 v2, v89, v3
	v_not_b32_e32 v3, v2
	v_or_b32_e32 v4, 0x80000000, v2
	v_cmp_gt_i32_e32 vcc, 0, v2
	s_nop 1
	v_cndmask_b32_e32 v2, v4, v3, vcc
	v_cmp_le_u32_e32 vcc, v149, v87
	s_nop 1
	v_cndmask_b32_e32 v248, 0, v2, vcc
	s_branch .Lidxp_w56
.Lidxp_e56:
	v_max_f32_e32 v18, 0, v18
	v_max_f32_e32 v19, 0, v19
	v_fma_f32 v18, v174, v18, 0
	v_max_f32_e32 v20, 0, v20
	v_fmac_f32_e32 v18, v173, v19
	v_max_f32_e32 v21, 0, v21
	v_fmac_f32_e32 v18, v172, v20
	v_max_f32_e32 v22, 0, v22
	v_fmac_f32_e32 v18, v171, v21
	v_max_f32_e32 v23, 0, v23
	v_fmac_f32_e32 v18, v170, v22
	v_max_f32_e32 v24, 0, v24
	v_fmac_f32_e32 v18, v169, v23
	v_max_f32_e32 v25, 0, v25
	v_fmac_f32_e32 v18, v168, v24
	v_max_f32_e32 v26, 0, v26
	v_fmac_f32_e32 v18, v167, v25
	v_max_f32_e32 v27, 0, v27
	v_fmac_f32_e32 v18, v166, v26
	v_max_f32_e32 v28, 0, v28
	v_fmac_f32_e32 v18, v165, v27
	v_max_f32_e32 v29, 0, v29
	v_fmac_f32_e32 v18, v164, v28
	v_max_f32_e32 v30, 0, v30
	v_fmac_f32_e32 v18, v163, v29
	v_fmac_f32_e32 v18, v162, v30
	v_max_f32_e32 v19, 0, v31
	v_fmac_f32_e32 v18, v161, v19
	v_max_f32_e32 v19, 0, v32
	v_fmac_f32_e32 v18, v160, v19
	v_max_f32_e32 v19, 0, v33
	v_fmac_f32_e32 v18, v89, v19
	v_not_b32_e32 v19, v18
	v_or_b32_e32 v20, 0x80000000, v18
	v_cmp_gt_i32_e32 vcc, 0, v18
	s_nop 1
	v_cndmask_b32_e32 v18, v20, v19, vcc
	v_cmp_le_u32_e32 vcc, v150, v87
	s_nop 1
	v_cndmask_b32_e32 v249, 0, v18, vcc
	s_branch .Lidxp_w57
.Lidxp_e57:
	v_max_f32_e32 v2, 0, v2
	v_max_f32_e32 v3, 0, v3
	v_fma_f32 v2, v174, v2, 0
	v_max_f32_e32 v4, 0, v4
	v_fmac_f32_e32 v2, v173, v3
	v_max_f32_e32 v5, 0, v5
	v_fmac_f32_e32 v2, v172, v4
	v_max_f32_e32 v6, 0, v6
	v_fmac_f32_e32 v2, v171, v5
	v_max_f32_e32 v7, 0, v7
	v_fmac_f32_e32 v2, v170, v6
	v_max_f32_e32 v8, 0, v8
	v_fmac_f32_e32 v2, v169, v7
	v_max_f32_e32 v9, 0, v9
	v_fmac_f32_e32 v2, v168, v8
	v_max_f32_e32 v10, 0, v10
	v_fmac_f32_e32 v2, v167, v9
	v_max_f32_e32 v11, 0, v11
	v_fmac_f32_e32 v2, v166, v10
	v_max_f32_e32 v12, 0, v12
	v_fmac_f32_e32 v2, v165, v11
	v_max_f32_e32 v13, 0, v13
	v_fmac_f32_e32 v2, v164, v12
	v_max_f32_e32 v14, 0, v14
	v_fmac_f32_e32 v2, v163, v13
	v_fmac_f32_e32 v2, v162, v14
	v_max_f32_e32 v3, 0, v15
	v_fmac_f32_e32 v2, v161, v3
	v_max_f32_e32 v3, 0, v16
	v_fmac_f32_e32 v2, v160, v3
	v_max_f32_e32 v3, 0, v17
	v_fmac_f32_e32 v2, v89, v3
	v_not_b32_e32 v3, v2
	v_or_b32_e32 v4, 0x80000000, v2
	v_cmp_gt_i32_e32 vcc, 0, v2
	s_nop 1
	v_cndmask_b32_e32 v2, v4, v3, vcc
	v_cmp_le_u32_e32 vcc, v151, v87
	s_nop 1
	v_cndmask_b32_e32 v250, 0, v2, vcc
	s_branch .Lidxp_w58
.Lidxp_e58:
	v_max_f32_e32 v18, 0, v18
	v_max_f32_e32 v19, 0, v19
	v_fma_f32 v18, v174, v18, 0
	v_max_f32_e32 v20, 0, v20
	v_fmac_f32_e32 v18, v173, v19
	v_max_f32_e32 v21, 0, v21
	v_fmac_f32_e32 v18, v172, v20
	v_max_f32_e32 v22, 0, v22
	v_fmac_f32_e32 v18, v171, v21
	v_max_f32_e32 v23, 0, v23
	v_fmac_f32_e32 v18, v170, v22
	v_max_f32_e32 v24, 0, v24
	v_fmac_f32_e32 v18, v169, v23
	v_max_f32_e32 v25, 0, v25
	v_fmac_f32_e32 v18, v168, v24
	v_max_f32_e32 v26, 0, v26
	v_fmac_f32_e32 v18, v167, v25
	v_max_f32_e32 v27, 0, v27
	v_fmac_f32_e32 v18, v166, v26
	v_max_f32_e32 v28, 0, v28
	v_fmac_f32_e32 v18, v165, v27
	v_max_f32_e32 v29, 0, v29
	v_fmac_f32_e32 v18, v164, v28
	v_max_f32_e32 v30, 0, v30
	v_fmac_f32_e32 v18, v163, v29
	v_fmac_f32_e32 v18, v162, v30
	v_max_f32_e32 v19, 0, v31
	v_fmac_f32_e32 v18, v161, v19
	v_max_f32_e32 v19, 0, v32
	v_fmac_f32_e32 v18, v160, v19
	v_max_f32_e32 v19, 0, v33
	v_fmac_f32_e32 v18, v89, v19
	v_not_b32_e32 v19, v18
	v_or_b32_e32 v20, 0x80000000, v18
	v_cmp_gt_i32_e32 vcc, 0, v18
	s_nop 1
	v_cndmask_b32_e32 v18, v20, v19, vcc
	v_cmp_le_u32_e32 vcc, v152, v87
	s_nop 1
	v_cndmask_b32_e32 v199, 0, v18, vcc
	s_branch .Lidxp_w59
.Lidxp_e59:
	v_max_f32_e32 v2, 0, v2
	v_max_f32_e32 v3, 0, v3
	v_fma_f32 v2, v174, v2, 0
	v_max_f32_e32 v4, 0, v4
	v_fmac_f32_e32 v2, v173, v3
	v_max_f32_e32 v5, 0, v5
	v_fmac_f32_e32 v2, v172, v4
	v_max_f32_e32 v6, 0, v6
	v_fmac_f32_e32 v2, v171, v5
	v_max_f32_e32 v7, 0, v7
	v_fmac_f32_e32 v2, v170, v6
	v_max_f32_e32 v8, 0, v8
	v_fmac_f32_e32 v2, v169, v7
	v_max_f32_e32 v9, 0, v9
	v_fmac_f32_e32 v2, v168, v8
	v_max_f32_e32 v10, 0, v10
	v_fmac_f32_e32 v2, v167, v9
	v_max_f32_e32 v11, 0, v11
	v_fmac_f32_e32 v2, v166, v10
	v_max_f32_e32 v12, 0, v12
	v_fmac_f32_e32 v2, v165, v11
	v_max_f32_e32 v13, 0, v13
	v_fmac_f32_e32 v2, v164, v12
	v_max_f32_e32 v14, 0, v14
	v_fmac_f32_e32 v2, v163, v13
	v_fmac_f32_e32 v2, v162, v14
	v_max_f32_e32 v3, 0, v15
	v_fmac_f32_e32 v2, v161, v3
	v_max_f32_e32 v3, 0, v16
	v_fmac_f32_e32 v2, v160, v3
	v_max_f32_e32 v3, 0, v17
	v_fmac_f32_e32 v2, v89, v3
	v_not_b32_e32 v3, v2
	v_or_b32_e32 v4, 0x80000000, v2
	v_cmp_gt_i32_e32 vcc, 0, v2
	s_nop 1
	v_cndmask_b32_e32 v2, v4, v3, vcc
	v_cmp_le_u32_e32 vcc, v153, v87
	s_nop 1
	v_cndmask_b32_e32 v200, 0, v2, vcc
	s_branch .Lidxp_w60
.Lidxp_e60:
	v_max_f32_e32 v18, 0, v18
	v_max_f32_e32 v19, 0, v19
	v_fma_f32 v18, v174, v18, 0
	v_max_f32_e32 v20, 0, v20
	v_fmac_f32_e32 v18, v173, v19
	v_max_f32_e32 v21, 0, v21
	v_fmac_f32_e32 v18, v172, v20
	v_max_f32_e32 v22, 0, v22
	v_fmac_f32_e32 v18, v171, v21
	v_max_f32_e32 v23, 0, v23
	v_fmac_f32_e32 v18, v170, v22
	v_max_f32_e32 v24, 0, v24
	v_fmac_f32_e32 v18, v169, v23
	v_max_f32_e32 v25, 0, v25
	v_fmac_f32_e32 v18, v168, v24
	v_max_f32_e32 v26, 0, v26
	v_fmac_f32_e32 v18, v167, v25
	v_max_f32_e32 v27, 0, v27
	v_fmac_f32_e32 v18, v166, v26
	v_max_f32_e32 v28, 0, v28
	v_fmac_f32_e32 v18, v165, v27
	v_max_f32_e32 v29, 0, v29
	v_fmac_f32_e32 v18, v164, v28
	v_max_f32_e32 v30, 0, v30
	v_fmac_f32_e32 v18, v163, v29
	v_fmac_f32_e32 v18, v162, v30
	v_max_f32_e32 v19, 0, v31
	v_fmac_f32_e32 v18, v161, v19
	v_max_f32_e32 v19, 0, v32
	v_fmac_f32_e32 v18, v160, v19
	v_max_f32_e32 v19, 0, v33
	v_fmac_f32_e32 v18, v89, v19
	v_not_b32_e32 v19, v18
	v_or_b32_e32 v20, 0x80000000, v18
	v_cmp_gt_i32_e32 vcc, 0, v18
	s_nop 1
	v_cndmask_b32_e32 v18, v20, v19, vcc
	v_cmp_le_u32_e32 vcc, v154, v87
	s_nop 1
	v_cndmask_b32_e32 v207, 0, v18, vcc
	s_branch .Lidxp_w61
.Lidxp_e61:
	v_max_f32_e32 v2, 0, v2
	v_max_f32_e32 v3, 0, v3
	v_fma_f32 v2, v174, v2, 0
	v_max_f32_e32 v4, 0, v4
	v_fmac_f32_e32 v2, v173, v3
	v_max_f32_e32 v5, 0, v5
	v_fmac_f32_e32 v2, v172, v4
	v_max_f32_e32 v6, 0, v6
	v_fmac_f32_e32 v2, v171, v5
	v_max_f32_e32 v7, 0, v7
	v_fmac_f32_e32 v2, v170, v6
	v_max_f32_e32 v8, 0, v8
	v_fmac_f32_e32 v2, v169, v7
	v_max_f32_e32 v9, 0, v9
	v_fmac_f32_e32 v2, v168, v8
	v_max_f32_e32 v10, 0, v10
	v_fmac_f32_e32 v2, v167, v9
	v_max_f32_e32 v11, 0, v11
	v_fmac_f32_e32 v2, v166, v10
	v_max_f32_e32 v12, 0, v12
	v_fmac_f32_e32 v2, v165, v11
	v_max_f32_e32 v13, 0, v13
	v_fmac_f32_e32 v2, v164, v12
	v_max_f32_e32 v14, 0, v14
	v_fmac_f32_e32 v2, v163, v13
	v_fmac_f32_e32 v2, v162, v14
	v_max_f32_e32 v3, 0, v15
	v_fmac_f32_e32 v2, v161, v3
	v_max_f32_e32 v3, 0, v16
	v_fmac_f32_e32 v2, v160, v3
	v_max_f32_e32 v3, 0, v17
	v_fmac_f32_e32 v2, v89, v3
	v_not_b32_e32 v3, v2
	v_or_b32_e32 v4, 0x80000000, v2
	v_cmp_gt_i32_e32 vcc, 0, v2
	s_nop 1
	v_cndmask_b32_e32 v2, v4, v3, vcc
	v_cmp_le_u32_e32 vcc, v155, v87
	s_nop 1
	v_cndmask_b32_e32 v208, 0, v2, vcc
	s_branch .Lidxp_w62
.Lidxp_e62:
	v_max_f32_e32 v18, 0, v18
	v_max_f32_e32 v19, 0, v19
	v_fma_f32 v18, v174, v18, 0
	v_max_f32_e32 v20, 0, v20
	v_fmac_f32_e32 v18, v173, v19
	v_max_f32_e32 v21, 0, v21
	v_fmac_f32_e32 v18, v172, v20
	v_max_f32_e32 v22, 0, v22
	v_fmac_f32_e32 v18, v171, v21
	v_max_f32_e32 v23, 0, v23
	v_fmac_f32_e32 v18, v170, v22
	v_max_f32_e32 v24, 0, v24
	v_fmac_f32_e32 v18, v169, v23
	v_max_f32_e32 v25, 0, v25
	v_fmac_f32_e32 v18, v168, v24
	v_max_f32_e32 v26, 0, v26
	v_fmac_f32_e32 v18, v167, v25
	v_max_f32_e32 v27, 0, v27
	v_fmac_f32_e32 v18, v166, v26
	v_max_f32_e32 v28, 0, v28
	v_fmac_f32_e32 v18, v165, v27
	v_max_f32_e32 v29, 0, v29
	v_fmac_f32_e32 v18, v164, v28
	v_max_f32_e32 v30, 0, v30
	v_fmac_f32_e32 v18, v163, v29
	v_fmac_f32_e32 v18, v162, v30
	v_max_f32_e32 v19, 0, v31
	v_fmac_f32_e32 v18, v161, v19
	v_max_f32_e32 v19, 0, v32
	v_fmac_f32_e32 v18, v160, v19
	v_max_f32_e32 v19, 0, v33
	v_fmac_f32_e32 v18, v89, v19
	v_not_b32_e32 v19, v18
	v_or_b32_e32 v20, 0x80000000, v18
	v_cmp_gt_i32_e32 vcc, 0, v18
	s_nop 1
	v_cndmask_b32_e32 v18, v20, v19, vcc
	v_cmp_le_u32_e32 vcc, v156, v87
	s_nop 1
	v_cndmask_b32_e32 v210, 0, v18, vcc
	s_branch .Lidxp_w63
.Lidxp_e63:
	v_max_f32_e32 v2, 0, v2
	v_max_f32_e32 v3, 0, v3
	v_fma_f32 v2, v174, v2, 0
	v_max_f32_e32 v4, 0, v4
	v_fmac_f32_e32 v2, v173, v3
	v_max_f32_e32 v5, 0, v5
	v_fmac_f32_e32 v2, v172, v4
	v_max_f32_e32 v6, 0, v6
	v_fmac_f32_e32 v2, v171, v5
	v_max_f32_e32 v7, 0, v7
	v_fmac_f32_e32 v2, v170, v6
	v_max_f32_e32 v8, 0, v8
	v_fmac_f32_e32 v2, v169, v7
	v_max_f32_e32 v9, 0, v9
	v_fmac_f32_e32 v2, v168, v8
	v_max_f32_e32 v10, 0, v10
	v_fmac_f32_e32 v2, v167, v9
	v_max_f32_e32 v11, 0, v11
	v_fmac_f32_e32 v2, v166, v10
	v_max_f32_e32 v12, 0, v12
	v_fmac_f32_e32 v2, v165, v11
	v_max_f32_e32 v13, 0, v13
	v_fmac_f32_e32 v2, v164, v12
	v_max_f32_e32 v14, 0, v14
	v_fmac_f32_e32 v2, v163, v13
	v_fmac_f32_e32 v2, v162, v14
	v_max_f32_e32 v3, 0, v15
	v_fmac_f32_e32 v2, v161, v3
	v_max_f32_e32 v3, 0, v16
	v_fmac_f32_e32 v2, v160, v3
	v_max_f32_e32 v3, 0, v17
	v_fmac_f32_e32 v2, v89, v3
	v_not_b32_e32 v3, v2
	v_or_b32_e32 v4, 0x80000000, v2
	v_cmp_gt_i32_e32 vcc, 0, v2
	s_nop 1
	v_cndmask_b32_e32 v2, v4, v3, vcc
	v_cmp_le_u32_e32 vcc, v157, v87
	s_nop 1
	v_cndmask_b32_e32 v70, 0, v2, vcc
	s_branch .Lidxp_end
